# H2b + LDS-DMA addressing via SGPR base + 32-bit VGPR offset in the four GEMM K-loops (16 v_lshl_add_u64 per iteration removed from the load segments)
# speedup vs baseline: 1.0117x; 1.0047x over previous
; #define PG8_STAGE(bufoff, gbase, voff) do { _Pragma("unroll") for (int _i = 0; _i < 2; ++_i) \
;         __builtin_amdgcn_global_load_lds((const unsigned*)((const char*)(gbase) + (voff)[_i]), (PG8_LAS unsigned*)(lds + (bufoff) + ldsw + _i * 8192), 16, 0, 0); } while (0)
; #define PG8_WAIT_V(n) asm volatile("s_waitcnt vmcnt(" #n ")" ::: "memory")
; template <class Epi, class Sched>
; __device__ __forceinline__ void gemm_phase(PG8_LAS unsigned char* lds, const Gemm g, const Sched& S, const Epi& E) {
;     ...
;         const bool has_next = S.next(ui + 1, nxt);
;         const char* nA = has_next ? (const char*)g.A + (size_t)nxt.pm * tstep : cA; const char* nB = has_next ? (const char*)g.Bt + (size_t)nxt.pn * tstep : cB;
;         for (int t = 0; t < nt; t += 2) {
;             const bool last = (t == nt - 2);
;             const char* a1 = cA + (size_t)(t + 1) * kstep;
;             const char* a2 = last ? nA : cA + (size_t)(t + 2) * kstep; const char* b2 = last ? nB : cB + (size_t)(t + 2) * kstep;
;             const char* a3 = a2 + kstep; const char* b3 = b2 + kstep;
;             if (last && has_next) S.a_ready(nxt);
;             PG8_LDB(B0, 0, 0); PG8_SCHED; PG8_LDA(At, 0, 0); PG8_STAGE(PG8_SA(1, 1), a1 + hstep, voffA);
;             PG8_WAIT_L(8); PG8_BAR; PG8_WAIT_L(0); PG8_MMA(0, 0, At, B0); PG8_BAR; PG8_SCHED;
;             PG8_LDB(B1, 0, 1); PG8_STAGE(PG8_SB(0, 0), b2, voffB);
;             PG8_BAR; PG8_WAIT_L(0); PG8_MMA(0, 1, At, B1); PG8_BAR;
;             PG8_LDA(At, 0, 1); PG8_STAGE(PG8_SA(0, 0), a2, voffA);
;             PG8_BAR; PG8_WAIT_L(0); PG8_MMA(1, 0, At, B0); PG8_BAR; PG8_SCHED;
;             PG8_STAGE(PG8_SB(0, 1), b2 + hstep, voffB);
;             PG8_WAIT_V(6); PG8_BAR; PG8_MMA(1, 1, At, B1); PG8_BAR;
;             PG8_LDB(B0, 1, 0); PG8_SCHED; PG8_LDA(At, 1, 0); PG8_STAGE(PG8_SA(0, 1), a2 + hstep, voffA);
;             PG8_WAIT_L(8); PG8_BAR; PG8_WAIT_L(0); PG8_MMA(0, 0, At, B0); PG8_BAR; PG8_SCHED;
;             PG8_LDB(B1, 1, 1); PG8_STAGE(PG8_SB(1, 0), b3, voffB);
;             PG8_BAR; PG8_WAIT_L(0); PG8_MMA(0, 1, At, B1); PG8_BAR;
;             PG8_LDA(At, 1, 1); PG8_STAGE(PG8_SA(1, 0), a3, voffA);
;             PG8_BAR; PG8_WAIT_L(0); PG8_MMA(1, 0, At, B0); PG8_BAR; PG8_SCHED;
;             PG8_STAGE(PG8_SB(1, 1), b3 + hstep, voffB);
;             PG8_WAIT_V(6); PG8_BAR; PG8_MMA(1, 1, At, B1); PG8_BAR;
.LBB0_234:
	s_ashr_i32 s49, s48, 31
	v_cmp_lt_i64_e32 vcc, s[50:51], v[152:153]
	s_lshl_b64 s[50:51], s[48:49], 20
	s_add_u32 s50, s76, s50
	s_addc_u32 s51, s77, s51
	s_and_b64 s[64:65], vcc, exec
	s_cselect_b32 s0, s51, s69
	s_cselect_b32 s5, s50, s68
	s_ashr_i32 s47, s46, 31
	s_lshl_b64 s[64:65], s[46:47], 20
	s_add_u32 s64, s58, s64
	s_addc_u32 s65, s59, s65
	s_and_b64 s[72:73], vcc, exec
	s_cselect_b32 s47, s65, s71
	s_cselect_b32 s49, s64, s70
	s_add_u32 s68, s68, 0x80080
	s_addc_u32 s69, s69, 0
	s_add_u32 s97, s70, 0x100
	s_addc_u32 vcc_lo, s71, 0
	s_mov_b32 vcc_hi, -2
	s_setprio 0
	ds_read_b128 v[128:131], v162
	ds_read_b128 v[132:135], v162 offset:1024
	ds_read_b128 v[154:157], v162 offset:2048
	ds_read_b128 v[166:169], v162 offset:3072
	ds_read_b128 v[170:173], v163
	ds_read_b128 v[174:177], v163 offset:1024
	ds_read_b128 v[178:181], v163 offset:2048
	ds_read_b128 v[182:185], v163 offset:3072
	ds_read_b128 v[186:189], v163 offset:4096
	ds_read_b128 v[190:193], v163 offset:5120
	ds_read_b128 v[194:197], v163 offset:6144
	ds_read_b128 v[198:201], v163 offset:7168
	s_waitcnt lgkmcnt(11)
	ds_read_b128 v[202:205], v164
	ds_read_b128 v[206:209], v164 offset:1024
	ds_read_b128 v[210:213], v164 offset:2048
	ds_read_b128 v[214:217], v164 offset:3072
	s_add_u32 s10, s68, 0xfff80080
	s_addc_u32 s11, s69, -1
	s_cmp_eq_u32 vcc_hi, 28
	s_cselect_b32 s73, s0, s11
	s_cselect_b32 s72, s5, s10
	s_cselect_b32 s71, s47, vcc_lo
	s_cselect_b32 s70, s49, s97
	s_add_u32 s98, s70, s26
	s_addc_u32 s99, s71, s27
	s_add_u32 s100, s72, s26
	s_addc_u32 s101, s73, s27
	s_add_i32 m0, s67, 0xc000
	s_nop 0
	global_load_lds_dwordx4 v148, s[68:69]
	s_add_i32 m0, s67, 0xe000
	s_nop 0
	global_load_lds_dwordx4 v150, s[68:69]
	s_waitcnt vmcnt(8)
	s_waitcnt lgkmcnt(0)
	s_setprio 1
	s_barrier
	v_mfma_f32_16x16x32_bf16 v[124:127], v[128:131], v[170:173], 0
	v_mfma_f32_16x16x32_bf16 v[120:123], v[154:157], v[170:173], 0
	v_mfma_f32_16x16x32_bf16 v[116:119], v[128:131], v[178:181], 0
	v_mfma_f32_16x16x32_bf16 v[112:115], v[154:157], v[178:181], 0
	v_mfma_f32_16x16x32_bf16 v[108:111], v[128:131], v[186:189], 0
	v_mfma_f32_16x16x32_bf16 v[104:107], v[154:157], v[186:189], 0
	v_mfma_f32_16x16x32_bf16 v[100:103], v[128:131], v[194:197], 0
	v_mfma_f32_16x16x32_bf16 v[96:99], v[154:157], v[194:197], 0
	v_mfma_f32_16x16x32_bf16 v[124:127], v[132:135], v[174:177], v[124:127]
	v_mfma_f32_16x16x32_bf16 v[120:123], v[166:169], v[174:177], v[120:123]
	v_mfma_f32_16x16x32_bf16 v[116:119], v[132:135], v[182:185], v[116:119]
	v_mfma_f32_16x16x32_bf16 v[112:115], v[166:169], v[182:185], v[112:115]
	v_mfma_f32_16x16x32_bf16 v[108:111], v[132:135], v[190:193], v[108:111]
	v_mfma_f32_16x16x32_bf16 v[104:107], v[166:169], v[190:193], v[104:107]
	v_mfma_f32_16x16x32_bf16 v[100:103], v[132:135], v[198:201], v[100:103]
	v_mfma_f32_16x16x32_bf16 v[96:99], v[166:169], v[198:201], v[96:99]
	v_mfma_f32_16x16x32_bf16 v[60:63], v[202:205], v[170:173], 0
	v_mfma_f32_16x16x32_bf16 v[56:59], v[210:213], v[170:173], 0
	v_mfma_f32_16x16x32_bf16 v[52:55], v[202:205], v[178:181], 0
	v_mfma_f32_16x16x32_bf16 v[48:51], v[210:213], v[178:181], 0
	v_mfma_f32_16x16x32_bf16 v[44:47], v[202:205], v[186:189], 0
	v_mfma_f32_16x16x32_bf16 v[40:43], v[210:213], v[186:189], 0
	v_mfma_f32_16x16x32_bf16 v[36:39], v[202:205], v[194:197], 0
	v_mfma_f32_16x16x32_bf16 v[32:35], v[210:213], v[194:197], 0
	v_mfma_f32_16x16x32_bf16 v[60:63], v[206:209], v[174:177], v[60:63]
	v_mfma_f32_16x16x32_bf16 v[56:59], v[214:217], v[174:177], v[56:59]
	v_mfma_f32_16x16x32_bf16 v[52:55], v[206:209], v[182:185], v[52:55]
	v_mfma_f32_16x16x32_bf16 v[48:51], v[214:217], v[182:185], v[48:51]
	v_mfma_f32_16x16x32_bf16 v[44:47], v[206:209], v[190:193], v[44:47]
	v_mfma_f32_16x16x32_bf16 v[40:43], v[214:217], v[190:193], v[40:43]
	v_mfma_f32_16x16x32_bf16 v[36:39], v[206:209], v[198:201], v[36:39]
	v_mfma_f32_16x16x32_bf16 v[32:35], v[214:217], v[198:201], v[32:35]
	s_barrier
	s_setprio 0
	ds_read_b128 v[170:173], v163 offset:16384
	ds_read_b128 v[174:177], v163 offset:17408
	ds_read_b128 v[178:181], v163 offset:18432
	ds_read_b128 v[182:185], v163 offset:19456
	ds_read_b128 v[186:189], v163 offset:20480
	ds_read_b128 v[190:193], v163 offset:21504
	ds_read_b128 v[194:197], v163 offset:22528
	ds_read_b128 v[198:201], v163 offset:23552
	s_add_i32 s10, s90, s78
	s_mov_b32 m0, s10
	s_nop 0
	global_load_lds_dwordx4 v138, s[70:71]
	s_add_i32 m0, s10, 0x2000
	s_nop 0
	global_load_lds_dwordx4 v142, s[70:71]
	s_mov_b32 m0, s67
	s_nop 0
	global_load_lds_dwordx4 v136, s[72:73]
	s_mov_b32 m0, s79
	s_nop 0
	global_load_lds_dwordx4 v140, s[72:73]
	s_add_u32 s10, s70, 0x80000
	s_addc_u32 s11, s71, 0
	s_add_i32 s33, s91, s78
	s_mov_b32 m0, s33
	s_nop 0
	global_load_lds_dwordx4 v138, s[10:11]
	s_add_i32 m0, s33, 0x2000
	s_nop 0
	global_load_lds_dwordx4 v142, s[10:11]
	s_waitcnt vmcnt(8)
	s_waitcnt lgkmcnt(0)
	s_setprio 1
	s_barrier
; #define PG8_STAGE(bufoff, gbase, voff) do { _Pragma("unroll") for (int _i = 0; _i < 2; ++_i) \
;         __builtin_amdgcn_global_load_lds((const unsigned*)((const char*)(gbase) + (voff)[_i]), (PG8_LAS unsigned*)(lds + (bufoff) + ldsw + _i * 8192), 16, 0, 0); } while (0)
; #define PG8_LDA(dst, b, h) do { _Pragma("unroll") for (int m = 0; m < 4; ++m) _Pragma("unroll") for (int k = 0; k < 2; ++k) dst[m][k] = *(const PG8_LAS bf16x8*)(lds + PG8_SA(b, h) + aoff + m * 2048 + k * 1024); } while (0)
; #define PG8_LDB(dst, b, h) do { _Pragma("unroll") for (int n = 0; n < 2; ++n) _Pragma("unroll") for (int k = 0; k < 2; ++k) dst[n][k] = *(const PG8_LAS bf16x8*)(lds + PG8_SB(b, h) + boff + n * 2048 + k * 1024); } while (0)
; #define PG8_WAIT_V(n) asm volatile("s_waitcnt vmcnt(" #n ")" ::: "memory")
; #define PG8_WAIT_L(n) asm volatile("s_waitcnt lgkmcnt(" #n ")" ::: "memory")
; #define PG8_BAR __builtin_amdgcn_s_barrier()
; #define PG8_SCHED __builtin_amdgcn_sched_barrier(0)
; template <class Epi, class Sched>
; __device__ __forceinline__ void gemm_phase(PG8_LAS unsigned char* lds, const Gemm g, const Sched& S, const Epi& E) {
;     ...
;             PG8_LDB(B0, 0, 0); PG8_SCHED; PG8_LDA(At, 0, 0); PG8_STAGE(PG8_SA(1, 1), a1 + hstep, voffA);
;             PG8_WAIT_L(8); PG8_BAR; PG8_WAIT_L(0); PG8_MMA(0, 0, At, B0); PG8_BAR; PG8_SCHED;
;             PG8_LDB(B1, 0, 1); PG8_STAGE(PG8_SB(0, 0), b2, voffB);
;             PG8_BAR; PG8_WAIT_L(0); PG8_MMA(0, 1, At, B1); PG8_BAR;
;             PG8_LDA(At, 0, 1); PG8_STAGE(PG8_SA(0, 0), a2, voffA);
;             PG8_BAR; PG8_WAIT_L(0); PG8_MMA(1, 0, At, B0); PG8_BAR; PG8_SCHED;
;             PG8_STAGE(PG8_SB(0, 1), b2 + hstep, voffB);
;             PG8_WAIT_V(6); PG8_BAR; PG8_MMA(1, 1, At, B1); PG8_BAR;
;             PG8_LDB(B0, 1, 0); PG8_SCHED; PG8_LDA(At, 1, 0); PG8_STAGE(PG8_SA(0, 1), a2 + hstep, voffA);
;             PG8_WAIT_L(8); PG8_BAR; PG8_WAIT_L(0); PG8_MMA(0, 0, At, B0); PG8_BAR; PG8_SCHED;
;             PG8_LDB(B1, 1, 1); PG8_STAGE(PG8_SB(1, 0), b3, voffB);
;             PG8_BAR; PG8_WAIT_L(0); PG8_MMA(0, 1, At, B1); PG8_BAR;
;             PG8_LDA(At, 1, 1); PG8_STAGE(PG8_SA(1, 0), a3, voffA);
;             PG8_BAR; PG8_WAIT_L(0); PG8_MMA(1, 0, At, B0); PG8_BAR; PG8_SCHED;
;             PG8_STAGE(PG8_SB(1, 1), b3 + hstep, voffB);
;             PG8_WAIT_V(6); PG8_BAR; PG8_MMA(1, 1, At, B1); PG8_BAR;
	v_mfma_f32_16x16x32_bf16 v[92:95], v[128:131], v[170:173], 0
	v_mfma_f32_16x16x32_bf16 v[88:91], v[154:157], v[170:173], 0
	v_mfma_f32_16x16x32_bf16 v[84:87], v[128:131], v[178:181], 0
	v_mfma_f32_16x16x32_bf16 v[80:83], v[154:157], v[178:181], 0
	v_mfma_f32_16x16x32_bf16 v[76:79], v[128:131], v[186:189], 0
	v_mfma_f32_16x16x32_bf16 v[72:75], v[154:157], v[186:189], 0
	v_mfma_f32_16x16x32_bf16 v[68:71], v[128:131], v[194:197], 0
	v_mfma_f32_16x16x32_bf16 v[64:67], v[154:157], v[194:197], 0
	s_add_i32 s33, 0, 0x18000
	v_add_u32_e32 v144, s33, v160
	v_mfma_f32_16x16x32_bf16 v[92:95], v[132:135], v[174:177], v[92:95]
	v_mfma_f32_16x16x32_bf16 v[88:91], v[166:169], v[174:177], v[88:91]
	v_mfma_f32_16x16x32_bf16 v[84:87], v[132:135], v[182:185], v[84:87]
	v_mfma_f32_16x16x32_bf16 v[80:83], v[166:169], v[182:185], v[80:83]
	v_mfma_f32_16x16x32_bf16 v[76:79], v[132:135], v[190:193], v[76:79]
	v_mfma_f32_16x16x32_bf16 v[72:75], v[166:169], v[190:193], v[72:75]
	v_mfma_f32_16x16x32_bf16 v[68:71], v[132:135], v[198:201], v[68:71]
	v_mfma_f32_16x16x32_bf16 v[64:67], v[166:169], v[198:201], v[64:67]
	v_mfma_f32_16x16x32_bf16 v[28:31], v[202:205], v[170:173], 0
	v_mfma_f32_16x16x32_bf16 v[24:27], v[210:213], v[170:173], 0
	v_mfma_f32_16x16x32_bf16 v[20:23], v[202:205], v[178:181], 0
	v_mfma_f32_16x16x32_bf16 v[16:19], v[210:213], v[178:181], 0
	v_mfma_f32_16x16x32_bf16 v[12:15], v[202:205], v[186:189], 0
	v_mfma_f32_16x16x32_bf16 v[8:11], v[210:213], v[186:189], 0
	v_mfma_f32_16x16x32_bf16 v[4:7], v[202:205], v[194:197], 0
	v_mfma_f32_16x16x32_bf16 v[0:3], v[210:213], v[194:197], 0
	v_mfma_f32_16x16x32_bf16 v[28:31], v[206:209], v[174:177], v[28:31]
	v_mfma_f32_16x16x32_bf16 v[24:27], v[214:217], v[174:177], v[24:27]
	v_mfma_f32_16x16x32_bf16 v[20:23], v[206:209], v[182:185], v[20:23]
	v_mfma_f32_16x16x32_bf16 v[16:19], v[214:217], v[182:185], v[16:19]
	v_mfma_f32_16x16x32_bf16 v[12:15], v[206:209], v[190:193], v[12:15]
	v_mfma_f32_16x16x32_bf16 v[8:11], v[214:217], v[190:193], v[8:11]
	v_mfma_f32_16x16x32_bf16 v[4:7], v[206:209], v[198:201], v[4:7]
	v_mfma_f32_16x16x32_bf16 v[0:3], v[214:217], v[198:201], v[0:3]
	s_barrier
	s_setprio 0
	ds_read_b128 v[128:131], v162 offset:32768
	ds_read_b128 v[132:135], v162 offset:33792
	ds_read_b128 v[154:157], v162 offset:34816
	ds_read_b128 v[166:169], v162 offset:35840
	ds_read_b128 v[170:173], v163 offset:32768
	ds_read_b128 v[174:177], v163 offset:33792
	ds_read_b128 v[178:181], v163 offset:34816
	ds_read_b128 v[182:185], v163 offset:35840
	ds_read_b128 v[186:189], v163 offset:36864
	ds_read_b128 v[190:193], v163 offset:37888
	ds_read_b128 v[194:197], v163 offset:38912
	ds_read_b128 v[198:201], v163 offset:39936
	s_waitcnt lgkmcnt(11)
	ds_read_b128 v[202:205], v164 offset:32768
	ds_read_b128 v[206:209], v164 offset:33792
	ds_read_b128 v[210:213], v164 offset:34816
	ds_read_b128 v[214:217], v164 offset:35840
	s_add_u32 s10, s72, 0x80000
	s_addc_u32 s11, s73, 0
	s_mov_b32 m0, s80
	s_nop 0
	global_load_lds_dwordx4 v136, s[10:11]
	s_mov_b32 m0, s81
	s_nop 0
	global_load_lds_dwordx4 v140, s[10:11]
	s_waitcnt vmcnt(8)
	s_waitcnt lgkmcnt(0)
	s_setprio 1
	s_barrier
	v_mfma_f32_16x16x32_bf16 v[124:127], v[128:131], v[170:173], v[124:127]
	v_mfma_f32_16x16x32_bf16 v[120:123], v[154:157], v[170:173], v[120:123]
	v_mfma_f32_16x16x32_bf16 v[116:119], v[128:131], v[178:181], v[116:119]
	v_mfma_f32_16x16x32_bf16 v[112:115], v[154:157], v[178:181], v[112:115]
	v_mfma_f32_16x16x32_bf16 v[108:111], v[128:131], v[186:189], v[108:111]
	v_mfma_f32_16x16x32_bf16 v[104:107], v[154:157], v[186:189], v[104:107]
	v_mfma_f32_16x16x32_bf16 v[100:103], v[128:131], v[194:197], v[100:103]
	v_mfma_f32_16x16x32_bf16 v[96:99], v[154:157], v[194:197], v[96:99]
	v_mfma_f32_16x16x32_bf16 v[124:127], v[132:135], v[174:177], v[124:127]
	v_mfma_f32_16x16x32_bf16 v[120:123], v[166:169], v[174:177], v[120:123]
	v_mfma_f32_16x16x32_bf16 v[116:119], v[132:135], v[182:185], v[116:119]
	v_mfma_f32_16x16x32_bf16 v[112:115], v[166:169], v[182:185], v[112:115]
	v_mfma_f32_16x16x32_bf16 v[108:111], v[132:135], v[190:193], v[108:111]
	v_mfma_f32_16x16x32_bf16 v[104:107], v[166:169], v[190:193], v[104:107]
	v_mfma_f32_16x16x32_bf16 v[100:103], v[132:135], v[198:201], v[100:103]
	v_mfma_f32_16x16x32_bf16 v[96:99], v[166:169], v[198:201], v[96:99]
	v_mfma_f32_16x16x32_bf16 v[60:63], v[202:205], v[170:173], v[60:63]
	v_mfma_f32_16x16x32_bf16 v[56:59], v[210:213], v[170:173], v[56:59]
	v_mfma_f32_16x16x32_bf16 v[52:55], v[202:205], v[178:181], v[52:55]
	v_mfma_f32_16x16x32_bf16 v[48:51], v[210:213], v[178:181], v[48:51]
	v_mfma_f32_16x16x32_bf16 v[44:47], v[202:205], v[186:189], v[44:47]
	v_mfma_f32_16x16x32_bf16 v[40:43], v[210:213], v[186:189], v[40:43]
	v_mfma_f32_16x16x32_bf16 v[36:39], v[202:205], v[194:197], v[36:39]
	v_mfma_f32_16x16x32_bf16 v[32:35], v[210:213], v[194:197], v[32:35]
	v_mfma_f32_16x16x32_bf16 v[60:63], v[206:209], v[174:177], v[60:63]
	v_mfma_f32_16x16x32_bf16 v[56:59], v[214:217], v[174:177], v[56:59]
	v_mfma_f32_16x16x32_bf16 v[52:55], v[206:209], v[182:185], v[52:55]
	v_mfma_f32_16x16x32_bf16 v[48:51], v[214:217], v[182:185], v[48:51]
	v_mfma_f32_16x16x32_bf16 v[44:47], v[206:209], v[190:193], v[44:47]
	v_mfma_f32_16x16x32_bf16 v[40:43], v[214:217], v[190:193], v[40:43]
	v_mfma_f32_16x16x32_bf16 v[36:39], v[206:209], v[198:201], v[36:39]
	v_mfma_f32_16x16x32_bf16 v[32:35], v[214:217], v[198:201], v[32:35]
	s_barrier
; #define PG8_STAGE(bufoff, gbase, voff) do { _Pragma("unroll") for (int _i = 0; _i < 2; ++_i) \
;         __builtin_amdgcn_global_load_lds((const unsigned*)((const char*)(gbase) + (voff)[_i]), (PG8_LAS unsigned*)(lds + (bufoff) + ldsw + _i * 8192), 16, 0, 0); } while (0)
; #define PG8_LDA(dst, b, h) do { _Pragma("unroll") for (int m = 0; m < 4; ++m) _Pragma("unroll") for (int k = 0; k < 2; ++k) dst[m][k] = *(const PG8_LAS bf16x8*)(lds + PG8_SA(b, h) + aoff + m * 2048 + k * 1024); } while (0)
; template <class Epi, class Sched>
; __device__ __forceinline__ void gemm_phase(PG8_LAS unsigned char* lds, const Gemm g, const Sched& S, const Epi& E) {
;     ...
;         const bool has_next = S.next(ui + 1, nxt);
;         const char* nA = has_next ? (const char*)g.A + (size_t)nxt.pm * tstep : cA; const char* nB = has_next ? (const char*)g.Bt + (size_t)nxt.pn * tstep : cB;
;         for (int t = 0; t < nt; t += 2) {
;             const bool last = (t == nt - 2);
;             const char* a1 = cA + (size_t)(t + 1) * kstep;
;             const char* a2 = last ? nA : cA + (size_t)(t + 2) * kstep; const char* b2 = last ? nB : cB + (size_t)(t + 2) * kstep;
;     ...
;             PG8_LDB(B0, 0, 0); PG8_SCHED; PG8_LDA(At, 0, 0); PG8_STAGE(PG8_SA(1, 1), a1 + hstep, voffA);
;             PG8_WAIT_L(8); PG8_BAR; PG8_WAIT_L(0); PG8_MMA(0, 0, At, B0); PG8_BAR; PG8_SCHED;
;             PG8_LDB(B1, 0, 1); PG8_STAGE(PG8_SB(0, 0), b2, voffB);
;             PG8_BAR; PG8_WAIT_L(0); PG8_MMA(0, 1, At, B1); PG8_BAR;
;             PG8_LDA(At, 0, 1); PG8_STAGE(PG8_SA(0, 0), a2, voffA);
;             PG8_BAR; PG8_WAIT_L(0); PG8_MMA(1, 0, At, B0); PG8_BAR; PG8_SCHED;
;             PG8_STAGE(PG8_SB(0, 1), b2 + hstep, voffB);
;             PG8_WAIT_V(6); PG8_BAR; PG8_MMA(1, 1, At, B1); PG8_BAR;
;             PG8_LDB(B0, 1, 0); PG8_SCHED; PG8_LDA(At, 1, 0); PG8_STAGE(PG8_SA(0, 1), a2 + hstep, voffA);
;             PG8_WAIT_L(8); PG8_BAR; PG8_WAIT_L(0); PG8_MMA(0, 0, At, B0); PG8_BAR; PG8_SCHED;
;             PG8_LDB(B1, 1, 1); PG8_STAGE(PG8_SB(1, 0), b3, voffB);
;             PG8_BAR; PG8_WAIT_L(0); PG8_MMA(0, 1, At, B1); PG8_BAR;
;             PG8_LDA(At, 1, 1); PG8_STAGE(PG8_SA(1, 0), a3, voffA);
;             PG8_BAR; PG8_WAIT_L(0); PG8_MMA(1, 0, At, B0); PG8_BAR; PG8_SCHED;
;             PG8_STAGE(PG8_SB(1, 1), b3 + hstep, voffB);
;             PG8_WAIT_V(6); PG8_BAR; PG8_MMA(1, 1, At, B1); PG8_BAR;
	s_setprio 0
	ds_read_b128 v[170:173], v163 offset:49152
	ds_read_b128 v[174:177], v163 offset:50176
	ds_read_b128 v[178:181], v163 offset:51200
	ds_read_b128 v[182:185], v163 offset:52224
	ds_read_b128 v[186:189], v163 offset:53248
	ds_read_b128 v[190:193], v163 offset:54272
	ds_read_b128 v[194:197], v163 offset:55296
	ds_read_b128 v[198:201], v163 offset:56320
	s_add_i32 s72, 0, 0x1c000
	s_add_i32 s10, s33, s78
	v_add_u32_e32 v144, s72, v160
	s_mov_b32 m0, s10
	s_nop 0
	global_load_lds_dwordx4 v138, s[98:99]
	s_add_i32 m0, s10, 0x2000
	s_nop 0
	global_load_lds_dwordx4 v142, s[98:99]
	s_mov_b32 m0, s84
	s_nop 0
	global_load_lds_dwordx4 v136, s[100:101]
	s_mov_b32 m0, s85
	s_nop 0
	global_load_lds_dwordx4 v140, s[100:101]
	s_add_u32 s10, s70, 0x80080
	s_addc_u32 s11, s71, 0
	s_add_i32 s33, s72, s78
	s_mov_b32 m0, s33
	s_nop 0
	global_load_lds_dwordx4 v138, s[10:11]
	s_add_i32 m0, s33, 0x2000
	s_nop 0
	global_load_lds_dwordx4 v142, s[10:11]
	s_waitcnt vmcnt(8)
	s_waitcnt lgkmcnt(0)
	s_setprio 1
	s_barrier
	v_mfma_f32_16x16x32_bf16 v[92:95], v[128:131], v[170:173], v[92:95]
	v_mfma_f32_16x16x32_bf16 v[88:91], v[154:157], v[170:173], v[88:91]
	v_mfma_f32_16x16x32_bf16 v[84:87], v[128:131], v[178:181], v[84:87]
	v_mfma_f32_16x16x32_bf16 v[80:83], v[154:157], v[178:181], v[80:83]
	v_mfma_f32_16x16x32_bf16 v[76:79], v[128:131], v[186:189], v[76:79]
	v_mfma_f32_16x16x32_bf16 v[72:75], v[154:157], v[186:189], v[72:75]
	v_mfma_f32_16x16x32_bf16 v[68:71], v[128:131], v[194:197], v[68:71]
	v_mfma_f32_16x16x32_bf16 v[64:67], v[154:157], v[194:197], v[64:67]
	s_add_i32 vcc_hi, vcc_hi, 2
	s_add_u32 s68, s68, 0x100
	s_addc_u32 s69, s69, 0
	s_add_u32 s97, s97, 0x100
	s_addc_u32 vcc_lo, vcc_lo, 0
	s_cmp_gt_u32 vcc_hi, 29
	v_mfma_f32_16x16x32_bf16 v[92:95], v[132:135], v[174:177], v[92:95]
	v_mfma_f32_16x16x32_bf16 v[88:91], v[166:169], v[174:177], v[88:91]
	v_mfma_f32_16x16x32_bf16 v[84:87], v[132:135], v[182:185], v[84:87]
	v_mfma_f32_16x16x32_bf16 v[80:83], v[166:169], v[182:185], v[80:83]
	v_mfma_f32_16x16x32_bf16 v[76:79], v[132:135], v[190:193], v[76:79]
	v_mfma_f32_16x16x32_bf16 v[72:75], v[166:169], v[190:193], v[72:75]
	v_mfma_f32_16x16x32_bf16 v[68:71], v[132:135], v[198:201], v[68:71]
	v_mfma_f32_16x16x32_bf16 v[64:67], v[166:169], v[198:201], v[64:67]
	v_mfma_f32_16x16x32_bf16 v[28:31], v[202:205], v[170:173], v[28:31]
	v_mfma_f32_16x16x32_bf16 v[24:27], v[210:213], v[170:173], v[24:27]
	v_mfma_f32_16x16x32_bf16 v[20:23], v[202:205], v[178:181], v[20:23]
	v_mfma_f32_16x16x32_bf16 v[16:19], v[210:213], v[178:181], v[16:19]
	v_mfma_f32_16x16x32_bf16 v[12:15], v[202:205], v[186:189], v[12:15]
	v_mfma_f32_16x16x32_bf16 v[8:11], v[210:213], v[186:189], v[8:11]
	v_mfma_f32_16x16x32_bf16 v[4:7], v[202:205], v[194:197], v[4:7]
	v_mfma_f32_16x16x32_bf16 v[0:3], v[210:213], v[194:197], v[0:3]
	v_mfma_f32_16x16x32_bf16 v[28:31], v[206:209], v[174:177], v[28:31]
	v_mfma_f32_16x16x32_bf16 v[24:27], v[214:217], v[174:177], v[24:27]
	v_mfma_f32_16x16x32_bf16 v[20:23], v[206:209], v[182:185], v[20:23]
	v_mfma_f32_16x16x32_bf16 v[16:19], v[214:217], v[182:185], v[16:19]
	v_mfma_f32_16x16x32_bf16 v[12:15], v[206:209], v[190:193], v[12:15]
	v_mfma_f32_16x16x32_bf16 v[8:11], v[214:217], v[190:193], v[8:11]
	v_mfma_f32_16x16x32_bf16 v[4:7], v[206:209], v[198:201], v[4:7]
	v_mfma_f32_16x16x32_bf16 v[0:3], v[214:217], v[198:201], v[0:3]
	s_barrier
.LBB0_235:
	s_setprio 0
	ds_read_b128 v[128:131], v162
	ds_read_b128 v[132:135], v162 offset:1024
	ds_read_b128 v[154:157], v162 offset:2048
	ds_read_b128 v[166:169], v162 offset:3072
	ds_read_b128 v[170:173], v163
	ds_read_b128 v[174:177], v163 offset:1024
	ds_read_b128 v[178:181], v163 offset:2048
	ds_read_b128 v[182:185], v163 offset:3072
	ds_read_b128 v[186:189], v163 offset:4096
	ds_read_b128 v[190:193], v163 offset:5120
	ds_read_b128 v[194:197], v163 offset:6144
	ds_read_b128 v[198:201], v163 offset:7168
	s_waitcnt lgkmcnt(11)
	ds_read_b128 v[202:205], v164
	ds_read_b128 v[206:209], v164 offset:1024
	ds_read_b128 v[210:213], v164 offset:2048
	ds_read_b128 v[214:217], v164 offset:3072
	s_add_u32 s10, s68, 0xfff80080
	s_addc_u32 s11, s69, -1
	s_cmp_eq_u32 vcc_hi, 28
	s_cselect_b32 s73, s0, s11
	s_cselect_b32 s72, s5, s10
	s_cselect_b32 s71, s47, vcc_lo
	s_cselect_b32 s70, s49, s97
	s_add_u32 s98, s70, s26
	s_addc_u32 s99, s71, s27
	s_add_u32 s100, s72, s26
	s_addc_u32 s101, s73, s27
	s_add_i32 m0, s67, 0xc000
	s_nop 0
	global_load_lds_dwordx4 v148, s[68:69]
	s_add_i32 m0, s67, 0xe000
	s_nop 0
	global_load_lds_dwordx4 v150, s[68:69]
	s_waitcnt vmcnt(8)
	s_waitcnt lgkmcnt(0)
	s_setprio 1
	s_barrier
; #define PG8_STAGE(bufoff, gbase, voff) do { _Pragma("unroll") for (int _i = 0; _i < 2; ++_i) \
;         __builtin_amdgcn_global_load_lds((const unsigned*)((const char*)(gbase) + (voff)[_i]), (PG8_LAS unsigned*)(lds + (bufoff) + ldsw + _i * 8192), 16, 0, 0); } while (0)
; #define PG8_LDA(dst, b, h) do { _Pragma("unroll") for (int m = 0; m < 4; ++m) _Pragma("unroll") for (int k = 0; k < 2; ++k) dst[m][k] = *(const PG8_LAS bf16x8*)(lds + PG8_SA(b, h) + aoff + m * 2048 + k * 1024); } while (0)
; #define PG8_LDB(dst, b, h) do { _Pragma("unroll") for (int n = 0; n < 2; ++n) _Pragma("unroll") for (int k = 0; k < 2; ++k) dst[n][k] = *(const PG8_LAS bf16x8*)(lds + PG8_SB(b, h) + boff + n * 2048 + k * 1024); } while (0)
; #define PG8_WAIT_V(n) asm volatile("s_waitcnt vmcnt(" #n ")" ::: "memory")
; #define PG8_WAIT_L(n) asm volatile("s_waitcnt lgkmcnt(" #n ")" ::: "memory")
; #define PG8_BAR __builtin_amdgcn_s_barrier()
; #define PG8_SCHED __builtin_amdgcn_sched_barrier(0)
; template <class Epi, class Sched>
; __device__ __forceinline__ void gemm_phase(PG8_LAS unsigned char* lds, const Gemm g, const Sched& S, const Epi& E) {
;     ...
;             PG8_LDB(B0, 0, 0); PG8_SCHED; PG8_LDA(At, 0, 0); PG8_STAGE(PG8_SA(1, 1), a1 + hstep, voffA);
;             PG8_WAIT_L(8); PG8_BAR; PG8_WAIT_L(0); PG8_MMA(0, 0, At, B0); PG8_BAR; PG8_SCHED;
;             PG8_LDB(B1, 0, 1); PG8_STAGE(PG8_SB(0, 0), b2, voffB);
;             PG8_BAR; PG8_WAIT_L(0); PG8_MMA(0, 1, At, B1); PG8_BAR;
;             PG8_LDA(At, 0, 1); PG8_STAGE(PG8_SA(0, 0), a2, voffA);
;             PG8_BAR; PG8_WAIT_L(0); PG8_MMA(1, 0, At, B0); PG8_BAR; PG8_SCHED;
;             PG8_STAGE(PG8_SB(0, 1), b2 + hstep, voffB);
;             PG8_WAIT_V(6); PG8_BAR; PG8_MMA(1, 1, At, B1); PG8_BAR;
;             PG8_LDB(B0, 1, 0); PG8_SCHED; PG8_LDA(At, 1, 0); PG8_STAGE(PG8_SA(0, 1), a2 + hstep, voffA);
;             PG8_WAIT_L(8); PG8_BAR; PG8_WAIT_L(0); PG8_MMA(0, 0, At, B0); PG8_BAR; PG8_SCHED;
;             PG8_LDB(B1, 1, 1); PG8_STAGE(PG8_SB(1, 0), b3, voffB);
;             PG8_BAR; PG8_WAIT_L(0); PG8_MMA(0, 1, At, B1); PG8_BAR;
;             PG8_LDA(At, 1, 1); PG8_STAGE(PG8_SA(1, 0), a3, voffA);
;             PG8_BAR; PG8_WAIT_L(0); PG8_MMA(1, 0, At, B0); PG8_BAR; PG8_SCHED;
;             PG8_STAGE(PG8_SB(1, 1), b3 + hstep, voffB);
;             PG8_WAIT_V(6); PG8_BAR; PG8_MMA(1, 1, At, B1); PG8_BAR;
	v_mfma_f32_16x16x32_bf16 v[124:127], v[128:131], v[170:173], v[124:127]
	v_mfma_f32_16x16x32_bf16 v[120:123], v[154:157], v[170:173], v[120:123]
	v_mfma_f32_16x16x32_bf16 v[116:119], v[128:131], v[178:181], v[116:119]
	v_mfma_f32_16x16x32_bf16 v[112:115], v[154:157], v[178:181], v[112:115]
	v_mfma_f32_16x16x32_bf16 v[108:111], v[128:131], v[186:189], v[108:111]
	v_mfma_f32_16x16x32_bf16 v[104:107], v[154:157], v[186:189], v[104:107]
	v_mfma_f32_16x16x32_bf16 v[100:103], v[128:131], v[194:197], v[100:103]
	v_mfma_f32_16x16x32_bf16 v[96:99], v[154:157], v[194:197], v[96:99]
	v_mfma_f32_16x16x32_bf16 v[124:127], v[132:135], v[174:177], v[124:127]
	v_mfma_f32_16x16x32_bf16 v[120:123], v[166:169], v[174:177], v[120:123]
	v_mfma_f32_16x16x32_bf16 v[116:119], v[132:135], v[182:185], v[116:119]
	v_mfma_f32_16x16x32_bf16 v[112:115], v[166:169], v[182:185], v[112:115]
	v_mfma_f32_16x16x32_bf16 v[108:111], v[132:135], v[190:193], v[108:111]
	v_mfma_f32_16x16x32_bf16 v[104:107], v[166:169], v[190:193], v[104:107]
	v_mfma_f32_16x16x32_bf16 v[100:103], v[132:135], v[198:201], v[100:103]
	v_mfma_f32_16x16x32_bf16 v[96:99], v[166:169], v[198:201], v[96:99]
	v_mfma_f32_16x16x32_bf16 v[60:63], v[202:205], v[170:173], v[60:63]
	v_mfma_f32_16x16x32_bf16 v[56:59], v[210:213], v[170:173], v[56:59]
	v_mfma_f32_16x16x32_bf16 v[52:55], v[202:205], v[178:181], v[52:55]
	v_mfma_f32_16x16x32_bf16 v[48:51], v[210:213], v[178:181], v[48:51]
	v_mfma_f32_16x16x32_bf16 v[44:47], v[202:205], v[186:189], v[44:47]
	v_mfma_f32_16x16x32_bf16 v[40:43], v[210:213], v[186:189], v[40:43]
	v_mfma_f32_16x16x32_bf16 v[36:39], v[202:205], v[194:197], v[36:39]
	v_mfma_f32_16x16x32_bf16 v[32:35], v[210:213], v[194:197], v[32:35]
	v_mfma_f32_16x16x32_bf16 v[60:63], v[206:209], v[174:177], v[60:63]
	v_mfma_f32_16x16x32_bf16 v[56:59], v[214:217], v[174:177], v[56:59]
	v_mfma_f32_16x16x32_bf16 v[52:55], v[206:209], v[182:185], v[52:55]
	v_mfma_f32_16x16x32_bf16 v[48:51], v[214:217], v[182:185], v[48:51]
	v_mfma_f32_16x16x32_bf16 v[44:47], v[206:209], v[190:193], v[44:47]
	v_mfma_f32_16x16x32_bf16 v[40:43], v[214:217], v[190:193], v[40:43]
	v_mfma_f32_16x16x32_bf16 v[36:39], v[206:209], v[198:201], v[36:39]
	v_mfma_f32_16x16x32_bf16 v[32:35], v[214:217], v[198:201], v[32:35]
	s_barrier
	s_setprio 0
	ds_read_b128 v[170:173], v163 offset:16384
	ds_read_b128 v[174:177], v163 offset:17408
	ds_read_b128 v[178:181], v163 offset:18432
	ds_read_b128 v[182:185], v163 offset:19456
	ds_read_b128 v[186:189], v163 offset:20480
	ds_read_b128 v[190:193], v163 offset:21504
	ds_read_b128 v[194:197], v163 offset:22528
	ds_read_b128 v[198:201], v163 offset:23552
	s_add_i32 s10, s90, s78
	s_mov_b32 m0, s10
	s_nop 0
	global_load_lds_dwordx4 v138, s[70:71]
	s_add_i32 m0, s10, 0x2000
	s_nop 0
	global_load_lds_dwordx4 v142, s[70:71]
	s_mov_b32 m0, s67
	s_nop 0
	global_load_lds_dwordx4 v136, s[72:73]
	s_mov_b32 m0, s79
	s_nop 0
	global_load_lds_dwordx4 v140, s[72:73]
	s_add_u32 s10, s70, 0x80000
	s_addc_u32 s11, s71, 0
	s_add_i32 s33, s91, s78
	s_mov_b32 m0, s33
	s_nop 0
	global_load_lds_dwordx4 v138, s[10:11]
	s_add_i32 m0, s33, 0x2000
	s_nop 0
	global_load_lds_dwordx4 v142, s[10:11]
	s_waitcnt vmcnt(8)
	s_waitcnt lgkmcnt(0)
	s_setprio 1
	s_barrier
	v_mfma_f32_16x16x32_bf16 v[92:95], v[128:131], v[170:173], v[92:95]
	v_mfma_f32_16x16x32_bf16 v[88:91], v[154:157], v[170:173], v[88:91]
	v_mfma_f32_16x16x32_bf16 v[84:87], v[128:131], v[178:181], v[84:87]
	v_mfma_f32_16x16x32_bf16 v[80:83], v[154:157], v[178:181], v[80:83]
	v_mfma_f32_16x16x32_bf16 v[76:79], v[128:131], v[186:189], v[76:79]
	v_mfma_f32_16x16x32_bf16 v[72:75], v[154:157], v[186:189], v[72:75]
	v_mfma_f32_16x16x32_bf16 v[68:71], v[128:131], v[194:197], v[68:71]
	v_mfma_f32_16x16x32_bf16 v[64:67], v[154:157], v[194:197], v[64:67]
	s_add_i32 s33, 0, 0x18000
	v_add_u32_e32 v144, s33, v160
	v_mfma_f32_16x16x32_bf16 v[92:95], v[132:135], v[174:177], v[92:95]
	v_mfma_f32_16x16x32_bf16 v[88:91], v[166:169], v[174:177], v[88:91]
	v_mfma_f32_16x16x32_bf16 v[84:87], v[132:135], v[182:185], v[84:87]
	v_mfma_f32_16x16x32_bf16 v[80:83], v[166:169], v[182:185], v[80:83]
	v_mfma_f32_16x16x32_bf16 v[76:79], v[132:135], v[190:193], v[76:79]
	v_mfma_f32_16x16x32_bf16 v[72:75], v[166:169], v[190:193], v[72:75]
	v_mfma_f32_16x16x32_bf16 v[68:71], v[132:135], v[198:201], v[68:71]
	v_mfma_f32_16x16x32_bf16 v[64:67], v[166:169], v[198:201], v[64:67]
	v_mfma_f32_16x16x32_bf16 v[28:31], v[202:205], v[170:173], v[28:31]
	v_mfma_f32_16x16x32_bf16 v[24:27], v[210:213], v[170:173], v[24:27]
	v_mfma_f32_16x16x32_bf16 v[20:23], v[202:205], v[178:181], v[20:23]
	v_mfma_f32_16x16x32_bf16 v[16:19], v[210:213], v[178:181], v[16:19]
	v_mfma_f32_16x16x32_bf16 v[12:15], v[202:205], v[186:189], v[12:15]
	v_mfma_f32_16x16x32_bf16 v[8:11], v[210:213], v[186:189], v[8:11]
	v_mfma_f32_16x16x32_bf16 v[4:7], v[202:205], v[194:197], v[4:7]
	v_mfma_f32_16x16x32_bf16 v[0:3], v[210:213], v[194:197], v[0:3]
	v_mfma_f32_16x16x32_bf16 v[28:31], v[206:209], v[174:177], v[28:31]
	v_mfma_f32_16x16x32_bf16 v[24:27], v[214:217], v[174:177], v[24:27]
	v_mfma_f32_16x16x32_bf16 v[20:23], v[206:209], v[182:185], v[20:23]
	v_mfma_f32_16x16x32_bf16 v[16:19], v[214:217], v[182:185], v[16:19]
	v_mfma_f32_16x16x32_bf16 v[12:15], v[206:209], v[190:193], v[12:15]
	v_mfma_f32_16x16x32_bf16 v[8:11], v[214:217], v[190:193], v[8:11]
	v_mfma_f32_16x16x32_bf16 v[4:7], v[206:209], v[198:201], v[4:7]
	v_mfma_f32_16x16x32_bf16 v[0:3], v[214:217], v[198:201], v[0:3]
	s_barrier
; #define PG8_STAGE(bufoff, gbase, voff) do { _Pragma("unroll") for (int _i = 0; _i < 2; ++_i) \
;         __builtin_amdgcn_global_load_lds((const unsigned*)((const char*)(gbase) + (voff)[_i]), (PG8_LAS unsigned*)(lds + (bufoff) + ldsw + _i * 8192), 16, 0, 0); } while (0)
; #define PG8_LDA(dst, b, h) do { _Pragma("unroll") for (int m = 0; m < 4; ++m) _Pragma("unroll") for (int k = 0; k < 2; ++k) dst[m][k] = *(const PG8_LAS bf16x8*)(lds + PG8_SA(b, h) + aoff + m * 2048 + k * 1024); } while (0)
; #define PG8_LDB(dst, b, h) do { _Pragma("unroll") for (int n = 0; n < 2; ++n) _Pragma("unroll") for (int k = 0; k < 2; ++k) dst[n][k] = *(const PG8_LAS bf16x8*)(lds + PG8_SB(b, h) + boff + n * 2048 + k * 1024); } while (0)
; #define PG8_WAIT_V(n) asm volatile("s_waitcnt vmcnt(" #n ")" ::: "memory")
; #define PG8_WAIT_L(n) asm volatile("s_waitcnt lgkmcnt(" #n ")" ::: "memory")
; #define PG8_BAR __builtin_amdgcn_s_barrier()
; #define PG8_SCHED __builtin_amdgcn_sched_barrier(0)
; template <class Epi, class Sched>
; __device__ __forceinline__ void gemm_phase(PG8_LAS unsigned char* lds, const Gemm g, const Sched& S, const Epi& E) {
;     ...
;             PG8_LDB(B0, 0, 0); PG8_SCHED; PG8_LDA(At, 0, 0); PG8_STAGE(PG8_SA(1, 1), a1 + hstep, voffA);
;             PG8_WAIT_L(8); PG8_BAR; PG8_WAIT_L(0); PG8_MMA(0, 0, At, B0); PG8_BAR; PG8_SCHED;
;             PG8_LDB(B1, 0, 1); PG8_STAGE(PG8_SB(0, 0), b2, voffB);
;             PG8_BAR; PG8_WAIT_L(0); PG8_MMA(0, 1, At, B1); PG8_BAR;
;             PG8_LDA(At, 0, 1); PG8_STAGE(PG8_SA(0, 0), a2, voffA);
;             PG8_BAR; PG8_WAIT_L(0); PG8_MMA(1, 0, At, B0); PG8_BAR; PG8_SCHED;
;             PG8_STAGE(PG8_SB(0, 1), b2 + hstep, voffB);
;             PG8_WAIT_V(6); PG8_BAR; PG8_MMA(1, 1, At, B1); PG8_BAR;
;             PG8_LDB(B0, 1, 0); PG8_SCHED; PG8_LDA(At, 1, 0); PG8_STAGE(PG8_SA(0, 1), a2 + hstep, voffA);
;             PG8_WAIT_L(8); PG8_BAR; PG8_WAIT_L(0); PG8_MMA(0, 0, At, B0); PG8_BAR; PG8_SCHED;
;             PG8_LDB(B1, 1, 1); PG8_STAGE(PG8_SB(1, 0), b3, voffB);
;             PG8_BAR; PG8_WAIT_L(0); PG8_MMA(0, 1, At, B1); PG8_BAR;
;             PG8_LDA(At, 1, 1); PG8_STAGE(PG8_SA(1, 0), a3, voffA);
;             PG8_BAR; PG8_WAIT_L(0); PG8_MMA(1, 0, At, B0); PG8_BAR; PG8_SCHED;
;             PG8_STAGE(PG8_SB(1, 1), b3 + hstep, voffB);
;             PG8_WAIT_V(6); PG8_BAR; PG8_MMA(1, 1, At, B1); PG8_BAR;
	s_setprio 0
	ds_read_b128 v[128:131], v162 offset:32768
	ds_read_b128 v[132:135], v162 offset:33792
	ds_read_b128 v[154:157], v162 offset:34816
	ds_read_b128 v[166:169], v162 offset:35840
	ds_read_b128 v[170:173], v163 offset:32768
	ds_read_b128 v[174:177], v163 offset:33792
	ds_read_b128 v[178:181], v163 offset:34816
	ds_read_b128 v[182:185], v163 offset:35840
	ds_read_b128 v[186:189], v163 offset:36864
	ds_read_b128 v[190:193], v163 offset:37888
	ds_read_b128 v[194:197], v163 offset:38912
	ds_read_b128 v[198:201], v163 offset:39936
	s_waitcnt lgkmcnt(11)
	ds_read_b128 v[202:205], v164 offset:32768
	ds_read_b128 v[206:209], v164 offset:33792
	ds_read_b128 v[210:213], v164 offset:34816
	ds_read_b128 v[214:217], v164 offset:35840
	s_add_u32 s10, s72, 0x80000
	s_addc_u32 s11, s73, 0
	s_mov_b32 m0, s80
	s_nop 0
	global_load_lds_dwordx4 v136, s[10:11]
	s_mov_b32 m0, s81
	s_nop 0
	global_load_lds_dwordx4 v140, s[10:11]
	s_waitcnt vmcnt(8)
	s_waitcnt lgkmcnt(0)
	s_setprio 1
	s_barrier
	v_mfma_f32_16x16x32_bf16 v[124:127], v[128:131], v[170:173], v[124:127]
	v_mfma_f32_16x16x32_bf16 v[120:123], v[154:157], v[170:173], v[120:123]
	v_mfma_f32_16x16x32_bf16 v[116:119], v[128:131], v[178:181], v[116:119]
	v_mfma_f32_16x16x32_bf16 v[112:115], v[154:157], v[178:181], v[112:115]
	v_mfma_f32_16x16x32_bf16 v[108:111], v[128:131], v[186:189], v[108:111]
	v_mfma_f32_16x16x32_bf16 v[104:107], v[154:157], v[186:189], v[104:107]
	v_mfma_f32_16x16x32_bf16 v[100:103], v[128:131], v[194:197], v[100:103]
	v_mfma_f32_16x16x32_bf16 v[96:99], v[154:157], v[194:197], v[96:99]
	v_mfma_f32_16x16x32_bf16 v[124:127], v[132:135], v[174:177], v[124:127]
	v_mfma_f32_16x16x32_bf16 v[120:123], v[166:169], v[174:177], v[120:123]
	v_mfma_f32_16x16x32_bf16 v[116:119], v[132:135], v[182:185], v[116:119]
	v_mfma_f32_16x16x32_bf16 v[112:115], v[166:169], v[182:185], v[112:115]
	v_mfma_f32_16x16x32_bf16 v[108:111], v[132:135], v[190:193], v[108:111]
	v_mfma_f32_16x16x32_bf16 v[104:107], v[166:169], v[190:193], v[104:107]
	v_mfma_f32_16x16x32_bf16 v[100:103], v[132:135], v[198:201], v[100:103]
	v_mfma_f32_16x16x32_bf16 v[96:99], v[166:169], v[198:201], v[96:99]
	v_mfma_f32_16x16x32_bf16 v[60:63], v[202:205], v[170:173], v[60:63]
	v_mfma_f32_16x16x32_bf16 v[56:59], v[210:213], v[170:173], v[56:59]
	v_mfma_f32_16x16x32_bf16 v[52:55], v[202:205], v[178:181], v[52:55]
	v_mfma_f32_16x16x32_bf16 v[48:51], v[210:213], v[178:181], v[48:51]
	v_mfma_f32_16x16x32_bf16 v[44:47], v[202:205], v[186:189], v[44:47]
	v_mfma_f32_16x16x32_bf16 v[40:43], v[210:213], v[186:189], v[40:43]
	v_mfma_f32_16x16x32_bf16 v[36:39], v[202:205], v[194:197], v[36:39]
	v_mfma_f32_16x16x32_bf16 v[32:35], v[210:213], v[194:197], v[32:35]
	v_mfma_f32_16x16x32_bf16 v[60:63], v[206:209], v[174:177], v[60:63]
	v_mfma_f32_16x16x32_bf16 v[56:59], v[214:217], v[174:177], v[56:59]
	v_mfma_f32_16x16x32_bf16 v[52:55], v[206:209], v[182:185], v[52:55]
	v_mfma_f32_16x16x32_bf16 v[48:51], v[214:217], v[182:185], v[48:51]
	v_mfma_f32_16x16x32_bf16 v[44:47], v[206:209], v[190:193], v[44:47]
	v_mfma_f32_16x16x32_bf16 v[40:43], v[214:217], v[190:193], v[40:43]
	v_mfma_f32_16x16x32_bf16 v[36:39], v[206:209], v[198:201], v[36:39]
	v_mfma_f32_16x16x32_bf16 v[32:35], v[214:217], v[198:201], v[32:35]
	s_barrier
	s_setprio 0
	ds_read_b128 v[170:173], v163 offset:49152
	ds_read_b128 v[174:177], v163 offset:50176
	ds_read_b128 v[178:181], v163 offset:51200
	ds_read_b128 v[182:185], v163 offset:52224
	ds_read_b128 v[186:189], v163 offset:53248
	ds_read_b128 v[190:193], v163 offset:54272
	ds_read_b128 v[194:197], v163 offset:55296
	ds_read_b128 v[198:201], v163 offset:56320
	s_add_i32 s72, 0, 0x1c000
	s_add_i32 s10, s33, s78
	v_add_u32_e32 v144, s72, v160
	s_mov_b32 m0, s10
	s_nop 0
	global_load_lds_dwordx4 v138, s[98:99]
	s_add_i32 m0, s10, 0x2000
	s_nop 0
	global_load_lds_dwordx4 v142, s[98:99]
	s_mov_b32 m0, s84
	s_nop 0
	global_load_lds_dwordx4 v136, s[100:101]
	s_mov_b32 m0, s85
	s_nop 0
	global_load_lds_dwordx4 v140, s[100:101]
	s_add_u32 s10, s70, 0x80080
	s_addc_u32 s11, s71, 0
	s_add_i32 s33, s72, s78
	s_mov_b32 m0, s33
	s_nop 0
	global_load_lds_dwordx4 v138, s[10:11]
	s_add_i32 m0, s33, 0x2000
	s_nop 0
	global_load_lds_dwordx4 v142, s[10:11]
	s_waitcnt vmcnt(8)
	s_waitcnt lgkmcnt(0)
	s_setprio 1
	s_barrier
	v_mfma_f32_16x16x32_bf16 v[92:95], v[128:131], v[170:173], v[92:95]
	v_mfma_f32_16x16x32_bf16 v[88:91], v[154:157], v[170:173], v[88:91]
	v_mfma_f32_16x16x32_bf16 v[84:87], v[128:131], v[178:181], v[84:87]
	v_mfma_f32_16x16x32_bf16 v[80:83], v[154:157], v[178:181], v[80:83]
	v_mfma_f32_16x16x32_bf16 v[76:79], v[128:131], v[186:189], v[76:79]
	v_mfma_f32_16x16x32_bf16 v[72:75], v[154:157], v[186:189], v[72:75]
	v_mfma_f32_16x16x32_bf16 v[68:71], v[128:131], v[194:197], v[68:71]
	v_mfma_f32_16x16x32_bf16 v[64:67], v[154:157], v[194:197], v[64:67]
	s_add_i32 vcc_hi, vcc_hi, 2
	s_add_u32 s68, s68, 0x100
	s_addc_u32 s69, s69, 0
	s_add_u32 s97, s97, 0x100
	s_addc_u32 vcc_lo, vcc_lo, 0
	s_cmp_gt_u32 vcc_hi, 29
	v_mfma_f32_16x16x32_bf16 v[92:95], v[132:135], v[174:177], v[92:95]
	v_mfma_f32_16x16x32_bf16 v[88:91], v[166:169], v[174:177], v[88:91]
	v_mfma_f32_16x16x32_bf16 v[84:87], v[132:135], v[182:185], v[84:87]
	v_mfma_f32_16x16x32_bf16 v[80:83], v[166:169], v[182:185], v[80:83]
	v_mfma_f32_16x16x32_bf16 v[76:79], v[132:135], v[190:193], v[76:79]
	v_mfma_f32_16x16x32_bf16 v[72:75], v[166:169], v[190:193], v[72:75]
	v_mfma_f32_16x16x32_bf16 v[68:71], v[132:135], v[198:201], v[68:71]
	v_mfma_f32_16x16x32_bf16 v[64:67], v[166:169], v[198:201], v[64:67]
	v_mfma_f32_16x16x32_bf16 v[28:31], v[202:205], v[170:173], v[28:31]
	v_mfma_f32_16x16x32_bf16 v[24:27], v[210:213], v[170:173], v[24:27]
	v_mfma_f32_16x16x32_bf16 v[20:23], v[202:205], v[178:181], v[20:23]
	v_mfma_f32_16x16x32_bf16 v[16:19], v[210:213], v[178:181], v[16:19]
	v_mfma_f32_16x16x32_bf16 v[12:15], v[202:205], v[186:189], v[12:15]
	v_mfma_f32_16x16x32_bf16 v[8:11], v[210:213], v[186:189], v[8:11]
	v_mfma_f32_16x16x32_bf16 v[4:7], v[202:205], v[194:197], v[4:7]
	v_mfma_f32_16x16x32_bf16 v[0:3], v[210:213], v[194:197], v[0:3]
	v_mfma_f32_16x16x32_bf16 v[28:31], v[206:209], v[174:177], v[28:31]
	v_mfma_f32_16x16x32_bf16 v[24:27], v[214:217], v[174:177], v[24:27]
	v_mfma_f32_16x16x32_bf16 v[20:23], v[206:209], v[182:185], v[20:23]
	v_mfma_f32_16x16x32_bf16 v[16:19], v[214:217], v[182:185], v[16:19]
	v_mfma_f32_16x16x32_bf16 v[12:15], v[206:209], v[190:193], v[12:15]
	v_mfma_f32_16x16x32_bf16 v[8:11], v[214:217], v[190:193], v[8:11]
	v_mfma_f32_16x16x32_bf16 v[4:7], v[206:209], v[198:201], v[4:7]
	v_mfma_f32_16x16x32_bf16 v[0:3], v[214:217], v[198:201], v[0:3]
	s_barrier
; __device__ __forceinline__ unsigned cvt_pk_bf16(float lo, float hi) { const bf16v2_t v = __builtin_convertvector((f32x2){lo, hi}, bf16v2_t); return __builtin_bit_cast(unsigned, v); }
;     __device__ __forceinline__ void operator()(const AccT& acc, const pg8::Unit& u, int wr, int wc, int fr, int fq) const {
;     ...
;         } else {
;             if (u.pm >= 128) return;
;             const int col = (pn - 24) * 128 + cl;
; #pragma unroll
;             for (int ai = 0; ai < 2; ++ai)
; #pragma unroll
;                 for (int m = 0; m < 4; ++m) {
;                     const f32x4 a = acc[ai][0][m][0] * acc[ai][1][m][0], b = acc[ai][0][m][1] * acc[ai][1][m][1];
;                     u32x4 w; w.x = cvt_pk_bf16(a[0], a[1]); w.y = cvt_pk_bf16(a[2], a[3]); w.z = cvt_pk_bf16(b[0], b[1]); w.w = cvt_pk_bf16(b[2], b[3]);
;                     *(u32x4*)(P + (size_t)(row0 + ai * 128 + m * 16) * 1024 + col) = w;
;                 }
	s_cbranch_scc0 .LBB0_235
	s_setprio 0
	v_lshl_add_u32 v154, s4, 8, v147
	s_cmp_gt_i32 s66, 7
	s_mov_b64 s[68:69], -1
	s_cbranch_scc0 .LBB0_277
	s_cmpk_gt_i32 s4, 0x7f
	s_cselect_b64 s[68:69], -1, 0
	s_cmpk_lt_i32 s4, 0x80
	s_cselect_b64 s[70:71], -1, 0
	s_cmp_gt_u32 s66, 23
	s_mov_b64 s[4:5], -1
	s_cbranch_scc0 .LBB0_241
	s_andn2_b64 vcc, exec, s[70:71]
	s_cbranch_vccnz .LBB0_240
	v_pk_mul_f32 v[130:131], v[126:127], v[62:63]
	v_pk_mul_f32 v[128:129], v[124:125], v[60:61]
	v_pk_mul_f32 v[132:133], v[122:123], v[58:59]
	v_ashrrev_i32_e32 v155, 31, v154
	v_lshl_add_u32 v144, s66, 7, v161
	v_pk_mul_f32 v[134:135], v[120:121], v[56:57]
	v_cvt_pk_bf16_f32 v128, v128, v129
	v_cvt_pk_bf16_f32 v129, v130, v131
	v_cvt_pk_bf16_f32 v131, v132, v133
	v_lshlrev_b64 v[132:133], 11, v[154:155]
	v_cvt_pk_bf16_f32 v130, v134, v135
	v_lshl_add_u64 v[132:133], s[8:9], 0, v[132:133]
	v_lshlrev_b64 v[134:135], 1, v[144:145]
	v_lshl_add_u64 v[132:133], v[132:133], 0, v[134:135]
	global_store_dwordx4 v[132:133], v[128:131], off
	v_pk_mul_f32 v[156:157], v[114:115], v[50:51]
	v_pk_mul_f32 v[158:159], v[112:113], v[48:49]
	v_pk_mul_f32 v[130:131], v[118:119], v[54:55]
	v_pk_mul_f32 v[128:129], v[116:117], v[52:53]
	s_mov_b32 s0, 0x40000
	v_cvt_pk_bf16_f32 v128, v128, v129
	v_cvt_pk_bf16_f32 v129, v130, v131
	v_cvt_pk_bf16_f32 v131, v156, v157
	v_or_b32_e32 v156, 16, v154
	v_ashrrev_i32_e32 v157, 31, v156
	v_lshlrev_b64 v[156:157], 11, v[156:157]
	v_lshl_add_u64 v[156:157], s[8:9], 0, v[156:157]
	v_cvt_pk_bf16_f32 v130, v158, v159
	v_lshl_add_u64 v[156:157], v[156:157], 0, v[134:135]
	global_store_dwordx4 v[156:157], v[128:131], off
	v_pk_mul_f32 v[156:157], v[106:107], v[42:43]
	v_pk_mul_f32 v[158:159], v[104:105], v[40:41]
	v_pk_mul_f32 v[130:131], v[110:111], v[46:47]
	v_pk_mul_f32 v[128:129], v[108:109], v[44:45]
	s_nop 0
	v_cvt_pk_bf16_f32 v128, v128, v129
	v_cvt_pk_bf16_f32 v129, v130, v131
	v_cvt_pk_bf16_f32 v131, v156, v157
	v_or_b32_e32 v156, 32, v154
	v_ashrrev_i32_e32 v157, 31, v156
	v_lshlrev_b64 v[156:157], 11, v[156:157]
	v_lshl_add_u64 v[156:157], s[8:9], 0, v[156:157]
	v_cvt_pk_bf16_f32 v130, v158, v159
	v_lshl_add_u64 v[156:157], v[156:157], 0, v[134:135]
	global_store_dwordx4 v[156:157], v[128:131], off
	v_pk_mul_f32 v[156:157], v[98:99], v[34:35]
	v_pk_mul_f32 v[158:159], v[96:97], v[32:33]
	v_pk_mul_f32 v[130:131], v[102:103], v[38:39]
	v_pk_mul_f32 v[128:129], v[100:101], v[36:37]
	s_nop 0
	v_cvt_pk_bf16_f32 v128, v128, v129
	v_cvt_pk_bf16_f32 v129, v130, v131
	v_cvt_pk_bf16_f32 v131, v156, v157
	v_or_b32_e32 v156, 48, v154
	v_ashrrev_i32_e32 v157, 31, v156
	v_lshlrev_b64 v[156:157], 11, v[156:157]
	v_lshl_add_u64 v[156:157], s[8:9], 0, v[156:157]
	v_cvt_pk_bf16_f32 v130, v158, v159
	v_lshl_add_u64 v[134:135], v[156:157], 0, v[134:135]
	global_store_dwordx4 v[134:135], v[128:131], off
	v_pk_mul_f32 v[134:135], v[90:91], v[26:27]
	v_pk_mul_f32 v[156:157], v[88:89], v[24:25]
	v_pk_mul_f32 v[130:131], v[94:95], v[30:31]
	v_pk_mul_f32 v[128:129], v[92:93], v[28:29]
	s_nop 0
	v_cvt_pk_bf16_f32 v128, v128, v129
	v_cvt_pk_bf16_f32 v129, v130, v131
	v_cvt_pk_bf16_f32 v131, v134, v135
	v_add_co_u32_e32 v134, vcc, s0, v132
	v_cvt_pk_bf16_f32 v130, v156, v157
	s_nop 0
	v_addc_co_u32_e32 v135, vcc, 0, v133, vcc
	global_store_dwordx4 v[134:135], v[128:131], off
	v_pk_mul_f32 v[134:135], v[82:83], v[18:19]
	s_mov_b32 s0, 0x48000
	v_pk_mul_f32 v[130:131], v[86:87], v[22:23]
	v_pk_mul_f32 v[128:129], v[84:85], v[20:21]
	v_pk_mul_f32 v[156:157], v[80:81], v[16:17]
	v_cvt_pk_bf16_f32 v128, v128, v129
	v_cvt_pk_bf16_f32 v129, v130, v131
	v_cvt_pk_bf16_f32 v131, v134, v135
	v_add_co_u32_e32 v134, vcc, s0, v132
	v_cvt_pk_bf16_f32 v130, v156, v157
	s_nop 0
	v_addc_co_u32_e32 v135, vcc, 0, v133, vcc
	global_store_dwordx4 v[134:135], v[128:131], off
	v_pk_mul_f32 v[134:135], v[74:75], v[10:11]
	s_mov_b32 s0, 0x50000
	v_pk_mul_f32 v[130:131], v[78:79], v[14:15]
	v_pk_mul_f32 v[128:129], v[76:77], v[12:13]
	v_pk_mul_f32 v[156:157], v[72:73], v[8:9]
	v_cvt_pk_bf16_f32 v128, v128, v129
	v_cvt_pk_bf16_f32 v129, v130, v131
	v_cvt_pk_bf16_f32 v131, v134, v135
	v_add_co_u32_e32 v134, vcc, s0, v132
	v_cvt_pk_bf16_f32 v130, v156, v157
	s_nop 0
	v_addc_co_u32_e32 v135, vcc, 0, v133, vcc
	global_store_dwordx4 v[134:135], v[128:131], off
	v_pk_mul_f32 v[134:135], v[66:67], v[2:3]
	v_pk_mul_f32 v[156:157], v[64:65], v[0:1]
	v_pk_mul_f32 v[130:131], v[70:71], v[6:7]
	v_pk_mul_f32 v[128:129], v[68:69], v[4:5]
	v_add_co_u32_e32 v132, vcc, 0x58000, v132
	v_cvt_pk_bf16_f32 v128, v128, v129
	v_cvt_pk_bf16_f32 v129, v130, v131
	v_cvt_pk_bf16_f32 v130, v156, v157
	v_cvt_pk_bf16_f32 v131, v134, v135
	v_addc_co_u32_e32 v133, vcc, 0, v133, vcc
	global_store_dwordx4 v[132:133], v[128:131], off

; #define PG8_STAGE(bufoff, gbase, voff) do { _Pragma("unroll") for (int _i = 0; _i < 2; ++_i) \
;         __builtin_amdgcn_global_load_lds((const unsigned*)((const char*)(gbase) + (voff)[_i]), (PG8_LAS unsigned*)(lds + (bufoff) + ldsw + _i * 8192), 16, 0, 0); } while (0)
; #define PG8_WAIT_V(n) asm volatile("s_waitcnt vmcnt(" #n ")" ::: "memory")
; template <class Epi, class Sched>
; __device__ __forceinline__ void gemm_phase(PG8_LAS unsigned char* lds, const Gemm g, const Sched& S, const Epi& E) {
;     ...
;         const bool has_next = S.next(ui + 1, nxt);
;         const char* nA = has_next ? (const char*)g.A + (size_t)nxt.pm * tstep : cA; const char* nB = has_next ? (const char*)g.Bt + (size_t)nxt.pn * tstep : cB;
;         for (int t = 0; t < nt; t += 2) {
;             const bool last = (t == nt - 2);
;             const char* a1 = cA + (size_t)(t + 1) * kstep;
;             const char* a2 = last ? nA : cA + (size_t)(t + 2) * kstep; const char* b2 = last ? nB : cB + (size_t)(t + 2) * kstep;
;             const char* a3 = a2 + kstep; const char* b3 = b2 + kstep;
;             if (last && has_next) S.a_ready(nxt);
;             PG8_LDB(B0, 0, 0); PG8_SCHED; PG8_LDA(At, 0, 0); PG8_STAGE(PG8_SA(1, 1), a1 + hstep, voffA);
;             PG8_WAIT_L(8); PG8_BAR; PG8_WAIT_L(0); PG8_MMA(0, 0, At, B0); PG8_BAR; PG8_SCHED;
;             PG8_LDB(B1, 0, 1); PG8_STAGE(PG8_SB(0, 0), b2, voffB);
;             PG8_BAR; PG8_WAIT_L(0); PG8_MMA(0, 1, At, B1); PG8_BAR;
;             PG8_LDA(At, 0, 1); PG8_STAGE(PG8_SA(0, 0), a2, voffA);
;             PG8_BAR; PG8_WAIT_L(0); PG8_MMA(1, 0, At, B0); PG8_BAR; PG8_SCHED;
;             PG8_STAGE(PG8_SB(0, 1), b2 + hstep, voffB);
;             PG8_WAIT_V(6); PG8_BAR; PG8_MMA(1, 1, At, B1); PG8_BAR;
;             PG8_LDB(B0, 1, 0); PG8_SCHED; PG8_LDA(At, 1, 0); PG8_STAGE(PG8_SA(0, 1), a2 + hstep, voffA);
;             PG8_WAIT_L(8); PG8_BAR; PG8_WAIT_L(0); PG8_MMA(0, 0, At, B0); PG8_BAR; PG8_SCHED;
;             PG8_LDB(B1, 1, 1); PG8_STAGE(PG8_SB(1, 0), b3, voffB);
;             PG8_BAR; PG8_WAIT_L(0); PG8_MMA(0, 1, At, B1); PG8_BAR;
;             PG8_LDA(At, 1, 1); PG8_STAGE(PG8_SA(1, 0), a3, voffA);
;             PG8_BAR; PG8_WAIT_L(0); PG8_MMA(1, 0, At, B0); PG8_BAR; PG8_SCHED;
;             PG8_STAGE(PG8_SB(1, 1), b3 + hstep, voffB);
;             PG8_WAIT_V(6); PG8_BAR; PG8_MMA(1, 1, At, B1); PG8_BAR;
.LBB0_665:
	s_ashr_i32 s19, s18, 31
	s_lshl_b64 s[10:11], s[18:19], 20
	v_cmp_lt_i64_e32 vcc, s[20:21], v[156:157]
	s_add_u32 s20, s41, s10
	s_addc_u32 s21, s42, s11
	s_and_b64 s[10:11], vcc, exec
	s_cselect_b32 s19, s21, s31
	s_cselect_b32 s70, s20, s30
	s_ashr_i32 s17, s16, 31
	s_lshl_b64 s[10:11], s[16:17], 20
	s_add_u32 s26, s43, s10
	s_addc_u32 s27, s44, s11
	s_and_b64 s[10:11], vcc, exec
	s_cselect_b32 s17, s27, s35
	s_cselect_b32 s71, s26, s34
	s_add_u32 s30, s30, 0x80080
	s_addc_u32 s31, s31, 0
	s_add_u32 s72, s34, 0x100
	s_addc_u32 s73, s35, 0
	s_mov_b32 s74, -2
	s_setprio 0
	ds_read_b128 v[128:131], v169
	ds_read_b128 v[132:135], v169 offset:1024
	ds_read_b128 v[136:139], v169 offset:2048
	ds_read_b128 v[140:143], v169 offset:3072
	ds_read_b128 v[160:163], v170
	ds_read_b128 v[172:175], v170 offset:1024
	ds_read_b128 v[176:179], v170 offset:2048
	ds_read_b128 v[180:183], v170 offset:3072
	ds_read_b128 v[184:187], v170 offset:4096
	ds_read_b128 v[188:191], v170 offset:5120
	ds_read_b128 v[192:195], v170 offset:6144
	ds_read_b128 v[196:199], v170 offset:7168
	s_waitcnt lgkmcnt(11)
	ds_read_b128 v[200:203], v171
	ds_read_b128 v[204:207], v171 offset:1024
	ds_read_b128 v[208:211], v171 offset:2048
	ds_read_b128 v[212:215], v171 offset:3072
	s_add_u32 s10, s30, 0xfff80080
	s_addc_u32 s11, s31, -1
	s_cmp_eq_u32 s74, 28
	s_cselect_b32 s39, s19, s11
	s_cselect_b32 s38, s70, s10
	s_cselect_b32 s35, s17, s73
	s_cselect_b32 s34, s71, s72
	s_add_u32 s98, s34, s4
	s_addc_u32 s99, s35, s5
	s_add_u32 s100, s38, s4
	s_addc_u32 s101, s39, s5
	s_add_i32 m0, s29, 0xc000
	s_nop 0
	global_load_lds_dwordx4 v152, s[30:31]
	s_add_i32 m0, s29, 0xe000
	s_nop 0
	global_load_lds_dwordx4 v154, s[30:31]
	s_waitcnt vmcnt(8)
	s_waitcnt lgkmcnt(0)
	s_setprio 1
	s_barrier
	v_mfma_f32_16x16x32_bf16 v[120:123], v[128:131], v[160:163], 0
	v_mfma_f32_16x16x32_bf16 v[124:127], v[136:139], v[160:163], 0
	v_mfma_f32_16x16x32_bf16 v[112:115], v[128:131], v[176:179], 0
	v_mfma_f32_16x16x32_bf16 v[116:119], v[136:139], v[176:179], 0
	v_mfma_f32_16x16x32_bf16 v[96:99], v[128:131], v[184:187], 0
	v_mfma_f32_16x16x32_bf16 v[88:91], v[136:139], v[184:187], 0
	v_mfma_f32_16x16x32_bf16 v[80:83], v[128:131], v[192:195], 0
	v_mfma_f32_16x16x32_bf16 v[72:75], v[136:139], v[192:195], 0
	v_mfma_f32_16x16x32_bf16 v[120:123], v[132:135], v[172:175], v[120:123]
	v_mfma_f32_16x16x32_bf16 v[124:127], v[140:143], v[172:175], v[124:127]
	v_mfma_f32_16x16x32_bf16 v[112:115], v[132:135], v[180:183], v[112:115]
	v_mfma_f32_16x16x32_bf16 v[116:119], v[140:143], v[180:183], v[116:119]
	v_mfma_f32_16x16x32_bf16 v[96:99], v[132:135], v[188:191], v[96:99]
	v_mfma_f32_16x16x32_bf16 v[88:91], v[140:143], v[188:191], v[88:91]
	v_mfma_f32_16x16x32_bf16 v[80:83], v[132:135], v[196:199], v[80:83]
	v_mfma_f32_16x16x32_bf16 v[72:75], v[140:143], v[196:199], v[72:75]
	v_mfma_f32_16x16x32_bf16 v[108:111], v[200:203], v[160:163], 0
	v_mfma_f32_16x16x32_bf16 v[104:107], v[208:211], v[160:163], 0
	v_mfma_f32_16x16x32_bf16 v[100:103], v[200:203], v[176:179], 0
	v_mfma_f32_16x16x32_bf16 v[92:95], v[208:211], v[176:179], 0
	v_mfma_f32_16x16x32_bf16 v[84:87], v[200:203], v[184:187], 0
	v_mfma_f32_16x16x32_bf16 v[76:79], v[208:211], v[184:187], 0
	v_mfma_f32_16x16x32_bf16 v[68:71], v[200:203], v[192:195], 0
	v_mfma_f32_16x16x32_bf16 v[64:67], v[208:211], v[192:195], 0
	v_mfma_f32_16x16x32_bf16 v[108:111], v[204:207], v[172:175], v[108:111]
	v_mfma_f32_16x16x32_bf16 v[104:107], v[212:215], v[172:175], v[104:107]
	v_mfma_f32_16x16x32_bf16 v[100:103], v[204:207], v[180:183], v[100:103]
	v_mfma_f32_16x16x32_bf16 v[92:95], v[212:215], v[180:183], v[92:95]
	v_mfma_f32_16x16x32_bf16 v[84:87], v[204:207], v[188:191], v[84:87]
	v_mfma_f32_16x16x32_bf16 v[76:79], v[212:215], v[188:191], v[76:79]
	v_mfma_f32_16x16x32_bf16 v[68:71], v[204:207], v[196:199], v[68:71]
	v_mfma_f32_16x16x32_bf16 v[64:67], v[212:215], v[196:199], v[64:67]
	s_barrier
	s_setprio 0
	ds_read_b128 v[160:163], v170 offset:16384
	ds_read_b128 v[172:175], v170 offset:17408
	ds_read_b128 v[176:179], v170 offset:18432
	ds_read_b128 v[180:183], v170 offset:19456
	ds_read_b128 v[184:187], v170 offset:20480
	ds_read_b128 v[188:191], v170 offset:21504
	ds_read_b128 v[192:195], v170 offset:22528
	ds_read_b128 v[196:199], v170 offset:23552
	s_add_i32 s10, s66, s45
	s_mov_b32 m0, s10
	s_nop 0
	global_load_lds_dwordx4 v146, s[34:35]
	s_add_i32 m0, s10, 0x2000
	s_nop 0
	global_load_lds_dwordx4 v150, s[34:35]
	s_mov_b32 m0, s29
	s_nop 0
	global_load_lds_dwordx4 v144, s[38:39]
	s_mov_b32 m0, s46
	s_nop 0
	global_load_lds_dwordx4 v148, s[38:39]
	s_add_u32 s10, s34, 0x80000
	s_addc_u32 s11, s35, 0
	s_add_i32 s33, s67, s45
	s_mov_b32 m0, s33
	s_nop 0
	global_load_lds_dwordx4 v146, s[10:11]
	s_add_i32 m0, s33, 0x2000
	s_nop 0
	global_load_lds_dwordx4 v150, s[10:11]
	s_waitcnt vmcnt(8)
	s_waitcnt lgkmcnt(0)
	s_setprio 1
	s_barrier
; #define PG8_STAGE(bufoff, gbase, voff) do { _Pragma("unroll") for (int _i = 0; _i < 2; ++_i) \
;         __builtin_amdgcn_global_load_lds((const unsigned*)((const char*)(gbase) + (voff)[_i]), (PG8_LAS unsigned*)(lds + (bufoff) + ldsw + _i * 8192), 16, 0, 0); } while (0)
; #define PG8_LDA(dst, b, h) do { _Pragma("unroll") for (int m = 0; m < 4; ++m) _Pragma("unroll") for (int k = 0; k < 2; ++k) dst[m][k] = *(const PG8_LAS bf16x8*)(lds + PG8_SA(b, h) + aoff + m * 2048 + k * 1024); } while (0)
; #define PG8_LDB(dst, b, h) do { _Pragma("unroll") for (int n = 0; n < 2; ++n) _Pragma("unroll") for (int k = 0; k < 2; ++k) dst[n][k] = *(const PG8_LAS bf16x8*)(lds + PG8_SB(b, h) + boff + n * 2048 + k * 1024); } while (0)
; #define PG8_WAIT_V(n) asm volatile("s_waitcnt vmcnt(" #n ")" ::: "memory")
; #define PG8_WAIT_L(n) asm volatile("s_waitcnt lgkmcnt(" #n ")" ::: "memory")
; #define PG8_BAR __builtin_amdgcn_s_barrier()
; #define PG8_SCHED __builtin_amdgcn_sched_barrier(0)
; template <class Epi, class Sched>
; __device__ __forceinline__ void gemm_phase(PG8_LAS unsigned char* lds, const Gemm g, const Sched& S, const Epi& E) {
;     ...
;             PG8_LDB(B0, 0, 0); PG8_SCHED; PG8_LDA(At, 0, 0); PG8_STAGE(PG8_SA(1, 1), a1 + hstep, voffA);
;             PG8_WAIT_L(8); PG8_BAR; PG8_WAIT_L(0); PG8_MMA(0, 0, At, B0); PG8_BAR; PG8_SCHED;
;             PG8_LDB(B1, 0, 1); PG8_STAGE(PG8_SB(0, 0), b2, voffB);
;             PG8_BAR; PG8_WAIT_L(0); PG8_MMA(0, 1, At, B1); PG8_BAR;
;             PG8_LDA(At, 0, 1); PG8_STAGE(PG8_SA(0, 0), a2, voffA);
;             PG8_BAR; PG8_WAIT_L(0); PG8_MMA(1, 0, At, B0); PG8_BAR; PG8_SCHED;
;             PG8_STAGE(PG8_SB(0, 1), b2 + hstep, voffB);
;             PG8_WAIT_V(6); PG8_BAR; PG8_MMA(1, 1, At, B1); PG8_BAR;
;             PG8_LDB(B0, 1, 0); PG8_SCHED; PG8_LDA(At, 1, 0); PG8_STAGE(PG8_SA(0, 1), a2 + hstep, voffA);
;             PG8_WAIT_L(8); PG8_BAR; PG8_WAIT_L(0); PG8_MMA(0, 0, At, B0); PG8_BAR; PG8_SCHED;
;             PG8_LDB(B1, 1, 1); PG8_STAGE(PG8_SB(1, 0), b3, voffB);
;             PG8_BAR; PG8_WAIT_L(0); PG8_MMA(0, 1, At, B1); PG8_BAR;
;             PG8_LDA(At, 1, 1); PG8_STAGE(PG8_SA(1, 0), a3, voffA);
;             PG8_BAR; PG8_WAIT_L(0); PG8_MMA(1, 0, At, B0); PG8_BAR; PG8_SCHED;
;             PG8_STAGE(PG8_SB(1, 1), b3 + hstep, voffB);
;             PG8_WAIT_V(6); PG8_BAR; PG8_MMA(1, 1, At, B1); PG8_BAR;
	v_mfma_f32_16x16x32_bf16 v[60:63], v[128:131], v[160:163], 0
	v_mfma_f32_16x16x32_bf16 v[56:59], v[136:139], v[160:163], 0
	v_mfma_f32_16x16x32_bf16 v[48:51], v[128:131], v[176:179], 0
	v_mfma_f32_16x16x32_bf16 v[40:43], v[136:139], v[176:179], 0
	v_mfma_f32_16x16x32_bf16 v[32:35], v[128:131], v[184:187], 0
	v_mfma_f32_16x16x32_bf16 v[24:27], v[136:139], v[184:187], 0
	v_mfma_f32_16x16x32_bf16 v[16:19], v[128:131], v[192:195], 0
	v_mfma_f32_16x16x32_bf16 v[8:11], v[136:139], v[192:195], 0
	s_add_i32 s33, 0, 0x18000
	v_mfma_f32_16x16x32_bf16 v[60:63], v[132:135], v[172:175], v[60:63]
	v_mfma_f32_16x16x32_bf16 v[56:59], v[140:143], v[172:175], v[56:59]
	v_mfma_f32_16x16x32_bf16 v[48:51], v[132:135], v[180:183], v[48:51]
	v_mfma_f32_16x16x32_bf16 v[40:43], v[140:143], v[180:183], v[40:43]
	v_mfma_f32_16x16x32_bf16 v[32:35], v[132:135], v[188:191], v[32:35]
	v_mfma_f32_16x16x32_bf16 v[24:27], v[140:143], v[188:191], v[24:27]
	v_mfma_f32_16x16x32_bf16 v[16:19], v[132:135], v[196:199], v[16:19]
	v_mfma_f32_16x16x32_bf16 v[8:11], v[140:143], v[196:199], v[8:11]
	v_mfma_f32_16x16x32_bf16 v[52:55], v[200:203], v[160:163], 0
	v_mfma_f32_16x16x32_bf16 v[44:47], v[208:211], v[160:163], 0
	v_mfma_f32_16x16x32_bf16 v[36:39], v[200:203], v[176:179], 0
	v_mfma_f32_16x16x32_bf16 v[28:31], v[208:211], v[176:179], 0
	v_mfma_f32_16x16x32_bf16 v[20:23], v[200:203], v[184:187], 0
	v_mfma_f32_16x16x32_bf16 v[12:15], v[208:211], v[184:187], 0
	v_mfma_f32_16x16x32_bf16 v[4:7], v[200:203], v[192:195], 0
	v_mfma_f32_16x16x32_bf16 v[0:3], v[208:211], v[192:195], 0
	v_mfma_f32_16x16x32_bf16 v[52:55], v[204:207], v[172:175], v[52:55]
	v_mfma_f32_16x16x32_bf16 v[44:47], v[212:215], v[172:175], v[44:47]
	v_mfma_f32_16x16x32_bf16 v[36:39], v[204:207], v[180:183], v[36:39]
	v_mfma_f32_16x16x32_bf16 v[28:31], v[212:215], v[180:183], v[28:31]
	v_mfma_f32_16x16x32_bf16 v[20:23], v[204:207], v[188:191], v[20:23]
	v_mfma_f32_16x16x32_bf16 v[12:15], v[212:215], v[188:191], v[12:15]
	v_mfma_f32_16x16x32_bf16 v[4:7], v[204:207], v[196:199], v[4:7]
	v_mfma_f32_16x16x32_bf16 v[0:3], v[212:215], v[196:199], v[0:3]
	s_barrier
	s_setprio 0
	ds_read_b128 v[128:131], v169 offset:32768
	ds_read_b128 v[132:135], v169 offset:33792
	ds_read_b128 v[136:139], v169 offset:34816
	ds_read_b128 v[140:143], v169 offset:35840
	ds_read_b128 v[160:163], v170 offset:32768
	ds_read_b128 v[172:175], v170 offset:33792
	ds_read_b128 v[176:179], v170 offset:34816
	ds_read_b128 v[180:183], v170 offset:35840
	ds_read_b128 v[184:187], v170 offset:36864
	ds_read_b128 v[188:191], v170 offset:37888
	ds_read_b128 v[192:195], v170 offset:38912
	ds_read_b128 v[196:199], v170 offset:39936
	s_waitcnt lgkmcnt(11)
	ds_read_b128 v[200:203], v171 offset:32768
	ds_read_b128 v[204:207], v171 offset:33792
	ds_read_b128 v[208:211], v171 offset:34816
	ds_read_b128 v[212:215], v171 offset:35840
	s_add_u32 s10, s38, 0x80000
	s_addc_u32 s11, s39, 0
	s_mov_b32 m0, s47
	s_nop 0
	global_load_lds_dwordx4 v144, s[10:11]
	s_mov_b32 m0, s48
	s_nop 0
	global_load_lds_dwordx4 v148, s[10:11]
	s_waitcnt vmcnt(8)
	s_waitcnt lgkmcnt(0)
	s_setprio 1
	s_barrier
	v_mfma_f32_16x16x32_bf16 v[120:123], v[128:131], v[160:163], v[120:123]
	v_mfma_f32_16x16x32_bf16 v[124:127], v[136:139], v[160:163], v[124:127]
	v_mfma_f32_16x16x32_bf16 v[112:115], v[128:131], v[176:179], v[112:115]
	v_mfma_f32_16x16x32_bf16 v[116:119], v[136:139], v[176:179], v[116:119]
	v_mfma_f32_16x16x32_bf16 v[96:99], v[128:131], v[184:187], v[96:99]
	v_mfma_f32_16x16x32_bf16 v[88:91], v[136:139], v[184:187], v[88:91]
	v_mfma_f32_16x16x32_bf16 v[80:83], v[128:131], v[192:195], v[80:83]
	v_mfma_f32_16x16x32_bf16 v[72:75], v[136:139], v[192:195], v[72:75]
	v_mfma_f32_16x16x32_bf16 v[120:123], v[132:135], v[172:175], v[120:123]
	v_mfma_f32_16x16x32_bf16 v[124:127], v[140:143], v[172:175], v[124:127]
	v_mfma_f32_16x16x32_bf16 v[112:115], v[132:135], v[180:183], v[112:115]
	v_mfma_f32_16x16x32_bf16 v[116:119], v[140:143], v[180:183], v[116:119]
	v_mfma_f32_16x16x32_bf16 v[96:99], v[132:135], v[188:191], v[96:99]
	v_mfma_f32_16x16x32_bf16 v[88:91], v[140:143], v[188:191], v[88:91]
	v_mfma_f32_16x16x32_bf16 v[80:83], v[132:135], v[196:199], v[80:83]
	v_mfma_f32_16x16x32_bf16 v[72:75], v[140:143], v[196:199], v[72:75]
	v_mfma_f32_16x16x32_bf16 v[108:111], v[200:203], v[160:163], v[108:111]
	v_mfma_f32_16x16x32_bf16 v[104:107], v[208:211], v[160:163], v[104:107]
	v_mfma_f32_16x16x32_bf16 v[100:103], v[200:203], v[176:179], v[100:103]
	v_mfma_f32_16x16x32_bf16 v[92:95], v[208:211], v[176:179], v[92:95]
	v_mfma_f32_16x16x32_bf16 v[84:87], v[200:203], v[184:187], v[84:87]
	v_mfma_f32_16x16x32_bf16 v[76:79], v[208:211], v[184:187], v[76:79]
	v_mfma_f32_16x16x32_bf16 v[68:71], v[200:203], v[192:195], v[68:71]
	v_mfma_f32_16x16x32_bf16 v[64:67], v[208:211], v[192:195], v[64:67]
	v_mfma_f32_16x16x32_bf16 v[108:111], v[204:207], v[172:175], v[108:111]
	v_mfma_f32_16x16x32_bf16 v[104:107], v[212:215], v[172:175], v[104:107]
	v_mfma_f32_16x16x32_bf16 v[100:103], v[204:207], v[180:183], v[100:103]
	v_mfma_f32_16x16x32_bf16 v[92:95], v[212:215], v[180:183], v[92:95]
	v_mfma_f32_16x16x32_bf16 v[84:87], v[204:207], v[188:191], v[84:87]
	v_mfma_f32_16x16x32_bf16 v[76:79], v[212:215], v[188:191], v[76:79]
	v_mfma_f32_16x16x32_bf16 v[68:71], v[204:207], v[196:199], v[68:71]
	v_mfma_f32_16x16x32_bf16 v[64:67], v[212:215], v[196:199], v[64:67]
	s_barrier
; #define PG8_STAGE(bufoff, gbase, voff) do { _Pragma("unroll") for (int _i = 0; _i < 2; ++_i) \
;         __builtin_amdgcn_global_load_lds((const unsigned*)((const char*)(gbase) + (voff)[_i]), (PG8_LAS unsigned*)(lds + (bufoff) + ldsw + _i * 8192), 16, 0, 0); } while (0)
; #define PG8_LDA(dst, b, h) do { _Pragma("unroll") for (int m = 0; m < 4; ++m) _Pragma("unroll") for (int k = 0; k < 2; ++k) dst[m][k] = *(const PG8_LAS bf16x8*)(lds + PG8_SA(b, h) + aoff + m * 2048 + k * 1024); } while (0)
; template <class Epi, class Sched>
; __device__ __forceinline__ void gemm_phase(PG8_LAS unsigned char* lds, const Gemm g, const Sched& S, const Epi& E) {
;     ...
;         const bool has_next = S.next(ui + 1, nxt);
;         const char* nA = has_next ? (const char*)g.A + (size_t)nxt.pm * tstep : cA; const char* nB = has_next ? (const char*)g.Bt + (size_t)nxt.pn * tstep : cB;
;         for (int t = 0; t < nt; t += 2) {
;             const bool last = (t == nt - 2);
;             const char* a1 = cA + (size_t)(t + 1) * kstep;
;             const char* a2 = last ? nA : cA + (size_t)(t + 2) * kstep; const char* b2 = last ? nB : cB + (size_t)(t + 2) * kstep;
;     ...
;             PG8_LDB(B0, 0, 0); PG8_SCHED; PG8_LDA(At, 0, 0); PG8_STAGE(PG8_SA(1, 1), a1 + hstep, voffA);
;             PG8_WAIT_L(8); PG8_BAR; PG8_WAIT_L(0); PG8_MMA(0, 0, At, B0); PG8_BAR; PG8_SCHED;
;             PG8_LDB(B1, 0, 1); PG8_STAGE(PG8_SB(0, 0), b2, voffB);
;             PG8_BAR; PG8_WAIT_L(0); PG8_MMA(0, 1, At, B1); PG8_BAR;
;             PG8_LDA(At, 0, 1); PG8_STAGE(PG8_SA(0, 0), a2, voffA);
;             PG8_BAR; PG8_WAIT_L(0); PG8_MMA(1, 0, At, B0); PG8_BAR; PG8_SCHED;
;             PG8_STAGE(PG8_SB(0, 1), b2 + hstep, voffB);
;             PG8_WAIT_V(6); PG8_BAR; PG8_MMA(1, 1, At, B1); PG8_BAR;
;             PG8_LDB(B0, 1, 0); PG8_SCHED; PG8_LDA(At, 1, 0); PG8_STAGE(PG8_SA(0, 1), a2 + hstep, voffA);
;             PG8_WAIT_L(8); PG8_BAR; PG8_WAIT_L(0); PG8_MMA(0, 0, At, B0); PG8_BAR; PG8_SCHED;
;             PG8_LDB(B1, 1, 1); PG8_STAGE(PG8_SB(1, 0), b3, voffB);
;             PG8_BAR; PG8_WAIT_L(0); PG8_MMA(0, 1, At, B1); PG8_BAR;
;             PG8_LDA(At, 1, 1); PG8_STAGE(PG8_SA(1, 0), a3, voffA);
;             PG8_BAR; PG8_WAIT_L(0); PG8_MMA(1, 0, At, B0); PG8_BAR; PG8_SCHED;
;             PG8_STAGE(PG8_SB(1, 1), b3 + hstep, voffB);
;             PG8_WAIT_V(6); PG8_BAR; PG8_MMA(1, 1, At, B1); PG8_BAR;
	s_setprio 0
	ds_read_b128 v[160:163], v170 offset:49152
	ds_read_b128 v[172:175], v170 offset:50176
	ds_read_b128 v[176:179], v170 offset:51200
	ds_read_b128 v[180:183], v170 offset:52224
	ds_read_b128 v[184:187], v170 offset:53248
	ds_read_b128 v[188:191], v170 offset:54272
	ds_read_b128 v[192:195], v170 offset:55296
	ds_read_b128 v[196:199], v170 offset:56320
	s_add_i32 s38, 0, 0x1c000
	s_add_i32 s10, s33, s45
	s_mov_b32 m0, s10
	s_nop 0
	global_load_lds_dwordx4 v146, s[98:99]
	s_add_i32 m0, s10, 0x2000
	s_nop 0
	global_load_lds_dwordx4 v150, s[98:99]
	s_mov_b32 m0, s50
	s_nop 0
	global_load_lds_dwordx4 v144, s[100:101]
	s_mov_b32 m0, s51
	s_nop 0
	global_load_lds_dwordx4 v148, s[100:101]
	s_add_u32 s10, s34, 0x80080
	s_addc_u32 s11, s35, 0
	s_add_i32 s33, s38, s45
	s_mov_b32 m0, s33
	s_nop 0
	global_load_lds_dwordx4 v146, s[10:11]
	s_add_i32 m0, s33, 0x2000
	s_nop 0
	global_load_lds_dwordx4 v150, s[10:11]
	s_waitcnt vmcnt(8)
	s_waitcnt lgkmcnt(0)
	s_setprio 1
	s_barrier
	v_mfma_f32_16x16x32_bf16 v[60:63], v[128:131], v[160:163], v[60:63]
	v_mfma_f32_16x16x32_bf16 v[56:59], v[136:139], v[160:163], v[56:59]
	v_mfma_f32_16x16x32_bf16 v[48:51], v[128:131], v[176:179], v[48:51]
	v_mfma_f32_16x16x32_bf16 v[40:43], v[136:139], v[176:179], v[40:43]
	v_mfma_f32_16x16x32_bf16 v[32:35], v[128:131], v[184:187], v[32:35]
	v_mfma_f32_16x16x32_bf16 v[24:27], v[136:139], v[184:187], v[24:27]
	v_mfma_f32_16x16x32_bf16 v[16:19], v[128:131], v[192:195], v[16:19]
	v_mfma_f32_16x16x32_bf16 v[8:11], v[136:139], v[192:195], v[8:11]
	s_add_i32 s74, s74, 2
	s_add_u32 s30, s30, 0x100
	s_addc_u32 s31, s31, 0
	s_add_u32 s72, s72, 0x100
	s_addc_u32 s73, s73, 0
	s_cmp_gt_u32 s74, 29
	v_mfma_f32_16x16x32_bf16 v[60:63], v[132:135], v[172:175], v[60:63]
	v_mfma_f32_16x16x32_bf16 v[56:59], v[140:143], v[172:175], v[56:59]
	v_mfma_f32_16x16x32_bf16 v[48:51], v[132:135], v[180:183], v[48:51]
	v_mfma_f32_16x16x32_bf16 v[40:43], v[140:143], v[180:183], v[40:43]
	v_mfma_f32_16x16x32_bf16 v[32:35], v[132:135], v[188:191], v[32:35]
	v_mfma_f32_16x16x32_bf16 v[24:27], v[140:143], v[188:191], v[24:27]
	v_mfma_f32_16x16x32_bf16 v[16:19], v[132:135], v[196:199], v[16:19]
	v_mfma_f32_16x16x32_bf16 v[8:11], v[140:143], v[196:199], v[8:11]
	v_mfma_f32_16x16x32_bf16 v[52:55], v[200:203], v[160:163], v[52:55]
	v_mfma_f32_16x16x32_bf16 v[44:47], v[208:211], v[160:163], v[44:47]
	v_mfma_f32_16x16x32_bf16 v[36:39], v[200:203], v[176:179], v[36:39]
	v_mfma_f32_16x16x32_bf16 v[28:31], v[208:211], v[176:179], v[28:31]
	v_mfma_f32_16x16x32_bf16 v[20:23], v[200:203], v[184:187], v[20:23]
	v_mfma_f32_16x16x32_bf16 v[12:15], v[208:211], v[184:187], v[12:15]
	v_mfma_f32_16x16x32_bf16 v[4:7], v[200:203], v[192:195], v[4:7]
	v_mfma_f32_16x16x32_bf16 v[0:3], v[208:211], v[192:195], v[0:3]
	v_mfma_f32_16x16x32_bf16 v[52:55], v[204:207], v[172:175], v[52:55]
	v_mfma_f32_16x16x32_bf16 v[44:47], v[212:215], v[172:175], v[44:47]
	v_mfma_f32_16x16x32_bf16 v[36:39], v[204:207], v[180:183], v[36:39]
	v_mfma_f32_16x16x32_bf16 v[28:31], v[212:215], v[180:183], v[28:31]
	v_mfma_f32_16x16x32_bf16 v[20:23], v[204:207], v[188:191], v[20:23]
	v_mfma_f32_16x16x32_bf16 v[12:15], v[212:215], v[188:191], v[12:15]
	v_mfma_f32_16x16x32_bf16 v[4:7], v[204:207], v[196:199], v[4:7]
	v_mfma_f32_16x16x32_bf16 v[0:3], v[212:215], v[196:199], v[0:3]
	s_barrier
.LBB0_666:
	s_setprio 0
	ds_read_b128 v[128:131], v169
	ds_read_b128 v[132:135], v169 offset:1024
	ds_read_b128 v[136:139], v169 offset:2048
	ds_read_b128 v[140:143], v169 offset:3072
	ds_read_b128 v[160:163], v170
	ds_read_b128 v[172:175], v170 offset:1024
	ds_read_b128 v[176:179], v170 offset:2048
	ds_read_b128 v[180:183], v170 offset:3072
	ds_read_b128 v[184:187], v170 offset:4096
	ds_read_b128 v[188:191], v170 offset:5120
	ds_read_b128 v[192:195], v170 offset:6144
	ds_read_b128 v[196:199], v170 offset:7168
	s_waitcnt lgkmcnt(11)
	ds_read_b128 v[200:203], v171
	ds_read_b128 v[204:207], v171 offset:1024
	ds_read_b128 v[208:211], v171 offset:2048
	ds_read_b128 v[212:215], v171 offset:3072
	s_add_u32 s10, s30, 0xfff80080
	s_addc_u32 s11, s31, -1
	s_cmp_eq_u32 s74, 28
	s_cselect_b32 s39, s19, s11
	s_cselect_b32 s38, s70, s10
	s_cselect_b32 s35, s17, s73
	s_cselect_b32 s34, s71, s72
	s_add_u32 s98, s34, s4
	s_addc_u32 s99, s35, s5
	s_add_u32 s100, s38, s4
	s_addc_u32 s101, s39, s5
	s_add_i32 m0, s29, 0xc000
	s_nop 0
	global_load_lds_dwordx4 v152, s[30:31]
	s_add_i32 m0, s29, 0xe000
	s_nop 0
	global_load_lds_dwordx4 v154, s[30:31]
	s_waitcnt vmcnt(8)
	s_waitcnt lgkmcnt(0)
	s_setprio 1
	s_barrier
; #define PG8_STAGE(bufoff, gbase, voff) do { _Pragma("unroll") for (int _i = 0; _i < 2; ++_i) \
;         __builtin_amdgcn_global_load_lds((const unsigned*)((const char*)(gbase) + (voff)[_i]), (PG8_LAS unsigned*)(lds + (bufoff) + ldsw + _i * 8192), 16, 0, 0); } while (0)
; #define PG8_LDA(dst, b, h) do { _Pragma("unroll") for (int m = 0; m < 4; ++m) _Pragma("unroll") for (int k = 0; k < 2; ++k) dst[m][k] = *(const PG8_LAS bf16x8*)(lds + PG8_SA(b, h) + aoff + m * 2048 + k * 1024); } while (0)
; #define PG8_LDB(dst, b, h) do { _Pragma("unroll") for (int n = 0; n < 2; ++n) _Pragma("unroll") for (int k = 0; k < 2; ++k) dst[n][k] = *(const PG8_LAS bf16x8*)(lds + PG8_SB(b, h) + boff + n * 2048 + k * 1024); } while (0)
; #define PG8_WAIT_V(n) asm volatile("s_waitcnt vmcnt(" #n ")" ::: "memory")
; #define PG8_WAIT_L(n) asm volatile("s_waitcnt lgkmcnt(" #n ")" ::: "memory")
; #define PG8_BAR __builtin_amdgcn_s_barrier()
; #define PG8_SCHED __builtin_amdgcn_sched_barrier(0)
; template <class Epi, class Sched>
; __device__ __forceinline__ void gemm_phase(PG8_LAS unsigned char* lds, const Gemm g, const Sched& S, const Epi& E) {
;     ...
;             PG8_LDB(B0, 0, 0); PG8_SCHED; PG8_LDA(At, 0, 0); PG8_STAGE(PG8_SA(1, 1), a1 + hstep, voffA);
;             PG8_WAIT_L(8); PG8_BAR; PG8_WAIT_L(0); PG8_MMA(0, 0, At, B0); PG8_BAR; PG8_SCHED;
;             PG8_LDB(B1, 0, 1); PG8_STAGE(PG8_SB(0, 0), b2, voffB);
;             PG8_BAR; PG8_WAIT_L(0); PG8_MMA(0, 1, At, B1); PG8_BAR;
;             PG8_LDA(At, 0, 1); PG8_STAGE(PG8_SA(0, 0), a2, voffA);
;             PG8_BAR; PG8_WAIT_L(0); PG8_MMA(1, 0, At, B0); PG8_BAR; PG8_SCHED;
;             PG8_STAGE(PG8_SB(0, 1), b2 + hstep, voffB);
;             PG8_WAIT_V(6); PG8_BAR; PG8_MMA(1, 1, At, B1); PG8_BAR;
;             PG8_LDB(B0, 1, 0); PG8_SCHED; PG8_LDA(At, 1, 0); PG8_STAGE(PG8_SA(0, 1), a2 + hstep, voffA);
;             PG8_WAIT_L(8); PG8_BAR; PG8_WAIT_L(0); PG8_MMA(0, 0, At, B0); PG8_BAR; PG8_SCHED;
;             PG8_LDB(B1, 1, 1); PG8_STAGE(PG8_SB(1, 0), b3, voffB);
;             PG8_BAR; PG8_WAIT_L(0); PG8_MMA(0, 1, At, B1); PG8_BAR;
;             PG8_LDA(At, 1, 1); PG8_STAGE(PG8_SA(1, 0), a3, voffA);
;             PG8_BAR; PG8_WAIT_L(0); PG8_MMA(1, 0, At, B0); PG8_BAR; PG8_SCHED;
;             PG8_STAGE(PG8_SB(1, 1), b3 + hstep, voffB);
;             PG8_WAIT_V(6); PG8_BAR; PG8_MMA(1, 1, At, B1); PG8_BAR;
	v_mfma_f32_16x16x32_bf16 v[120:123], v[128:131], v[160:163], v[120:123]
	v_mfma_f32_16x16x32_bf16 v[124:127], v[136:139], v[160:163], v[124:127]
	v_mfma_f32_16x16x32_bf16 v[112:115], v[128:131], v[176:179], v[112:115]
	v_mfma_f32_16x16x32_bf16 v[116:119], v[136:139], v[176:179], v[116:119]
	v_mfma_f32_16x16x32_bf16 v[96:99], v[128:131], v[184:187], v[96:99]
	v_mfma_f32_16x16x32_bf16 v[88:91], v[136:139], v[184:187], v[88:91]
	v_mfma_f32_16x16x32_bf16 v[80:83], v[128:131], v[192:195], v[80:83]
	v_mfma_f32_16x16x32_bf16 v[72:75], v[136:139], v[192:195], v[72:75]
	v_mfma_f32_16x16x32_bf16 v[120:123], v[132:135], v[172:175], v[120:123]
	v_mfma_f32_16x16x32_bf16 v[124:127], v[140:143], v[172:175], v[124:127]
	v_mfma_f32_16x16x32_bf16 v[112:115], v[132:135], v[180:183], v[112:115]
	v_mfma_f32_16x16x32_bf16 v[116:119], v[140:143], v[180:183], v[116:119]
	v_mfma_f32_16x16x32_bf16 v[96:99], v[132:135], v[188:191], v[96:99]
	v_mfma_f32_16x16x32_bf16 v[88:91], v[140:143], v[188:191], v[88:91]
	v_mfma_f32_16x16x32_bf16 v[80:83], v[132:135], v[196:199], v[80:83]
	v_mfma_f32_16x16x32_bf16 v[72:75], v[140:143], v[196:199], v[72:75]
	v_mfma_f32_16x16x32_bf16 v[108:111], v[200:203], v[160:163], v[108:111]
	v_mfma_f32_16x16x32_bf16 v[104:107], v[208:211], v[160:163], v[104:107]
	v_mfma_f32_16x16x32_bf16 v[100:103], v[200:203], v[176:179], v[100:103]
	v_mfma_f32_16x16x32_bf16 v[92:95], v[208:211], v[176:179], v[92:95]
	v_mfma_f32_16x16x32_bf16 v[84:87], v[200:203], v[184:187], v[84:87]
	v_mfma_f32_16x16x32_bf16 v[76:79], v[208:211], v[184:187], v[76:79]
	v_mfma_f32_16x16x32_bf16 v[68:71], v[200:203], v[192:195], v[68:71]
	v_mfma_f32_16x16x32_bf16 v[64:67], v[208:211], v[192:195], v[64:67]
	v_mfma_f32_16x16x32_bf16 v[108:111], v[204:207], v[172:175], v[108:111]
	v_mfma_f32_16x16x32_bf16 v[104:107], v[212:215], v[172:175], v[104:107]
	v_mfma_f32_16x16x32_bf16 v[100:103], v[204:207], v[180:183], v[100:103]
	v_mfma_f32_16x16x32_bf16 v[92:95], v[212:215], v[180:183], v[92:95]
	v_mfma_f32_16x16x32_bf16 v[84:87], v[204:207], v[188:191], v[84:87]
	v_mfma_f32_16x16x32_bf16 v[76:79], v[212:215], v[188:191], v[76:79]
	v_mfma_f32_16x16x32_bf16 v[68:71], v[204:207], v[196:199], v[68:71]
	v_mfma_f32_16x16x32_bf16 v[64:67], v[212:215], v[196:199], v[64:67]
	s_barrier
	s_setprio 0
	ds_read_b128 v[160:163], v170 offset:16384
	ds_read_b128 v[172:175], v170 offset:17408
	ds_read_b128 v[176:179], v170 offset:18432
	ds_read_b128 v[180:183], v170 offset:19456
	ds_read_b128 v[184:187], v170 offset:20480
	ds_read_b128 v[188:191], v170 offset:21504
	ds_read_b128 v[192:195], v170 offset:22528
	ds_read_b128 v[196:199], v170 offset:23552
	s_add_i32 s10, s66, s45
	s_mov_b32 m0, s10
	s_nop 0
	global_load_lds_dwordx4 v146, s[34:35]
	s_add_i32 m0, s10, 0x2000
	s_nop 0
	global_load_lds_dwordx4 v150, s[34:35]
	s_mov_b32 m0, s29
	s_nop 0
	global_load_lds_dwordx4 v144, s[38:39]
	s_mov_b32 m0, s46
	s_nop 0
	global_load_lds_dwordx4 v148, s[38:39]
	s_add_u32 s10, s34, 0x80000
	s_addc_u32 s11, s35, 0
	s_add_i32 s33, s67, s45
	s_mov_b32 m0, s33
	s_nop 0
	global_load_lds_dwordx4 v146, s[10:11]
	s_add_i32 m0, s33, 0x2000
	s_nop 0
	global_load_lds_dwordx4 v150, s[10:11]
	s_waitcnt vmcnt(8)
	s_waitcnt lgkmcnt(0)
	s_setprio 1
	s_barrier
	v_mfma_f32_16x16x32_bf16 v[60:63], v[128:131], v[160:163], v[60:63]
	v_mfma_f32_16x16x32_bf16 v[56:59], v[136:139], v[160:163], v[56:59]
	v_mfma_f32_16x16x32_bf16 v[48:51], v[128:131], v[176:179], v[48:51]
	v_mfma_f32_16x16x32_bf16 v[40:43], v[136:139], v[176:179], v[40:43]
	v_mfma_f32_16x16x32_bf16 v[32:35], v[128:131], v[184:187], v[32:35]
	v_mfma_f32_16x16x32_bf16 v[24:27], v[136:139], v[184:187], v[24:27]
	v_mfma_f32_16x16x32_bf16 v[16:19], v[128:131], v[192:195], v[16:19]
	v_mfma_f32_16x16x32_bf16 v[8:11], v[136:139], v[192:195], v[8:11]
	s_add_i32 s33, 0, 0x18000
	v_mfma_f32_16x16x32_bf16 v[60:63], v[132:135], v[172:175], v[60:63]
	v_mfma_f32_16x16x32_bf16 v[56:59], v[140:143], v[172:175], v[56:59]
	v_mfma_f32_16x16x32_bf16 v[48:51], v[132:135], v[180:183], v[48:51]
	v_mfma_f32_16x16x32_bf16 v[40:43], v[140:143], v[180:183], v[40:43]
	v_mfma_f32_16x16x32_bf16 v[32:35], v[132:135], v[188:191], v[32:35]
	v_mfma_f32_16x16x32_bf16 v[24:27], v[140:143], v[188:191], v[24:27]
	v_mfma_f32_16x16x32_bf16 v[16:19], v[132:135], v[196:199], v[16:19]
	v_mfma_f32_16x16x32_bf16 v[8:11], v[140:143], v[196:199], v[8:11]
	v_mfma_f32_16x16x32_bf16 v[52:55], v[200:203], v[160:163], v[52:55]
	v_mfma_f32_16x16x32_bf16 v[44:47], v[208:211], v[160:163], v[44:47]
	v_mfma_f32_16x16x32_bf16 v[36:39], v[200:203], v[176:179], v[36:39]
	v_mfma_f32_16x16x32_bf16 v[28:31], v[208:211], v[176:179], v[28:31]
	v_mfma_f32_16x16x32_bf16 v[20:23], v[200:203], v[184:187], v[20:23]
	v_mfma_f32_16x16x32_bf16 v[12:15], v[208:211], v[184:187], v[12:15]
	v_mfma_f32_16x16x32_bf16 v[4:7], v[200:203], v[192:195], v[4:7]
	v_mfma_f32_16x16x32_bf16 v[0:3], v[208:211], v[192:195], v[0:3]
	v_mfma_f32_16x16x32_bf16 v[52:55], v[204:207], v[172:175], v[52:55]
	v_mfma_f32_16x16x32_bf16 v[44:47], v[212:215], v[172:175], v[44:47]
	v_mfma_f32_16x16x32_bf16 v[36:39], v[204:207], v[180:183], v[36:39]
	v_mfma_f32_16x16x32_bf16 v[28:31], v[212:215], v[180:183], v[28:31]
	v_mfma_f32_16x16x32_bf16 v[20:23], v[204:207], v[188:191], v[20:23]
	v_mfma_f32_16x16x32_bf16 v[12:15], v[212:215], v[188:191], v[12:15]
	v_mfma_f32_16x16x32_bf16 v[4:7], v[204:207], v[196:199], v[4:7]
	v_mfma_f32_16x16x32_bf16 v[0:3], v[212:215], v[196:199], v[0:3]
	s_barrier
; #define PG8_STAGE(bufoff, gbase, voff) do { _Pragma("unroll") for (int _i = 0; _i < 2; ++_i) \
;         __builtin_amdgcn_global_load_lds((const unsigned*)((const char*)(gbase) + (voff)[_i]), (PG8_LAS unsigned*)(lds + (bufoff) + ldsw + _i * 8192), 16, 0, 0); } while (0)
; #define PG8_LDA(dst, b, h) do { _Pragma("unroll") for (int m = 0; m < 4; ++m) _Pragma("unroll") for (int k = 0; k < 2; ++k) dst[m][k] = *(const PG8_LAS bf16x8*)(lds + PG8_SA(b, h) + aoff + m * 2048 + k * 1024); } while (0)
; #define PG8_LDB(dst, b, h) do { _Pragma("unroll") for (int n = 0; n < 2; ++n) _Pragma("unroll") for (int k = 0; k < 2; ++k) dst[n][k] = *(const PG8_LAS bf16x8*)(lds + PG8_SB(b, h) + boff + n * 2048 + k * 1024); } while (0)
; #define PG8_WAIT_V(n) asm volatile("s_waitcnt vmcnt(" #n ")" ::: "memory")
; #define PG8_WAIT_L(n) asm volatile("s_waitcnt lgkmcnt(" #n ")" ::: "memory")
; #define PG8_BAR __builtin_amdgcn_s_barrier()
; #define PG8_SCHED __builtin_amdgcn_sched_barrier(0)
; template <class Epi, class Sched>
; __device__ __forceinline__ void gemm_phase(PG8_LAS unsigned char* lds, const Gemm g, const Sched& S, const Epi& E) {
;     ...
;             PG8_LDB(B0, 0, 0); PG8_SCHED; PG8_LDA(At, 0, 0); PG8_STAGE(PG8_SA(1, 1), a1 + hstep, voffA);
;             PG8_WAIT_L(8); PG8_BAR; PG8_WAIT_L(0); PG8_MMA(0, 0, At, B0); PG8_BAR; PG8_SCHED;
;             PG8_LDB(B1, 0, 1); PG8_STAGE(PG8_SB(0, 0), b2, voffB);
;             PG8_BAR; PG8_WAIT_L(0); PG8_MMA(0, 1, At, B1); PG8_BAR;
;             PG8_LDA(At, 0, 1); PG8_STAGE(PG8_SA(0, 0), a2, voffA);
;             PG8_BAR; PG8_WAIT_L(0); PG8_MMA(1, 0, At, B0); PG8_BAR; PG8_SCHED;
;             PG8_STAGE(PG8_SB(0, 1), b2 + hstep, voffB);
;             PG8_WAIT_V(6); PG8_BAR; PG8_MMA(1, 1, At, B1); PG8_BAR;
;             PG8_LDB(B0, 1, 0); PG8_SCHED; PG8_LDA(At, 1, 0); PG8_STAGE(PG8_SA(0, 1), a2 + hstep, voffA);
;             PG8_WAIT_L(8); PG8_BAR; PG8_WAIT_L(0); PG8_MMA(0, 0, At, B0); PG8_BAR; PG8_SCHED;
;             PG8_LDB(B1, 1, 1); PG8_STAGE(PG8_SB(1, 0), b3, voffB);
;             PG8_BAR; PG8_WAIT_L(0); PG8_MMA(0, 1, At, B1); PG8_BAR;
;             PG8_LDA(At, 1, 1); PG8_STAGE(PG8_SA(1, 0), a3, voffA);
;             PG8_BAR; PG8_WAIT_L(0); PG8_MMA(1, 0, At, B0); PG8_BAR; PG8_SCHED;
;             PG8_STAGE(PG8_SB(1, 1), b3 + hstep, voffB);
;             PG8_WAIT_V(6); PG8_BAR; PG8_MMA(1, 1, At, B1); PG8_BAR;
	s_setprio 0
	ds_read_b128 v[128:131], v169 offset:32768
	ds_read_b128 v[132:135], v169 offset:33792
	ds_read_b128 v[136:139], v169 offset:34816
	ds_read_b128 v[140:143], v169 offset:35840
	ds_read_b128 v[160:163], v170 offset:32768
	ds_read_b128 v[172:175], v170 offset:33792
	ds_read_b128 v[176:179], v170 offset:34816
	ds_read_b128 v[180:183], v170 offset:35840
	ds_read_b128 v[184:187], v170 offset:36864
	ds_read_b128 v[188:191], v170 offset:37888
	ds_read_b128 v[192:195], v170 offset:38912
	ds_read_b128 v[196:199], v170 offset:39936
	s_waitcnt lgkmcnt(11)
	ds_read_b128 v[200:203], v171 offset:32768
	ds_read_b128 v[204:207], v171 offset:33792
	ds_read_b128 v[208:211], v171 offset:34816
	ds_read_b128 v[212:215], v171 offset:35840
	s_add_u32 s10, s38, 0x80000
	s_addc_u32 s11, s39, 0
	s_mov_b32 m0, s47
	s_nop 0
	global_load_lds_dwordx4 v144, s[10:11]
	s_mov_b32 m0, s48
	s_nop 0
	global_load_lds_dwordx4 v148, s[10:11]
	s_waitcnt vmcnt(8)
	s_waitcnt lgkmcnt(0)
	s_setprio 1
	s_barrier
	v_mfma_f32_16x16x32_bf16 v[120:123], v[128:131], v[160:163], v[120:123]
	v_mfma_f32_16x16x32_bf16 v[124:127], v[136:139], v[160:163], v[124:127]
	v_mfma_f32_16x16x32_bf16 v[112:115], v[128:131], v[176:179], v[112:115]
	v_mfma_f32_16x16x32_bf16 v[116:119], v[136:139], v[176:179], v[116:119]
	v_mfma_f32_16x16x32_bf16 v[96:99], v[128:131], v[184:187], v[96:99]
	v_mfma_f32_16x16x32_bf16 v[88:91], v[136:139], v[184:187], v[88:91]
	v_mfma_f32_16x16x32_bf16 v[80:83], v[128:131], v[192:195], v[80:83]
	v_mfma_f32_16x16x32_bf16 v[72:75], v[136:139], v[192:195], v[72:75]
	v_mfma_f32_16x16x32_bf16 v[120:123], v[132:135], v[172:175], v[120:123]
	v_mfma_f32_16x16x32_bf16 v[124:127], v[140:143], v[172:175], v[124:127]
	v_mfma_f32_16x16x32_bf16 v[112:115], v[132:135], v[180:183], v[112:115]
	v_mfma_f32_16x16x32_bf16 v[116:119], v[140:143], v[180:183], v[116:119]
	v_mfma_f32_16x16x32_bf16 v[96:99], v[132:135], v[188:191], v[96:99]
	v_mfma_f32_16x16x32_bf16 v[88:91], v[140:143], v[188:191], v[88:91]
	v_mfma_f32_16x16x32_bf16 v[80:83], v[132:135], v[196:199], v[80:83]
	v_mfma_f32_16x16x32_bf16 v[72:75], v[140:143], v[196:199], v[72:75]
	v_mfma_f32_16x16x32_bf16 v[108:111], v[200:203], v[160:163], v[108:111]
	v_mfma_f32_16x16x32_bf16 v[104:107], v[208:211], v[160:163], v[104:107]
	v_mfma_f32_16x16x32_bf16 v[100:103], v[200:203], v[176:179], v[100:103]
	v_mfma_f32_16x16x32_bf16 v[92:95], v[208:211], v[176:179], v[92:95]
	v_mfma_f32_16x16x32_bf16 v[84:87], v[200:203], v[184:187], v[84:87]
	v_mfma_f32_16x16x32_bf16 v[76:79], v[208:211], v[184:187], v[76:79]
	v_mfma_f32_16x16x32_bf16 v[68:71], v[200:203], v[192:195], v[68:71]
	v_mfma_f32_16x16x32_bf16 v[64:67], v[208:211], v[192:195], v[64:67]
	v_mfma_f32_16x16x32_bf16 v[108:111], v[204:207], v[172:175], v[108:111]
	v_mfma_f32_16x16x32_bf16 v[104:107], v[212:215], v[172:175], v[104:107]
	v_mfma_f32_16x16x32_bf16 v[100:103], v[204:207], v[180:183], v[100:103]
	v_mfma_f32_16x16x32_bf16 v[92:95], v[212:215], v[180:183], v[92:95]
	v_mfma_f32_16x16x32_bf16 v[84:87], v[204:207], v[188:191], v[84:87]
	v_mfma_f32_16x16x32_bf16 v[76:79], v[212:215], v[188:191], v[76:79]
	v_mfma_f32_16x16x32_bf16 v[68:71], v[204:207], v[196:199], v[68:71]
	v_mfma_f32_16x16x32_bf16 v[64:67], v[212:215], v[196:199], v[64:67]
	s_barrier
	s_setprio 0
	ds_read_b128 v[160:163], v170 offset:49152
	ds_read_b128 v[172:175], v170 offset:50176
	ds_read_b128 v[176:179], v170 offset:51200
	ds_read_b128 v[180:183], v170 offset:52224
	ds_read_b128 v[184:187], v170 offset:53248
	ds_read_b128 v[188:191], v170 offset:54272
	ds_read_b128 v[192:195], v170 offset:55296
	ds_read_b128 v[196:199], v170 offset:56320
	s_add_i32 s38, 0, 0x1c000
	s_add_i32 s10, s33, s45
	s_mov_b32 m0, s10
	s_nop 0
	global_load_lds_dwordx4 v146, s[98:99]
	s_add_i32 m0, s10, 0x2000
	s_nop 0
	global_load_lds_dwordx4 v150, s[98:99]
	s_mov_b32 m0, s50
	s_nop 0
	global_load_lds_dwordx4 v144, s[100:101]
	s_mov_b32 m0, s51
	s_nop 0
	global_load_lds_dwordx4 v148, s[100:101]
	s_add_u32 s10, s34, 0x80080
	s_addc_u32 s11, s35, 0
	s_add_i32 s33, s38, s45
	s_mov_b32 m0, s33
	s_nop 0
	global_load_lds_dwordx4 v146, s[10:11]
	s_add_i32 m0, s33, 0x2000
	s_nop 0
	global_load_lds_dwordx4 v150, s[10:11]
	s_waitcnt vmcnt(8)
	s_waitcnt lgkmcnt(0)
	s_setprio 1
	s_barrier
	v_mfma_f32_16x16x32_bf16 v[60:63], v[128:131], v[160:163], v[60:63]
	v_mfma_f32_16x16x32_bf16 v[56:59], v[136:139], v[160:163], v[56:59]
	v_mfma_f32_16x16x32_bf16 v[48:51], v[128:131], v[176:179], v[48:51]
	v_mfma_f32_16x16x32_bf16 v[40:43], v[136:139], v[176:179], v[40:43]
	v_mfma_f32_16x16x32_bf16 v[32:35], v[128:131], v[184:187], v[32:35]
	v_mfma_f32_16x16x32_bf16 v[24:27], v[136:139], v[184:187], v[24:27]
	v_mfma_f32_16x16x32_bf16 v[16:19], v[128:131], v[192:195], v[16:19]
	v_mfma_f32_16x16x32_bf16 v[8:11], v[136:139], v[192:195], v[8:11]
	s_add_i32 s74, s74, 2
	s_add_u32 s30, s30, 0x100
	s_addc_u32 s31, s31, 0
	s_add_u32 s72, s72, 0x100
	s_addc_u32 s73, s73, 0
	s_cmp_gt_u32 s74, 29
	v_mfma_f32_16x16x32_bf16 v[60:63], v[132:135], v[172:175], v[60:63]
	v_mfma_f32_16x16x32_bf16 v[56:59], v[140:143], v[172:175], v[56:59]
	v_mfma_f32_16x16x32_bf16 v[48:51], v[132:135], v[180:183], v[48:51]
	v_mfma_f32_16x16x32_bf16 v[40:43], v[140:143], v[180:183], v[40:43]
	v_mfma_f32_16x16x32_bf16 v[32:35], v[132:135], v[188:191], v[32:35]
	v_mfma_f32_16x16x32_bf16 v[24:27], v[140:143], v[188:191], v[24:27]
	v_mfma_f32_16x16x32_bf16 v[16:19], v[132:135], v[196:199], v[16:19]
	v_mfma_f32_16x16x32_bf16 v[8:11], v[140:143], v[196:199], v[8:11]
	v_mfma_f32_16x16x32_bf16 v[52:55], v[200:203], v[160:163], v[52:55]
	v_mfma_f32_16x16x32_bf16 v[44:47], v[208:211], v[160:163], v[44:47]
	v_mfma_f32_16x16x32_bf16 v[36:39], v[200:203], v[176:179], v[36:39]
	v_mfma_f32_16x16x32_bf16 v[28:31], v[208:211], v[176:179], v[28:31]
	v_mfma_f32_16x16x32_bf16 v[20:23], v[200:203], v[184:187], v[20:23]
	v_mfma_f32_16x16x32_bf16 v[12:15], v[208:211], v[184:187], v[12:15]
	v_mfma_f32_16x16x32_bf16 v[4:7], v[200:203], v[192:195], v[4:7]
	v_mfma_f32_16x16x32_bf16 v[0:3], v[208:211], v[192:195], v[0:3]
	v_mfma_f32_16x16x32_bf16 v[52:55], v[204:207], v[172:175], v[52:55]
	v_mfma_f32_16x16x32_bf16 v[44:47], v[212:215], v[172:175], v[44:47]
	v_mfma_f32_16x16x32_bf16 v[36:39], v[204:207], v[180:183], v[36:39]
	v_mfma_f32_16x16x32_bf16 v[28:31], v[212:215], v[180:183], v[28:31]
	v_mfma_f32_16x16x32_bf16 v[20:23], v[204:207], v[188:191], v[20:23]
	v_mfma_f32_16x16x32_bf16 v[12:15], v[212:215], v[188:191], v[12:15]
	v_mfma_f32_16x16x32_bf16 v[4:7], v[204:207], v[196:199], v[4:7]
	v_mfma_f32_16x16x32_bf16 v[0:3], v[212:215], v[196:199], v[0:3]
	s_barrier
;     __device__ __forceinline__ void operator()(const AccT& acc, const pg8::Unit& u, int wr, int wc, int fr, int fq) const {
;         const int row0 = u.pm * 256 + wr * 64 + fr, col0 = u.pn * 256 + wc * 32 + 8 * fq;
;         const float* ga = mod + (u.pm >= 64 ? 12288 : 0) + 2 * 2048;
;         f32x4 gv[2][2];
; #pragma unroll
;         for (int bj = 0; bj < 2; ++bj)
; #pragma unroll
;             for (int n = 0; n < 2; ++n) gv[bj][n] = *(const f32x4*)(ga + col0 + bj * 128 + n * 4);
; #pragma unroll
;         for (int ai = 0; ai < 2; ++ai) {
;             f32x4 xa[4][2], xb[4][2];
; #pragma unroll
;             for (int m = 0; m < 4; ++m) { const size_t off = (size_t)(row0 + ai * 128 + m * 16) * D + col0;
; #pragma unroll
;                 for (int bj = 0; bj < 2; ++bj) { xa[m][bj] = *(const f32x4*)(x + off + bj * 128); xb[m][bj] = *(const f32x4*)(x + off + bj * 128 + 4); } }
; #pragma unroll
;             for (int m = 0; m < 4; ++m) { const size_t off = (size_t)(row0 + ai * 128 + m * 16) * D + col0;
; #pragma unroll
;                 for (int bj = 0; bj < 2; ++bj) {
;                     const f32x4 a = ALPHA * xa[m][bj] + gv[bj][0] * acc[ai][bj][m][0], b = ALPHA * xb[m][bj] + gv[bj][1] * acc[ai][bj][m][1];
;                     u32x4 w; w.x = pk_h2(a[0], a[1]); w.y = pk_h2(a[2], a[3]); w.z = pk_h2(b[0], b[1]); w.w = pk_h2(b[2], b[3]);
;                     *(u32x4*)(U1 + off + bj * 128) = w; } }
	s_cbranch_scc0 .LBB0_666
	s_setprio 0
	v_lshl_or_b32 v160, s69, 8, v168
	s_cmp_gt_i32 s28, 63
	v_ashrrev_i32_e32 v161, 31, v160
	v_lshl_add_u32 v164, s28, 8, v166
	s_cselect_b32 s10, 0xc000, 0
	v_lshlrev_b64 v[128:129], 2, v[160:161]
	v_ashrrev_i32_e32 v165, 31, v164
	s_add_u32 s10, s58, s10
	v_lshl_add_u64 v[162:163], s[36:37], 0, v[128:129]
	v_lshlrev_b64 v[130:131], 13, v[164:165]
	v_or_b32_e32 v220, 16, v164
	s_addc_u32 s11, s59, 0
	v_lshl_add_u64 v[130:131], v[162:163], 0, v[130:131]
	v_ashrrev_i32_e32 v221, 31, v220
	global_load_dwordx4 v[172:175], v[130:131], off offset:16
	global_load_dwordx4 v[176:179], v[130:131], off
	global_load_dwordx4 v[180:183], v[130:131], off offset:528
	global_load_dwordx4 v[184:187], v[130:131], off offset:512
	v_lshlrev_b64 v[130:131], 13, v[220:221]
	v_lshl_add_u64 v[128:129], s[10:11], 0, v[128:129]
	v_lshl_add_u64 v[200:201], v[162:163], 0, v[130:131]
	v_lshl_add_u64 v[130:131], v[128:129], 0, s[6:7]
	global_load_dwordx4 v[188:191], v[200:201], off offset:16
	global_load_dwordx4 v[192:195], v[200:201], off
	global_load_dwordx4 v[136:139], v[130:131], off offset:16
	global_load_dwordx4 v[132:135], v[130:131], off offset:512
	v_add_co_u32_e32 v128, vcc, s68, v128
	v_or_b32_e32 v236, 32, v164
	s_nop 0
	v_addc_co_u32_e32 v129, vcc, 0, v129, vcc
	global_load_dwordx4 v[140:143], v[128:129], off
	s_nop 0
	global_load_dwordx4 v[128:131], v[130:131], off offset:528
	s_nop 0
	global_load_dwordx4 v[196:199], v[200:201], off offset:512
	s_nop 0
	global_load_dwordx4 v[200:203], v[200:201], off offset:528
	v_ashrrev_i32_e32 v237, 31, v236
	v_lshlrev_b64 v[204:205], 13, v[236:237]
	v_lshl_add_u64 v[216:217], v[162:163], 0, v[204:205]
	global_load_dwordx4 v[204:207], v[216:217], off
	global_load_dwordx4 v[208:211], v[216:217], off offset:16
	global_load_dwordx4 v[212:215], v[216:217], off offset:528
	s_nop 0
	global_load_dwordx4 v[216:219], v[216:217], off offset:512
	v_or_b32_e32 v238, 48, v164
	v_ashrrev_i32_e32 v239, 31, v238
	v_lshlrev_b64 v[222:223], 12, v[164:165]
	v_lshlrev_b64 v[224:225], 13, v[238:239]
	v_lshlrev_b64 v[160:161], 1, v[160:161]
	v_lshl_add_u64 v[222:223], s[0:1], 0, v[222:223]
	v_lshl_add_u64 v[232:233], v[162:163], 0, v[224:225]
	v_lshlrev_b64 v[240:241], 12, v[220:221]
	v_lshl_add_u64 v[244:245], v[222:223], 0, v[160:161]
	global_load_dwordx4 v[220:223], v[232:233], off offset:16
	global_load_dwordx4 v[224:227], v[232:233], off
	global_load_dwordx4 v[228:231], v[232:233], off offset:528
	s_nop 0
	global_load_dwordx4 v[232:235], v[232:233], off offset:512
	s_and_b64 vcc, exec, s[2:3]
	s_mov_b32 s69, s16
	s_mov_b32 s28, s18
	s_mov_b64 s[34:35], s[26:27]
	s_mov_b64 s[30:31], s[20:21]
	s_waitcnt vmcnt(0)
	v_pk_mul_f32 v[174:175], v[174:175], s[8:9] op_sel_hi:[1,0]
	v_pk_mul_f32 v[178:179], v[178:179], s[8:9] op_sel_hi:[1,0]
	v_pk_mul_f32 v[176:177], v[176:177], s[8:9] op_sel_hi:[1,0]
	v_pk_mul_f32 v[172:173], v[172:173], s[8:9] op_sel_hi:[1,0]
	v_pk_mul_f32 v[186:187], v[186:187], s[8:9] op_sel_hi:[1,0]
	v_pk_mul_f32 v[184:185], v[184:185], s[8:9] op_sel_hi:[1,0]
	v_pk_mul_f32 v[182:183], v[182:183], s[8:9] op_sel_hi:[1,0]
	v_pk_mul_f32 v[180:181], v[180:181], s[8:9] op_sel_hi:[1,0]
	v_pk_mul_f32 v[194:195], v[194:195], s[8:9] op_sel_hi:[1,0]
	v_pk_fma_f32 v[126:127], v[126:127], v[138:139], v[174:175]
	v_pk_fma_f32 v[124:125], v[124:125], v[136:137], v[172:173]
	v_pk_mul_f32 v[192:193], v[192:193], s[8:9] op_sel_hi:[1,0]
	v_pk_mul_f32 v[190:191], v[190:191], s[8:9] op_sel_hi:[1,0]
	v_pk_fma_f32 v[122:123], v[122:123], v[142:143], v[178:179]
	v_pk_fma_f32 v[120:121], v[120:121], v[140:141], v[176:177]
	v_pk_mul_f32 v[188:189], v[188:189], s[8:9] op_sel_hi:[1,0]
	v_pk_fma_f32 v[172:173], v[110:111], v[134:135], v[186:187]
	v_pk_fma_f32 v[110:111], v[108:109], v[132:133], v[184:185]
	v_cvt_pk_f16_f32 v108, v124, v125
	v_cvt_pk_f16_f32 v109, v126, v127
	v_pk_fma_f32 v[124:125], v[106:107], v[130:131], v[182:183]
	v_pk_fma_f32 v[104:105], v[104:105], v[128:129], v[180:181]
	v_cvt_pk_f16_f32 v106, v120, v121
	v_cvt_pk_f16_f32 v107, v122, v123
	v_pk_fma_f32 v[118:119], v[118:119], v[138:139], v[190:191]
	v_pk_fma_f32 v[116:117], v[116:117], v[136:137], v[188:189]
	v_cvt_pk_f16_f32 v110, v110, v111
	v_cvt_pk_f16_f32 v111, v172, v173
	v_pk_fma_f32 v[114:115], v[114:115], v[142:143], v[194:195]
	v_pk_fma_f32 v[126:127], v[112:113], v[140:141], v[192:193]
	v_cvt_pk_f16_f32 v112, v104, v105
	v_cvt_pk_f16_f32 v113, v124, v125
	global_store_dwordx4 v[244:245], v[106:109], off
	global_store_dwordx4 v[244:245], v[110:113], off offset:256
	v_cvt_pk_f16_f32 v104, v126, v127
	v_lshl_add_u64 v[108:109], s[0:1], 0, v[240:241]
	v_cvt_pk_f16_f32 v105, v114, v115
	v_cvt_pk_f16_f32 v106, v116, v117
	v_cvt_pk_f16_f32 v107, v118, v119
	v_lshl_add_u64 v[108:109], v[108:109], 0, v[160:161]
	global_store_dwordx4 v[108:109], v[104:107], off
	v_add_u32_e32 v172, 0x80, v164
	v_ashrrev_i32_e32 v173, 31, v172
	v_pk_mul_f32 v[104:105], v[198:199], s[8:9] op_sel_hi:[1,0]
	v_pk_mul_f32 v[106:107], v[196:197], s[8:9] op_sel_hi:[1,0]
	v_pk_fma_f32 v[102:103], v[102:103], v[134:135], v[104:105]
	v_pk_fma_f32 v[100:101], v[100:101], v[132:133], v[106:107]
	v_pk_mul_f32 v[104:105], v[202:203], s[8:9] op_sel_hi:[1,0]
	v_pk_mul_f32 v[106:107], v[200:201], s[8:9] op_sel_hi:[1,0]
	v_pk_fma_f32 v[104:105], v[94:95], v[130:131], v[104:105]
	v_pk_fma_f32 v[94:95], v[92:93], v[128:129], v[106:107]
	v_cvt_pk_f16_f32 v92, v100, v101
	v_cvt_pk_f16_f32 v93, v102, v103
	v_cvt_pk_f16_f32 v94, v94, v95
	v_cvt_pk_f16_f32 v95, v104, v105
	global_store_dwordx4 v[108:109], v[92:95], off offset:256
	v_pk_mul_f32 v[100:101], v[204:205], s[8:9] op_sel_hi:[1,0]
;     __device__ __forceinline__ void operator()(const AccT& acc, const pg8::Unit& u, int wr, int wc, int fr, int fq) const {
;     ...
;         for (int ai = 0; ai < 2; ++ai) {
;             f32x4 xa[4][2], xb[4][2];
; #pragma unroll
;             for (int m = 0; m < 4; ++m) { const size_t off = (size_t)(row0 + ai * 128 + m * 16) * D + col0;
; #pragma unroll
;                 for (int bj = 0; bj < 2; ++bj) { xa[m][bj] = *(const f32x4*)(x + off + bj * 128); xb[m][bj] = *(const f32x4*)(x + off + bj * 128 + 4); } }
; #pragma unroll
;             for (int m = 0; m < 4; ++m) { const size_t off = (size_t)(row0 + ai * 128 + m * 16) * D + col0;
; #pragma unroll
;                 for (int bj = 0; bj < 2; ++bj) {
;                     const f32x4 a = ALPHA * xa[m][bj] + gv[bj][0] * acc[ai][bj][m][0], b = ALPHA * xb[m][bj] + gv[bj][1] * acc[ai][bj][m][1];
;                     u32x4 w; w.x = pk_h2(a[0], a[1]); w.y = pk_h2(a[2], a[3]); w.z = pk_h2(b[0], b[1]); w.w = pk_h2(b[2], b[3]);
;                     *(u32x4*)(U1 + off + bj * 128) = w; } }
	v_add_u32_e32 v174, 0x90, v164
	v_pk_mul_f32 v[94:95], v[206:207], s[8:9] op_sel_hi:[1,0]
	v_lshlrev_b64 v[92:93], 12, v[236:237]
	v_pk_fma_f32 v[94:95], v[98:99], v[142:143], v[94:95]
	v_pk_fma_f32 v[96:97], v[96:97], v[140:141], v[100:101]
	v_pk_mul_f32 v[98:99], v[210:211], s[8:9] op_sel_hi:[1,0]
	v_pk_mul_f32 v[100:101], v[208:209], s[8:9] op_sel_hi:[1,0]
	v_pk_fma_f32 v[98:99], v[90:91], v[138:139], v[98:99]
	v_pk_fma_f32 v[90:91], v[88:89], v[136:137], v[100:101]
	v_lshl_add_u64 v[92:93], s[0:1], 0, v[92:93]
	v_cvt_pk_f16_f32 v88, v96, v97
	v_cvt_pk_f16_f32 v89, v94, v95
	v_cvt_pk_f16_f32 v90, v90, v91
	v_cvt_pk_f16_f32 v91, v98, v99
	v_lshl_add_u64 v[92:93], v[92:93], 0, v[160:161]
	global_store_dwordx4 v[92:93], v[88:91], off
	v_ashrrev_i32_e32 v175, 31, v174
	v_add_u32_e32 v176, 0xa0, v164
	v_pk_mul_f32 v[88:89], v[218:219], s[8:9] op_sel_hi:[1,0]
	v_pk_mul_f32 v[90:91], v[216:217], s[8:9] op_sel_hi:[1,0]
	v_pk_fma_f32 v[86:87], v[86:87], v[134:135], v[88:89]
	v_pk_fma_f32 v[84:85], v[84:85], v[132:133], v[90:91]
	v_pk_mul_f32 v[88:89], v[214:215], s[8:9] op_sel_hi:[1,0]
	v_pk_mul_f32 v[90:91], v[212:213], s[8:9] op_sel_hi:[1,0]
	v_pk_fma_f32 v[88:89], v[78:79], v[130:131], v[88:89]
	v_pk_fma_f32 v[78:79], v[76:77], v[128:129], v[90:91]
	v_cvt_pk_f16_f32 v76, v84, v85
	v_cvt_pk_f16_f32 v77, v86, v87
	v_cvt_pk_f16_f32 v78, v78, v79
	v_cvt_pk_f16_f32 v79, v88, v89
	global_store_dwordx4 v[92:93], v[76:79], off offset:256
	v_pk_mul_f32 v[84:85], v[224:225], s[8:9] op_sel_hi:[1,0]
	v_ashrrev_i32_e32 v177, 31, v176
	v_pk_mul_f32 v[78:79], v[226:227], s[8:9] op_sel_hi:[1,0]
	v_lshlrev_b64 v[76:77], 12, v[238:239]
	v_pk_fma_f32 v[78:79], v[82:83], v[142:143], v[78:79]
	v_pk_fma_f32 v[80:81], v[80:81], v[140:141], v[84:85]
	v_pk_mul_f32 v[82:83], v[222:223], s[8:9] op_sel_hi:[1,0]
	v_pk_mul_f32 v[84:85], v[220:221], s[8:9] op_sel_hi:[1,0]
	v_pk_fma_f32 v[82:83], v[74:75], v[138:139], v[82:83]
	v_pk_fma_f32 v[74:75], v[72:73], v[136:137], v[84:85]
	v_lshl_add_u64 v[76:77], s[0:1], 0, v[76:77]
	v_cvt_pk_f16_f32 v72, v80, v81
	v_cvt_pk_f16_f32 v73, v78, v79
	v_cvt_pk_f16_f32 v74, v74, v75
	v_cvt_pk_f16_f32 v75, v82, v83
	v_lshl_add_u64 v[76:77], v[76:77], 0, v[160:161]
	global_store_dwordx4 v[76:77], v[72:75], off
	v_lshlrev_b64 v[80:81], 13, v[174:175]
	v_lshl_add_u64 v[92:93], v[162:163], 0, v[80:81]
	v_pk_mul_f32 v[72:73], v[234:235], s[8:9] op_sel_hi:[1,0]
	v_pk_mul_f32 v[74:75], v[232:233], s[8:9] op_sel_hi:[1,0]
	v_pk_fma_f32 v[70:71], v[70:71], v[134:135], v[72:73]
	v_pk_fma_f32 v[68:69], v[68:69], v[132:133], v[74:75]
	v_pk_mul_f32 v[72:73], v[230:231], s[8:9] op_sel_hi:[1,0]
	v_pk_mul_f32 v[74:75], v[228:229], s[8:9] op_sel_hi:[1,0]
	v_pk_fma_f32 v[72:73], v[66:67], v[130:131], v[72:73]
	v_pk_fma_f32 v[66:67], v[64:65], v[128:129], v[74:75]
	v_cvt_pk_f16_f32 v64, v68, v69
	v_cvt_pk_f16_f32 v65, v70, v71
	v_cvt_pk_f16_f32 v66, v66, v67
	v_cvt_pk_f16_f32 v67, v72, v73
	global_store_dwordx4 v[76:77], v[64:67], off offset:256
	v_lshlrev_b64 v[96:97], 13, v[176:177]
	v_lshl_add_u64 v[108:109], v[162:163], 0, v[96:97]
	v_lshlrev_b64 v[64:65], 13, v[172:173]
	v_lshl_add_u64 v[76:77], v[162:163], 0, v[64:65]
	global_load_dwordx4 v[64:67], v[76:77], off
	global_load_dwordx4 v[68:71], v[76:77], off offset:16
	global_load_dwordx4 v[72:75], v[76:77], off offset:512
	s_nop 0
	global_load_dwordx4 v[76:79], v[76:77], off offset:528
	s_nop 0
	global_load_dwordx4 v[80:83], v[92:93], off
	global_load_dwordx4 v[84:87], v[92:93], off offset:16
	global_load_dwordx4 v[88:91], v[92:93], off offset:512
	s_nop 0
	global_load_dwordx4 v[92:95], v[92:93], off offset:528
	s_nop 0
	global_load_dwordx4 v[96:99], v[108:109], off
	global_load_dwordx4 v[100:103], v[108:109], off offset:16
	global_load_dwordx4 v[104:107], v[108:109], off offset:528
	s_nop 0
	global_load_dwordx4 v[108:111], v[108:109], off offset:512
	v_add_u32_e32 v164, 0xb0, v164
	v_ashrrev_i32_e32 v165, 31, v164
	v_lshlrev_b64 v[112:113], 13, v[164:165]
	v_lshl_add_u64 v[124:125], v[162:163], 0, v[112:113]
	global_load_dwordx4 v[112:115], v[124:125], off offset:16
	global_load_dwordx4 v[116:119], v[124:125], off
	global_load_dwordx4 v[120:123], v[124:125], off offset:528
	s_nop 0
	global_load_dwordx4 v[124:127], v[124:125], off offset:512
	v_lshlrev_b64 v[162:163], 12, v[172:173]
	s_waitcnt vmcnt(0)
; #define PG8_WAIT_V(n) asm volatile("s_waitcnt vmcnt(" #n ")" ::: "memory")
; #define PG8_BAR __builtin_amdgcn_s_barrier()
; template <class Epi, class Sched>
; __device__ __forceinline__ void gemm_phase(PG8_LAS unsigned char* lds, const Gemm g, const Sched& S, const Epi& E) {
;     ...
;         if (!has_next) break;
; #pragma unroll
;         for (int a = 0; a < 2; ++a)
; #pragma unroll
;             for (int b = 0; b < 2; ++b)
; #pragma unroll
;                 for (int m = 0; m < 4; ++m)
; #pragma unroll
;                     for (int n = 0; n < 2; ++n) acc[a][b][m][n] = (f32x4){0.f, 0.f, 0.f, 0.f};
;         cur = nxt; cA = nA; cB = nB; ++ui;
;     }
;     PG8_WAIT_V(0);
;     if (wr == 0) PG8_BAR;
;     PG8_BAR;
;     __device__ __forceinline__ void operator()(const AccT& acc, const pg8::Unit& u, int wr, int wc, int fr, int fq) const {
;     ...
;             for (int m = 0; m < 4; ++m) { const size_t off = (size_t)(row0 + ai * 128 + m * 16) * D + col0;
; #pragma unroll
;                 for (int bj = 0; bj < 2; ++bj) {
;                     const f32x4 a = ALPHA * xa[m][bj] + gv[bj][0] * acc[ai][bj][m][0], b = ALPHA * xb[m][bj] + gv[bj][1] * acc[ai][bj][m][1];
;                     u32x4 w; w.x = pk_h2(a[0], a[1]); w.y = pk_h2(a[2], a[3]); w.z = pk_h2(b[0], b[1]); w.w = pk_h2(b[2], b[3]);
;                     *(u32x4*)(U1 + off + bj * 128) = w; } }
	v_pk_mul_f32 v[66:67], v[66:67], s[8:9] op_sel_hi:[1,0]
	v_pk_mul_f32 v[64:65], v[64:65], s[8:9] op_sel_hi:[1,0]
	v_pk_fma_f32 v[62:63], v[62:63], v[142:143], v[66:67]
	v_pk_fma_f32 v[60:61], v[60:61], v[140:141], v[64:65]
	v_pk_mul_f32 v[64:65], v[70:71], s[8:9] op_sel_hi:[1,0]
	v_pk_mul_f32 v[66:67], v[68:69], s[8:9] op_sel_hi:[1,0]
	v_pk_fma_f32 v[64:65], v[58:59], v[138:139], v[64:65]
	v_pk_fma_f32 v[58:59], v[56:57], v[136:137], v[66:67]
	v_cvt_pk_f16_f32 v56, v60, v61
	v_lshl_add_u64 v[60:61], s[0:1], 0, v[162:163]
	v_cvt_pk_f16_f32 v57, v62, v63
	v_cvt_pk_f16_f32 v58, v58, v59
	v_cvt_pk_f16_f32 v59, v64, v65
	v_lshl_add_u64 v[60:61], v[60:61], 0, v[160:161]
	global_store_dwordx4 v[60:61], v[56:59], off
	s_nop 1
	v_pk_mul_f32 v[56:57], v[74:75], s[8:9] op_sel_hi:[1,0]
	v_pk_mul_f32 v[58:59], v[72:73], s[8:9] op_sel_hi:[1,0]
	v_pk_fma_f32 v[54:55], v[54:55], v[134:135], v[56:57]
	v_pk_fma_f32 v[52:53], v[52:53], v[132:133], v[58:59]
	v_pk_mul_f32 v[56:57], v[78:79], s[8:9] op_sel_hi:[1,0]
	v_pk_mul_f32 v[58:59], v[76:77], s[8:9] op_sel_hi:[1,0]
	v_pk_fma_f32 v[56:57], v[46:47], v[130:131], v[56:57]
	v_pk_fma_f32 v[46:47], v[44:45], v[128:129], v[58:59]
	v_cvt_pk_f16_f32 v44, v52, v53
	v_cvt_pk_f16_f32 v45, v54, v55
	v_cvt_pk_f16_f32 v46, v46, v47
	v_cvt_pk_f16_f32 v47, v56, v57
	global_store_dwordx4 v[60:61], v[44:47], off offset:256
	v_pk_mul_f32 v[52:53], v[80:81], s[8:9] op_sel_hi:[1,0]
	s_nop 0
	v_pk_mul_f32 v[46:47], v[82:83], s[8:9] op_sel_hi:[1,0]
	v_lshlrev_b64 v[44:45], 12, v[174:175]
	v_pk_fma_f32 v[46:47], v[50:51], v[142:143], v[46:47]
	v_pk_fma_f32 v[48:49], v[48:49], v[140:141], v[52:53]
	v_pk_mul_f32 v[50:51], v[86:87], s[8:9] op_sel_hi:[1,0]
	v_pk_mul_f32 v[52:53], v[84:85], s[8:9] op_sel_hi:[1,0]
	v_pk_fma_f32 v[50:51], v[42:43], v[138:139], v[50:51]
	v_pk_fma_f32 v[42:43], v[40:41], v[136:137], v[52:53]
	v_lshl_add_u64 v[44:45], s[0:1], 0, v[44:45]
	v_cvt_pk_f16_f32 v40, v48, v49
	v_cvt_pk_f16_f32 v41, v46, v47
	v_cvt_pk_f16_f32 v42, v42, v43
	v_cvt_pk_f16_f32 v43, v50, v51
	v_lshl_add_u64 v[44:45], v[44:45], 0, v[160:161]
	global_store_dwordx4 v[44:45], v[40:43], off
	s_nop 1
	v_pk_mul_f32 v[40:41], v[90:91], s[8:9] op_sel_hi:[1,0]
	v_pk_mul_f32 v[42:43], v[88:89], s[8:9] op_sel_hi:[1,0]
	v_pk_fma_f32 v[38:39], v[38:39], v[134:135], v[40:41]
	v_pk_fma_f32 v[36:37], v[36:37], v[132:133], v[42:43]
	v_pk_mul_f32 v[40:41], v[94:95], s[8:9] op_sel_hi:[1,0]
	v_pk_mul_f32 v[42:43], v[92:93], s[8:9] op_sel_hi:[1,0]
	v_pk_fma_f32 v[40:41], v[30:31], v[130:131], v[40:41]
	v_pk_fma_f32 v[30:31], v[28:29], v[128:129], v[42:43]
	v_cvt_pk_f16_f32 v28, v36, v37
	v_cvt_pk_f16_f32 v29, v38, v39
	v_cvt_pk_f16_f32 v30, v30, v31
	v_cvt_pk_f16_f32 v31, v40, v41
	global_store_dwordx4 v[44:45], v[28:31], off offset:256
	v_pk_mul_f32 v[36:37], v[96:97], s[8:9] op_sel_hi:[1,0]
	s_nop 0
	v_pk_mul_f32 v[30:31], v[98:99], s[8:9] op_sel_hi:[1,0]
	v_lshlrev_b64 v[28:29], 12, v[176:177]
	v_pk_fma_f32 v[30:31], v[34:35], v[142:143], v[30:31]
	v_pk_fma_f32 v[32:33], v[32:33], v[140:141], v[36:37]
	v_pk_mul_f32 v[34:35], v[102:103], s[8:9] op_sel_hi:[1,0]
	v_pk_mul_f32 v[36:37], v[100:101], s[8:9] op_sel_hi:[1,0]
	v_pk_fma_f32 v[34:35], v[26:27], v[138:139], v[34:35]
	v_pk_fma_f32 v[26:27], v[24:25], v[136:137], v[36:37]
	v_lshl_add_u64 v[28:29], s[0:1], 0, v[28:29]
	v_cvt_pk_f16_f32 v24, v32, v33
	v_cvt_pk_f16_f32 v25, v30, v31
	v_cvt_pk_f16_f32 v26, v26, v27
	v_cvt_pk_f16_f32 v27, v34, v35
	v_lshl_add_u64 v[28:29], v[28:29], 0, v[160:161]
	global_store_dwordx4 v[28:29], v[24:27], off
	s_nop 1
	v_pk_mul_f32 v[24:25], v[110:111], s[8:9] op_sel_hi:[1,0]
	v_pk_mul_f32 v[26:27], v[108:109], s[8:9] op_sel_hi:[1,0]
	v_pk_fma_f32 v[22:23], v[22:23], v[134:135], v[24:25]
	v_pk_fma_f32 v[20:21], v[20:21], v[132:133], v[26:27]
	v_pk_mul_f32 v[24:25], v[106:107], s[8:9] op_sel_hi:[1,0]
	v_pk_mul_f32 v[26:27], v[104:105], s[8:9] op_sel_hi:[1,0]
	v_pk_fma_f32 v[24:25], v[14:15], v[130:131], v[24:25]
	v_pk_fma_f32 v[14:15], v[12:13], v[128:129], v[26:27]
	v_cvt_pk_f16_f32 v12, v20, v21
	v_cvt_pk_f16_f32 v13, v22, v23
	v_cvt_pk_f16_f32 v14, v14, v15
	v_cvt_pk_f16_f32 v15, v24, v25
	global_store_dwordx4 v[28:29], v[12:15], off offset:256
	v_pk_mul_f32 v[20:21], v[116:117], s[8:9] op_sel_hi:[1,0]
	s_nop 0
	v_pk_mul_f32 v[14:15], v[118:119], s[8:9] op_sel_hi:[1,0]
	v_lshlrev_b64 v[12:13], 12, v[164:165]
	v_pk_fma_f32 v[14:15], v[18:19], v[142:143], v[14:15]
	v_pk_fma_f32 v[16:17], v[16:17], v[140:141], v[20:21]
	v_pk_mul_f32 v[18:19], v[114:115], s[8:9] op_sel_hi:[1,0]
	v_pk_mul_f32 v[20:21], v[112:113], s[8:9] op_sel_hi:[1,0]
	v_pk_fma_f32 v[18:19], v[10:11], v[138:139], v[18:19]
	v_pk_fma_f32 v[10:11], v[8:9], v[136:137], v[20:21]
	v_lshl_add_u64 v[12:13], s[0:1], 0, v[12:13]
	v_cvt_pk_f16_f32 v8, v16, v17
	v_cvt_pk_f16_f32 v9, v14, v15
	v_cvt_pk_f16_f32 v10, v10, v11
	v_cvt_pk_f16_f32 v11, v18, v19
	v_lshl_add_u64 v[12:13], v[12:13], 0, v[160:161]
	global_store_dwordx4 v[12:13], v[8:11], off
	s_nop 1
	v_pk_mul_f32 v[8:9], v[126:127], s[8:9] op_sel_hi:[1,0]
	v_pk_mul_f32 v[10:11], v[124:125], s[8:9] op_sel_hi:[1,0]
	v_pk_fma_f32 v[6:7], v[6:7], v[134:135], v[8:9]
	v_pk_fma_f32 v[4:5], v[4:5], v[132:133], v[10:11]
	v_pk_mul_f32 v[8:9], v[122:123], s[8:9] op_sel_hi:[1,0]
	v_pk_mul_f32 v[10:11], v[120:121], s[8:9] op_sel_hi:[1,0]
	v_pk_fma_f32 v[8:9], v[2:3], v[130:131], v[8:9]
	v_pk_fma_f32 v[2:3], v[0:1], v[128:129], v[10:11]
	v_cvt_pk_f16_f32 v0, v4, v5
	v_cvt_pk_f16_f32 v1, v6, v7
	v_cvt_pk_f16_f32 v2, v2, v3
	v_cvt_pk_f16_f32 v3, v8, v9
	global_store_dwordx4 v[12:13], v[0:3], off offset:256
	s_cbranch_vccz .LBB0_659
	s_waitcnt vmcnt(0)
	s_cmpk_gt_u32 s9, 0xff
	s_cbranch_scc1 .LBB0_670
	s_barrier

; #define PG8_STAGE(bufoff, gbase, voff) do { _Pragma("unroll") for (int _i = 0; _i < 2; ++_i) \
;         __builtin_amdgcn_global_load_lds((const unsigned*)((const char*)(gbase) + (voff)[_i]), (PG8_LAS unsigned*)(lds + (bufoff) + ldsw + _i * 8192), 16, 0, 0); } while (0)
; #define PG8_LDA(dst, b, h) do { _Pragma("unroll") for (int m = 0; m < 4; ++m) _Pragma("unroll") for (int k = 0; k < 2; ++k) dst[m][k] = *(const PG8_LAS bf16x8*)(lds + PG8_SA(b, h) + aoff + m * 2048 + k * 1024); } while (0)
; #define PG8_LDB(dst, b, h) do { _Pragma("unroll") for (int n = 0; n < 2; ++n) _Pragma("unroll") for (int k = 0; k < 2; ++k) dst[n][k] = *(const PG8_LAS bf16x8*)(lds + PG8_SB(b, h) + boff + n * 2048 + k * 1024); } while (0)
; #define PG8_WAIT_V(n) asm volatile("s_waitcnt vmcnt(" #n ")" ::: "memory")
; #define PG8_WAIT_L(n) asm volatile("s_waitcnt lgkmcnt(" #n ")" ::: "memory")
; #define PG8_BAR __builtin_amdgcn_s_barrier()
; #define PG8_SCHED __builtin_amdgcn_sched_barrier(0)
; template <class Epi, class Sched>
; __device__ __forceinline__ void gemm_phase(PG8_LAS unsigned char* lds, const Gemm g, const Sched& S, const Epi& E) {
;     ...
;         const bool has_next = S.next(ui + 1, nxt);
;         const char* nA = has_next ? (const char*)g.A + (size_t)nxt.pm * tstep : cA; const char* nB = has_next ? (const char*)g.Bt + (size_t)nxt.pn * tstep : cB;
;         for (int t = 0; t < nt; t += 2) {
;             const bool last = (t == nt - 2);
;             const char* a1 = cA + (size_t)(t + 1) * kstep;
;             const char* a2 = last ? nA : cA + (size_t)(t + 2) * kstep; const char* b2 = last ? nB : cB + (size_t)(t + 2) * kstep;
;             const char* a3 = a2 + kstep; const char* b3 = b2 + kstep;
;             if (last && has_next) S.a_ready(nxt);
;             PG8_LDB(B0, 0, 0); PG8_SCHED; PG8_LDA(At, 0, 0); PG8_STAGE(PG8_SA(1, 1), a1 + hstep, voffA);
;             PG8_WAIT_L(8); PG8_BAR; PG8_WAIT_L(0); PG8_MMA(0, 0, At, B0); PG8_BAR; PG8_SCHED;
;             PG8_LDB(B1, 0, 1); PG8_STAGE(PG8_SB(0, 0), b2, voffB);
;             PG8_BAR; PG8_WAIT_L(0); PG8_MMA(0, 1, At, B1); PG8_BAR;
;             PG8_LDA(At, 0, 1); PG8_STAGE(PG8_SA(0, 0), a2, voffA);
;             PG8_BAR; PG8_WAIT_L(0); PG8_MMA(1, 0, At, B0); PG8_BAR; PG8_SCHED;
;             PG8_STAGE(PG8_SB(0, 1), b2 + hstep, voffB);
;             PG8_WAIT_V(6); PG8_BAR; PG8_MMA(1, 1, At, B1); PG8_BAR;
.LBB0_802:
	s_ashr_i32 s9, s8, 31
	s_lshl_b64 s[10:11], s[8:9], 20
	v_cmp_lt_i64_e32 vcc, s[16:17], v[140:141]
	s_add_u32 s16, s35, s10
	s_addc_u32 s17, s36, s11
	s_and_b64 s[10:11], vcc, exec
	s_cselect_b32 s9, s17, s27
	s_cselect_b32 s66, s16, s26
	s_ashr_i32 s7, s6, 31
	s_lshl_b64 s[10:11], s[6:7], 20
	s_add_u32 s18, s37, s10
	s_addc_u32 s19, s38, s11
	s_and_b64 s[10:11], vcc, exec
	s_cselect_b32 s7, s19, s29
	s_cselect_b32 s67, s18, s28
	s_add_u32 s26, s26, 0x80080
	s_addc_u32 s27, s27, 0
	s_add_u32 s68, s28, 0x100
	s_addc_u32 s69, s29, 0
	s_mov_b32 s70, -2
	s_setprio 0
	ds_read_b128 v[150:153], v147
	ds_read_b128 v[154:157], v147 offset:1024
	ds_read_b128 v[158:161], v147 offset:2048
	ds_read_b128 v[162:165], v147 offset:3072
	ds_read_b128 v[166:169], v148
	ds_read_b128 v[170:173], v148 offset:1024
	ds_read_b128 v[174:177], v148 offset:2048
	ds_read_b128 v[178:181], v148 offset:3072
	ds_read_b128 v[182:185], v148 offset:4096
	ds_read_b128 v[186:189], v148 offset:5120
	ds_read_b128 v[190:193], v148 offset:6144
	ds_read_b128 v[194:197], v148 offset:7168
	s_waitcnt lgkmcnt(11)
	ds_read_b128 v[198:201], v149
	ds_read_b128 v[202:205], v149 offset:1024
	ds_read_b128 v[206:209], v149 offset:2048
	ds_read_b128 v[210:213], v149 offset:3072
	s_add_u32 s10, s26, 0xfff80080
	s_addc_u32 s11, s27, -1
	s_cmp_eq_u32 s70, 28
	s_cselect_b32 s31, s9, s11
	s_cselect_b32 s30, s66, s10
	s_cselect_b32 s29, s7, s69
	s_cselect_b32 s28, s67, s68
	s_add_u32 s98, s28, s4
	s_addc_u32 s99, s29, s5
	s_add_u32 s100, s30, s4
	s_addc_u32 s101, s31, s5
	s_add_i32 m0, s21, 0xc000
	s_nop 0
	global_load_lds_dwordx4 v136, s[26:27]
	s_add_i32 m0, s21, 0xe000
	s_nop 0
	global_load_lds_dwordx4 v138, s[26:27]
	s_waitcnt vmcnt(8)
	s_waitcnt lgkmcnt(0)
	s_setprio 1
	s_barrier
	v_mfma_f32_16x16x32_bf16 v[124:127], v[150:153], v[166:169], 0
	v_mfma_f32_16x16x32_bf16 v[120:123], v[158:161], v[166:169], 0
	v_mfma_f32_16x16x32_bf16 v[108:111], v[150:153], v[174:177], 0
	v_mfma_f32_16x16x32_bf16 v[104:107], v[158:161], v[174:177], 0
	v_mfma_f32_16x16x32_bf16 v[92:95], v[150:153], v[182:185], 0
	v_mfma_f32_16x16x32_bf16 v[88:91], v[158:161], v[182:185], 0
	v_mfma_f32_16x16x32_bf16 v[76:79], v[150:153], v[190:193], 0
	v_mfma_f32_16x16x32_bf16 v[72:75], v[158:161], v[190:193], 0
	v_mfma_f32_16x16x32_bf16 v[124:127], v[154:157], v[170:173], v[124:127]
	v_mfma_f32_16x16x32_bf16 v[120:123], v[162:165], v[170:173], v[120:123]
	v_mfma_f32_16x16x32_bf16 v[108:111], v[154:157], v[178:181], v[108:111]
	v_mfma_f32_16x16x32_bf16 v[104:107], v[162:165], v[178:181], v[104:107]
	v_mfma_f32_16x16x32_bf16 v[92:95], v[154:157], v[186:189], v[92:95]
	v_mfma_f32_16x16x32_bf16 v[88:91], v[162:165], v[186:189], v[88:91]
	v_mfma_f32_16x16x32_bf16 v[76:79], v[154:157], v[194:197], v[76:79]
	v_mfma_f32_16x16x32_bf16 v[72:75], v[162:165], v[194:197], v[72:75]
	v_mfma_f32_16x16x32_bf16 v[116:119], v[198:201], v[166:169], 0
	v_mfma_f32_16x16x32_bf16 v[112:115], v[206:209], v[166:169], 0
	v_mfma_f32_16x16x32_bf16 v[100:103], v[198:201], v[174:177], 0
	v_mfma_f32_16x16x32_bf16 v[96:99], v[206:209], v[174:177], 0
	v_mfma_f32_16x16x32_bf16 v[84:87], v[198:201], v[182:185], 0
	v_mfma_f32_16x16x32_bf16 v[80:83], v[206:209], v[182:185], 0
	v_mfma_f32_16x16x32_bf16 v[68:71], v[198:201], v[190:193], 0
	v_mfma_f32_16x16x32_bf16 v[64:67], v[206:209], v[190:193], 0
	v_mfma_f32_16x16x32_bf16 v[116:119], v[202:205], v[170:173], v[116:119]
	v_mfma_f32_16x16x32_bf16 v[112:115], v[210:213], v[170:173], v[112:115]
	v_mfma_f32_16x16x32_bf16 v[100:103], v[202:205], v[178:181], v[100:103]
	v_mfma_f32_16x16x32_bf16 v[96:99], v[210:213], v[178:181], v[96:99]
	v_mfma_f32_16x16x32_bf16 v[84:87], v[202:205], v[186:189], v[84:87]
	v_mfma_f32_16x16x32_bf16 v[80:83], v[210:213], v[186:189], v[80:83]
	v_mfma_f32_16x16x32_bf16 v[68:71], v[202:205], v[194:197], v[68:71]
	v_mfma_f32_16x16x32_bf16 v[64:67], v[210:213], v[194:197], v[64:67]
	s_barrier
	s_setprio 0
	ds_read_b128 v[166:169], v148 offset:16384
	ds_read_b128 v[170:173], v148 offset:17408
	ds_read_b128 v[174:177], v148 offset:18432
	ds_read_b128 v[178:181], v148 offset:19456
	ds_read_b128 v[182:185], v148 offset:20480
	ds_read_b128 v[186:189], v148 offset:21504
	ds_read_b128 v[190:193], v148 offset:22528
	ds_read_b128 v[194:197], v148 offset:23552
	s_add_i32 s10, s50, s39
	s_mov_b32 m0, s10
	s_nop 0
	global_load_lds_dwordx4 v132, s[28:29]
	s_add_i32 m0, s10, 0x2000
	s_nop 0
	global_load_lds_dwordx4 v128, s[28:29]
	s_mov_b32 m0, s21
	s_nop 0
	global_load_lds_dwordx4 v134, s[30:31]
	s_mov_b32 m0, s42
	s_nop 0
	global_load_lds_dwordx4 v130, s[30:31]
	s_add_u32 s10, s28, 0x80000
	s_addc_u32 s11, s29, 0
	s_add_i32 s33, s51, s39
	s_mov_b32 m0, s33
	s_nop 0
	global_load_lds_dwordx4 v132, s[10:11]
	s_add_i32 m0, s33, 0x2000
	s_nop 0
	global_load_lds_dwordx4 v128, s[10:11]
	s_waitcnt vmcnt(8)
	s_waitcnt lgkmcnt(0)
	s_setprio 1
	s_barrier
; #define PG8_STAGE(bufoff, gbase, voff) do { _Pragma("unroll") for (int _i = 0; _i < 2; ++_i) \
;         __builtin_amdgcn_global_load_lds((const unsigned*)((const char*)(gbase) + (voff)[_i]), (PG8_LAS unsigned*)(lds + (bufoff) + ldsw + _i * 8192), 16, 0, 0); } while (0)
; #define PG8_LDA(dst, b, h) do { _Pragma("unroll") for (int m = 0; m < 4; ++m) _Pragma("unroll") for (int k = 0; k < 2; ++k) dst[m][k] = *(const PG8_LAS bf16x8*)(lds + PG8_SA(b, h) + aoff + m * 2048 + k * 1024); } while (0)
; #define PG8_LDB(dst, b, h) do { _Pragma("unroll") for (int n = 0; n < 2; ++n) _Pragma("unroll") for (int k = 0; k < 2; ++k) dst[n][k] = *(const PG8_LAS bf16x8*)(lds + PG8_SB(b, h) + boff + n * 2048 + k * 1024); } while (0)
; #define PG8_MMA(ai, bj, At, Bt) do { __builtin_amdgcn_s_setprio(1); _Pragma("unroll") for (int m = 0; m < 4; ++m) _Pragma("unroll") for (int n = 0; n < 2; ++n) _Pragma("unroll") for (int k = 0; k < 2; ++k) \
;         acc[ai][bj][m][n] = __builtin_amdgcn_mfma_f32_16x16x32_bf16(Bt[n][k], At[m][k], acc[ai][bj][m][n], 0, 0, 0); __builtin_amdgcn_s_setprio(0); } while (0)
; #define PG8_WAIT_V(n) asm volatile("s_waitcnt vmcnt(" #n ")" ::: "memory")
; #define PG8_WAIT_L(n) asm volatile("s_waitcnt lgkmcnt(" #n ")" ::: "memory")
; #define PG8_BAR __builtin_amdgcn_s_barrier()
; #define PG8_SCHED __builtin_amdgcn_sched_barrier(0)
; template <class Epi, class Sched>
; __device__ __forceinline__ void gemm_phase(PG8_LAS unsigned char* lds, const Gemm g, const Sched& S, const Epi& E) {
;     ...
;             PG8_BAR; PG8_WAIT_L(0); PG8_MMA(1, 0, At, B0); PG8_BAR; PG8_SCHED;
;             PG8_STAGE(PG8_SB(0, 1), b2 + hstep, voffB);
;             PG8_WAIT_V(6); PG8_BAR; PG8_MMA(1, 1, At, B1); PG8_BAR;
;             PG8_LDB(B0, 1, 0); PG8_SCHED; PG8_LDA(At, 1, 0); PG8_STAGE(PG8_SA(0, 1), a2 + hstep, voffA);
;             PG8_WAIT_L(8); PG8_BAR; PG8_WAIT_L(0); PG8_MMA(0, 0, At, B0); PG8_BAR; PG8_SCHED;
;             PG8_LDB(B1, 1, 1); PG8_STAGE(PG8_SB(1, 0), b3, voffB);
;             PG8_BAR; PG8_WAIT_L(0); PG8_MMA(0, 1, At, B1); PG8_BAR;
	v_mfma_f32_16x16x32_bf16 v[60:63], v[150:153], v[166:169], 0
	v_mfma_f32_16x16x32_bf16 v[56:59], v[158:161], v[166:169], 0
	v_mfma_f32_16x16x32_bf16 v[44:47], v[150:153], v[174:177], 0
	v_mfma_f32_16x16x32_bf16 v[40:43], v[158:161], v[174:177], 0
	v_mfma_f32_16x16x32_bf16 v[28:31], v[150:153], v[182:185], 0
	v_mfma_f32_16x16x32_bf16 v[24:27], v[158:161], v[182:185], 0
	v_mfma_f32_16x16x32_bf16 v[12:15], v[150:153], v[190:193], 0
	v_mfma_f32_16x16x32_bf16 v[8:11], v[158:161], v[190:193], 0
	s_add_i32 s33, 0, 0x18000
	v_mfma_f32_16x16x32_bf16 v[60:63], v[154:157], v[170:173], v[60:63]
	v_mfma_f32_16x16x32_bf16 v[56:59], v[162:165], v[170:173], v[56:59]
	v_mfma_f32_16x16x32_bf16 v[44:47], v[154:157], v[178:181], v[44:47]
	v_mfma_f32_16x16x32_bf16 v[40:43], v[162:165], v[178:181], v[40:43]
	v_mfma_f32_16x16x32_bf16 v[28:31], v[154:157], v[186:189], v[28:31]
	v_mfma_f32_16x16x32_bf16 v[24:27], v[162:165], v[186:189], v[24:27]
	v_mfma_f32_16x16x32_bf16 v[12:15], v[154:157], v[194:197], v[12:15]
	v_mfma_f32_16x16x32_bf16 v[8:11], v[162:165], v[194:197], v[8:11]
	v_mfma_f32_16x16x32_bf16 v[52:55], v[198:201], v[166:169], 0
	v_mfma_f32_16x16x32_bf16 v[48:51], v[206:209], v[166:169], 0
	v_mfma_f32_16x16x32_bf16 v[36:39], v[198:201], v[174:177], 0
	v_mfma_f32_16x16x32_bf16 v[32:35], v[206:209], v[174:177], 0
	v_mfma_f32_16x16x32_bf16 v[20:23], v[198:201], v[182:185], 0
	v_mfma_f32_16x16x32_bf16 v[16:19], v[206:209], v[182:185], 0
	v_mfma_f32_16x16x32_bf16 v[4:7], v[198:201], v[190:193], 0
	v_mfma_f32_16x16x32_bf16 v[0:3], v[206:209], v[190:193], 0
	v_mfma_f32_16x16x32_bf16 v[52:55], v[202:205], v[170:173], v[52:55]
	v_mfma_f32_16x16x32_bf16 v[48:51], v[210:213], v[170:173], v[48:51]
	v_mfma_f32_16x16x32_bf16 v[36:39], v[202:205], v[178:181], v[36:39]
	v_mfma_f32_16x16x32_bf16 v[32:35], v[210:213], v[178:181], v[32:35]
	v_mfma_f32_16x16x32_bf16 v[20:23], v[202:205], v[186:189], v[20:23]
	v_mfma_f32_16x16x32_bf16 v[16:19], v[210:213], v[186:189], v[16:19]
	v_mfma_f32_16x16x32_bf16 v[4:7], v[202:205], v[194:197], v[4:7]
	v_mfma_f32_16x16x32_bf16 v[0:3], v[210:213], v[194:197], v[0:3]
	s_barrier
	s_setprio 0
	ds_read_b128 v[150:153], v147 offset:32768
	ds_read_b128 v[154:157], v147 offset:33792
	ds_read_b128 v[158:161], v147 offset:34816
	ds_read_b128 v[162:165], v147 offset:35840
	ds_read_b128 v[166:169], v148 offset:32768
	ds_read_b128 v[170:173], v148 offset:33792
	ds_read_b128 v[174:177], v148 offset:34816
	ds_read_b128 v[178:181], v148 offset:35840
	ds_read_b128 v[182:185], v148 offset:36864
	ds_read_b128 v[186:189], v148 offset:37888
	ds_read_b128 v[190:193], v148 offset:38912
	ds_read_b128 v[194:197], v148 offset:39936
	s_waitcnt lgkmcnt(11)
	ds_read_b128 v[198:201], v149 offset:32768
	ds_read_b128 v[202:205], v149 offset:33792
	ds_read_b128 v[206:209], v149 offset:34816
	ds_read_b128 v[210:213], v149 offset:35840
	s_add_u32 s10, s30, 0x80000
	s_addc_u32 s11, s31, 0
	s_mov_b32 m0, s43
	s_nop 0
	global_load_lds_dwordx4 v134, s[10:11]
	s_mov_b32 m0, s44
	s_nop 0
	global_load_lds_dwordx4 v130, s[10:11]
	s_waitcnt vmcnt(8)
	s_waitcnt lgkmcnt(0)
	s_setprio 1
	s_barrier
	v_mfma_f32_16x16x32_bf16 v[124:127], v[150:153], v[166:169], v[124:127]
	v_mfma_f32_16x16x32_bf16 v[120:123], v[158:161], v[166:169], v[120:123]
	v_mfma_f32_16x16x32_bf16 v[108:111], v[150:153], v[174:177], v[108:111]
	v_mfma_f32_16x16x32_bf16 v[104:107], v[158:161], v[174:177], v[104:107]
	v_mfma_f32_16x16x32_bf16 v[92:95], v[150:153], v[182:185], v[92:95]
	v_mfma_f32_16x16x32_bf16 v[88:91], v[158:161], v[182:185], v[88:91]
	v_mfma_f32_16x16x32_bf16 v[76:79], v[150:153], v[190:193], v[76:79]
	v_mfma_f32_16x16x32_bf16 v[72:75], v[158:161], v[190:193], v[72:75]
	v_mfma_f32_16x16x32_bf16 v[124:127], v[154:157], v[170:173], v[124:127]
	v_mfma_f32_16x16x32_bf16 v[120:123], v[162:165], v[170:173], v[120:123]
	v_mfma_f32_16x16x32_bf16 v[108:111], v[154:157], v[178:181], v[108:111]
	v_mfma_f32_16x16x32_bf16 v[104:107], v[162:165], v[178:181], v[104:107]
	v_mfma_f32_16x16x32_bf16 v[92:95], v[154:157], v[186:189], v[92:95]
	v_mfma_f32_16x16x32_bf16 v[88:91], v[162:165], v[186:189], v[88:91]
	v_mfma_f32_16x16x32_bf16 v[76:79], v[154:157], v[194:197], v[76:79]
	v_mfma_f32_16x16x32_bf16 v[72:75], v[162:165], v[194:197], v[72:75]
	v_mfma_f32_16x16x32_bf16 v[116:119], v[198:201], v[166:169], v[116:119]
	v_mfma_f32_16x16x32_bf16 v[112:115], v[206:209], v[166:169], v[112:115]
	v_mfma_f32_16x16x32_bf16 v[100:103], v[198:201], v[174:177], v[100:103]
	v_mfma_f32_16x16x32_bf16 v[96:99], v[206:209], v[174:177], v[96:99]
	v_mfma_f32_16x16x32_bf16 v[84:87], v[198:201], v[182:185], v[84:87]
	v_mfma_f32_16x16x32_bf16 v[80:83], v[206:209], v[182:185], v[80:83]
	v_mfma_f32_16x16x32_bf16 v[68:71], v[198:201], v[190:193], v[68:71]
	v_mfma_f32_16x16x32_bf16 v[64:67], v[206:209], v[190:193], v[64:67]
	v_mfma_f32_16x16x32_bf16 v[116:119], v[202:205], v[170:173], v[116:119]
	v_mfma_f32_16x16x32_bf16 v[112:115], v[210:213], v[170:173], v[112:115]
	v_mfma_f32_16x16x32_bf16 v[100:103], v[202:205], v[178:181], v[100:103]
	v_mfma_f32_16x16x32_bf16 v[96:99], v[210:213], v[178:181], v[96:99]
	v_mfma_f32_16x16x32_bf16 v[84:87], v[202:205], v[186:189], v[84:87]
	v_mfma_f32_16x16x32_bf16 v[80:83], v[210:213], v[186:189], v[80:83]
	v_mfma_f32_16x16x32_bf16 v[68:71], v[202:205], v[194:197], v[68:71]
	v_mfma_f32_16x16x32_bf16 v[64:67], v[210:213], v[194:197], v[64:67]
	s_barrier
; #define PG8_STAGE(bufoff, gbase, voff) do { _Pragma("unroll") for (int _i = 0; _i < 2; ++_i) \
;         __builtin_amdgcn_global_load_lds((const unsigned*)((const char*)(gbase) + (voff)[_i]), (PG8_LAS unsigned*)(lds + (bufoff) + ldsw + _i * 8192), 16, 0, 0); } while (0)
; #define PG8_LDA(dst, b, h) do { _Pragma("unroll") for (int m = 0; m < 4; ++m) _Pragma("unroll") for (int k = 0; k < 2; ++k) dst[m][k] = *(const PG8_LAS bf16x8*)(lds + PG8_SA(b, h) + aoff + m * 2048 + k * 1024); } while (0)
; #define PG8_LDB(dst, b, h) do { _Pragma("unroll") for (int n = 0; n < 2; ++n) _Pragma("unroll") for (int k = 0; k < 2; ++k) dst[n][k] = *(const PG8_LAS bf16x8*)(lds + PG8_SB(b, h) + boff + n * 2048 + k * 1024); } while (0)
; #define PG8_MMA(ai, bj, At, Bt) do { __builtin_amdgcn_s_setprio(1); _Pragma("unroll") for (int m = 0; m < 4; ++m) _Pragma("unroll") for (int n = 0; n < 2; ++n) _Pragma("unroll") for (int k = 0; k < 2; ++k) \
;         acc[ai][bj][m][n] = __builtin_amdgcn_mfma_f32_16x16x32_bf16(Bt[n][k], At[m][k], acc[ai][bj][m][n], 0, 0, 0); __builtin_amdgcn_s_setprio(0); } while (0)
; #define PG8_WAIT_V(n) asm volatile("s_waitcnt vmcnt(" #n ")" ::: "memory")
; #define PG8_WAIT_L(n) asm volatile("s_waitcnt lgkmcnt(" #n ")" ::: "memory")
; #define PG8_BAR __builtin_amdgcn_s_barrier()
; #define PG8_SCHED __builtin_amdgcn_sched_barrier(0)
; template <class Epi, class Sched>
; __device__ __forceinline__ void gemm_phase(PG8_LAS unsigned char* lds, const Gemm g, const Sched& S, const Epi& E) {
;     ...
;             PG8_LDB(B0, 0, 0); PG8_SCHED; PG8_LDA(At, 0, 0); PG8_STAGE(PG8_SA(1, 1), a1 + hstep, voffA);
;             PG8_WAIT_L(8); PG8_BAR; PG8_WAIT_L(0); PG8_MMA(0, 0, At, B0); PG8_BAR; PG8_SCHED;
;     ...
;             PG8_LDB(B0, 1, 0); PG8_SCHED; PG8_LDA(At, 1, 0); PG8_STAGE(PG8_SA(0, 1), a2 + hstep, voffA);
;             PG8_WAIT_L(8); PG8_BAR; PG8_WAIT_L(0); PG8_MMA(0, 0, At, B0); PG8_BAR; PG8_SCHED;
;             PG8_LDB(B1, 1, 1); PG8_STAGE(PG8_SB(1, 0), b3, voffB);
;             PG8_BAR; PG8_WAIT_L(0); PG8_MMA(0, 1, At, B1); PG8_BAR;
;             PG8_LDA(At, 1, 1); PG8_STAGE(PG8_SA(1, 0), a3, voffA);
;             PG8_BAR; PG8_WAIT_L(0); PG8_MMA(1, 0, At, B0); PG8_BAR; PG8_SCHED;
;             PG8_STAGE(PG8_SB(1, 1), b3 + hstep, voffB);
;             PG8_WAIT_V(6); PG8_BAR; PG8_MMA(1, 1, At, B1); PG8_BAR;
	s_setprio 0
	ds_read_b128 v[166:169], v148 offset:49152
	ds_read_b128 v[170:173], v148 offset:50176
	ds_read_b128 v[174:177], v148 offset:51200
	ds_read_b128 v[178:181], v148 offset:52224
	ds_read_b128 v[182:185], v148 offset:53248
	ds_read_b128 v[186:189], v148 offset:54272
	ds_read_b128 v[190:193], v148 offset:55296
	ds_read_b128 v[194:197], v148 offset:56320
	s_add_i32 s30, 0, 0x1c000
	s_add_i32 s10, s33, s39
	s_mov_b32 m0, s10
	s_nop 0
	global_load_lds_dwordx4 v132, s[98:99]
	s_add_i32 m0, s10, 0x2000
	s_nop 0
	global_load_lds_dwordx4 v128, s[98:99]
	s_mov_b32 m0, s46
	s_nop 0
	global_load_lds_dwordx4 v134, s[100:101]
	s_mov_b32 m0, s47
	s_nop 0
	global_load_lds_dwordx4 v130, s[100:101]
	s_add_u32 s10, s28, 0x80080
	s_addc_u32 s11, s29, 0
	s_add_i32 s28, s30, s39
	s_mov_b32 m0, s28
	s_nop 0
	global_load_lds_dwordx4 v132, s[10:11]
	s_add_i32 m0, s28, 0x2000
	s_nop 0
	global_load_lds_dwordx4 v128, s[10:11]
	s_waitcnt vmcnt(8)
	s_waitcnt lgkmcnt(0)
	s_setprio 1
	s_barrier
	v_mfma_f32_16x16x32_bf16 v[60:63], v[150:153], v[166:169], v[60:63]
	v_mfma_f32_16x16x32_bf16 v[56:59], v[158:161], v[166:169], v[56:59]
	v_mfma_f32_16x16x32_bf16 v[44:47], v[150:153], v[174:177], v[44:47]
	v_mfma_f32_16x16x32_bf16 v[40:43], v[158:161], v[174:177], v[40:43]
	v_mfma_f32_16x16x32_bf16 v[28:31], v[150:153], v[182:185], v[28:31]
	v_mfma_f32_16x16x32_bf16 v[24:27], v[158:161], v[182:185], v[24:27]
	v_mfma_f32_16x16x32_bf16 v[12:15], v[150:153], v[190:193], v[12:15]
	v_mfma_f32_16x16x32_bf16 v[8:11], v[158:161], v[190:193], v[8:11]
	s_add_i32 s70, s70, 2
	s_add_u32 s26, s26, 0x100
	s_addc_u32 s27, s27, 0
	s_add_u32 s68, s68, 0x100
	s_addc_u32 s69, s69, 0
	s_cmp_gt_u32 s70, 29
	v_mfma_f32_16x16x32_bf16 v[60:63], v[154:157], v[170:173], v[60:63]
	v_mfma_f32_16x16x32_bf16 v[56:59], v[162:165], v[170:173], v[56:59]
	v_mfma_f32_16x16x32_bf16 v[44:47], v[154:157], v[178:181], v[44:47]
	v_mfma_f32_16x16x32_bf16 v[40:43], v[162:165], v[178:181], v[40:43]
	v_mfma_f32_16x16x32_bf16 v[28:31], v[154:157], v[186:189], v[28:31]
	v_mfma_f32_16x16x32_bf16 v[24:27], v[162:165], v[186:189], v[24:27]
	v_mfma_f32_16x16x32_bf16 v[12:15], v[154:157], v[194:197], v[12:15]
	v_mfma_f32_16x16x32_bf16 v[8:11], v[162:165], v[194:197], v[8:11]
	v_mfma_f32_16x16x32_bf16 v[52:55], v[198:201], v[166:169], v[52:55]
	v_mfma_f32_16x16x32_bf16 v[48:51], v[206:209], v[166:169], v[48:51]
	v_mfma_f32_16x16x32_bf16 v[36:39], v[198:201], v[174:177], v[36:39]
	v_mfma_f32_16x16x32_bf16 v[32:35], v[206:209], v[174:177], v[32:35]
	v_mfma_f32_16x16x32_bf16 v[20:23], v[198:201], v[182:185], v[20:23]
	v_mfma_f32_16x16x32_bf16 v[16:19], v[206:209], v[182:185], v[16:19]
	v_mfma_f32_16x16x32_bf16 v[4:7], v[198:201], v[190:193], v[4:7]
	v_mfma_f32_16x16x32_bf16 v[0:3], v[206:209], v[190:193], v[0:3]
	v_mfma_f32_16x16x32_bf16 v[52:55], v[202:205], v[170:173], v[52:55]
	v_mfma_f32_16x16x32_bf16 v[48:51], v[210:213], v[170:173], v[48:51]
	v_mfma_f32_16x16x32_bf16 v[36:39], v[202:205], v[178:181], v[36:39]
	v_mfma_f32_16x16x32_bf16 v[32:35], v[210:213], v[178:181], v[32:35]
	v_mfma_f32_16x16x32_bf16 v[20:23], v[202:205], v[186:189], v[20:23]
	v_mfma_f32_16x16x32_bf16 v[16:19], v[210:213], v[186:189], v[16:19]
	v_mfma_f32_16x16x32_bf16 v[4:7], v[202:205], v[194:197], v[4:7]
	v_mfma_f32_16x16x32_bf16 v[0:3], v[210:213], v[194:197], v[0:3]
	s_barrier
.LBB0_803:
	s_setprio 0
	ds_read_b128 v[150:153], v147
	ds_read_b128 v[154:157], v147 offset:1024
	ds_read_b128 v[158:161], v147 offset:2048
	ds_read_b128 v[162:165], v147 offset:3072
	ds_read_b128 v[166:169], v148
	ds_read_b128 v[170:173], v148 offset:1024
	ds_read_b128 v[174:177], v148 offset:2048
	ds_read_b128 v[178:181], v148 offset:3072
	ds_read_b128 v[182:185], v148 offset:4096
	ds_read_b128 v[186:189], v148 offset:5120
	ds_read_b128 v[190:193], v148 offset:6144
	ds_read_b128 v[194:197], v148 offset:7168
	s_waitcnt lgkmcnt(11)
	ds_read_b128 v[198:201], v149
	ds_read_b128 v[202:205], v149 offset:1024
	ds_read_b128 v[206:209], v149 offset:2048
	ds_read_b128 v[210:213], v149 offset:3072
	s_add_u32 s10, s26, 0xfff80080
	s_addc_u32 s11, s27, -1
	s_cmp_eq_u32 s70, 28
	s_cselect_b32 s31, s9, s11
	s_cselect_b32 s30, s66, s10
	s_cselect_b32 s29, s7, s69
	s_cselect_b32 s28, s67, s68
	s_add_u32 s98, s28, s4
	s_addc_u32 s99, s29, s5
	s_add_u32 s100, s30, s4
	s_addc_u32 s101, s31, s5
	s_add_i32 m0, s21, 0xc000
	s_nop 0
	global_load_lds_dwordx4 v136, s[26:27]
	s_add_i32 m0, s21, 0xe000
	s_nop 0
	global_load_lds_dwordx4 v138, s[26:27]
	s_waitcnt vmcnt(8)
	s_waitcnt lgkmcnt(0)
	s_setprio 1
	s_barrier
; #define PG8_STAGE(bufoff, gbase, voff) do { _Pragma("unroll") for (int _i = 0; _i < 2; ++_i) \
;         __builtin_amdgcn_global_load_lds((const unsigned*)((const char*)(gbase) + (voff)[_i]), (PG8_LAS unsigned*)(lds + (bufoff) + ldsw + _i * 8192), 16, 0, 0); } while (0)
; #define PG8_LDA(dst, b, h) do { _Pragma("unroll") for (int m = 0; m < 4; ++m) _Pragma("unroll") for (int k = 0; k < 2; ++k) dst[m][k] = *(const PG8_LAS bf16x8*)(lds + PG8_SA(b, h) + aoff + m * 2048 + k * 1024); } while (0)
; #define PG8_LDB(dst, b, h) do { _Pragma("unroll") for (int n = 0; n < 2; ++n) _Pragma("unroll") for (int k = 0; k < 2; ++k) dst[n][k] = *(const PG8_LAS bf16x8*)(lds + PG8_SB(b, h) + boff + n * 2048 + k * 1024); } while (0)
; #define PG8_MMA(ai, bj, At, Bt) do { __builtin_amdgcn_s_setprio(1); _Pragma("unroll") for (int m = 0; m < 4; ++m) _Pragma("unroll") for (int n = 0; n < 2; ++n) _Pragma("unroll") for (int k = 0; k < 2; ++k) \
;         acc[ai][bj][m][n] = __builtin_amdgcn_mfma_f32_16x16x32_bf16(Bt[n][k], At[m][k], acc[ai][bj][m][n], 0, 0, 0); __builtin_amdgcn_s_setprio(0); } while (0)
; #define PG8_WAIT_V(n) asm volatile("s_waitcnt vmcnt(" #n ")" ::: "memory")
; #define PG8_WAIT_L(n) asm volatile("s_waitcnt lgkmcnt(" #n ")" ::: "memory")
; #define PG8_BAR __builtin_amdgcn_s_barrier()
; #define PG8_SCHED __builtin_amdgcn_sched_barrier(0)
; template <class Epi, class Sched>
; __device__ __forceinline__ void gemm_phase(PG8_LAS unsigned char* lds, const Gemm g, const Sched& S, const Epi& E) {
;     ...
;             PG8_WAIT_L(8); PG8_BAR; PG8_WAIT_L(0); PG8_MMA(0, 0, At, B0); PG8_BAR; PG8_SCHED;
;             PG8_LDB(B1, 0, 1); PG8_STAGE(PG8_SB(0, 0), b2, voffB);
;             PG8_BAR; PG8_WAIT_L(0); PG8_MMA(0, 1, At, B1); PG8_BAR;
;             PG8_LDA(At, 0, 1); PG8_STAGE(PG8_SA(0, 0), a2, voffA);
;             PG8_BAR; PG8_WAIT_L(0); PG8_MMA(1, 0, At, B0); PG8_BAR; PG8_SCHED;
;             PG8_STAGE(PG8_SB(0, 1), b2 + hstep, voffB);
;             PG8_WAIT_V(6); PG8_BAR; PG8_MMA(1, 1, At, B1); PG8_BAR;
;             PG8_LDB(B0, 1, 0); PG8_SCHED; PG8_LDA(At, 1, 0); PG8_STAGE(PG8_SA(0, 1), a2 + hstep, voffA);
;             PG8_WAIT_L(8); PG8_BAR; PG8_WAIT_L(0); PG8_MMA(0, 0, At, B0); PG8_BAR; PG8_SCHED;
	v_mfma_f32_16x16x32_bf16 v[124:127], v[150:153], v[166:169], v[124:127]
	v_mfma_f32_16x16x32_bf16 v[120:123], v[158:161], v[166:169], v[120:123]
	v_mfma_f32_16x16x32_bf16 v[108:111], v[150:153], v[174:177], v[108:111]
	v_mfma_f32_16x16x32_bf16 v[104:107], v[158:161], v[174:177], v[104:107]
	v_mfma_f32_16x16x32_bf16 v[92:95], v[150:153], v[182:185], v[92:95]
	v_mfma_f32_16x16x32_bf16 v[88:91], v[158:161], v[182:185], v[88:91]
	v_mfma_f32_16x16x32_bf16 v[76:79], v[150:153], v[190:193], v[76:79]
	v_mfma_f32_16x16x32_bf16 v[72:75], v[158:161], v[190:193], v[72:75]
	v_mfma_f32_16x16x32_bf16 v[124:127], v[154:157], v[170:173], v[124:127]
	v_mfma_f32_16x16x32_bf16 v[120:123], v[162:165], v[170:173], v[120:123]
	v_mfma_f32_16x16x32_bf16 v[108:111], v[154:157], v[178:181], v[108:111]
	v_mfma_f32_16x16x32_bf16 v[104:107], v[162:165], v[178:181], v[104:107]
	v_mfma_f32_16x16x32_bf16 v[92:95], v[154:157], v[186:189], v[92:95]
	v_mfma_f32_16x16x32_bf16 v[88:91], v[162:165], v[186:189], v[88:91]
	v_mfma_f32_16x16x32_bf16 v[76:79], v[154:157], v[194:197], v[76:79]
	v_mfma_f32_16x16x32_bf16 v[72:75], v[162:165], v[194:197], v[72:75]
	v_mfma_f32_16x16x32_bf16 v[116:119], v[198:201], v[166:169], v[116:119]
	v_mfma_f32_16x16x32_bf16 v[112:115], v[206:209], v[166:169], v[112:115]
	v_mfma_f32_16x16x32_bf16 v[100:103], v[198:201], v[174:177], v[100:103]
	v_mfma_f32_16x16x32_bf16 v[96:99], v[206:209], v[174:177], v[96:99]
	v_mfma_f32_16x16x32_bf16 v[84:87], v[198:201], v[182:185], v[84:87]
	v_mfma_f32_16x16x32_bf16 v[80:83], v[206:209], v[182:185], v[80:83]
	v_mfma_f32_16x16x32_bf16 v[68:71], v[198:201], v[190:193], v[68:71]
	v_mfma_f32_16x16x32_bf16 v[64:67], v[206:209], v[190:193], v[64:67]
	v_mfma_f32_16x16x32_bf16 v[116:119], v[202:205], v[170:173], v[116:119]
	v_mfma_f32_16x16x32_bf16 v[112:115], v[210:213], v[170:173], v[112:115]
	v_mfma_f32_16x16x32_bf16 v[100:103], v[202:205], v[178:181], v[100:103]
	v_mfma_f32_16x16x32_bf16 v[96:99], v[210:213], v[178:181], v[96:99]
	v_mfma_f32_16x16x32_bf16 v[84:87], v[202:205], v[186:189], v[84:87]
	v_mfma_f32_16x16x32_bf16 v[80:83], v[210:213], v[186:189], v[80:83]
	v_mfma_f32_16x16x32_bf16 v[68:71], v[202:205], v[194:197], v[68:71]
	v_mfma_f32_16x16x32_bf16 v[64:67], v[210:213], v[194:197], v[64:67]
	s_barrier
	s_setprio 0
	ds_read_b128 v[166:169], v148 offset:16384
	ds_read_b128 v[170:173], v148 offset:17408
	ds_read_b128 v[174:177], v148 offset:18432
	ds_read_b128 v[178:181], v148 offset:19456
	ds_read_b128 v[182:185], v148 offset:20480
	ds_read_b128 v[186:189], v148 offset:21504
	ds_read_b128 v[190:193], v148 offset:22528
	ds_read_b128 v[194:197], v148 offset:23552
	s_add_i32 s10, s50, s39
	s_mov_b32 m0, s10
	s_nop 0
	global_load_lds_dwordx4 v132, s[28:29]
	s_add_i32 m0, s10, 0x2000
	s_nop 0
	global_load_lds_dwordx4 v128, s[28:29]
	s_mov_b32 m0, s21
	s_nop 0
	global_load_lds_dwordx4 v134, s[30:31]
	s_mov_b32 m0, s42
	s_nop 0
	global_load_lds_dwordx4 v130, s[30:31]
	s_add_u32 s10, s28, 0x80000
	s_addc_u32 s11, s29, 0
	s_add_i32 s33, s51, s39
	s_mov_b32 m0, s33
	s_nop 0
	global_load_lds_dwordx4 v132, s[10:11]
	s_add_i32 m0, s33, 0x2000
	s_nop 0
	global_load_lds_dwordx4 v128, s[10:11]
	s_waitcnt vmcnt(8)
	s_waitcnt lgkmcnt(0)
	s_setprio 1
	s_barrier
	v_mfma_f32_16x16x32_bf16 v[60:63], v[150:153], v[166:169], v[60:63]
	v_mfma_f32_16x16x32_bf16 v[56:59], v[158:161], v[166:169], v[56:59]
	v_mfma_f32_16x16x32_bf16 v[44:47], v[150:153], v[174:177], v[44:47]
	v_mfma_f32_16x16x32_bf16 v[40:43], v[158:161], v[174:177], v[40:43]
	v_mfma_f32_16x16x32_bf16 v[28:31], v[150:153], v[182:185], v[28:31]
	v_mfma_f32_16x16x32_bf16 v[24:27], v[158:161], v[182:185], v[24:27]
	v_mfma_f32_16x16x32_bf16 v[12:15], v[150:153], v[190:193], v[12:15]
	v_mfma_f32_16x16x32_bf16 v[8:11], v[158:161], v[190:193], v[8:11]
	s_add_i32 s33, 0, 0x18000
	v_mfma_f32_16x16x32_bf16 v[60:63], v[154:157], v[170:173], v[60:63]
	v_mfma_f32_16x16x32_bf16 v[56:59], v[162:165], v[170:173], v[56:59]
	v_mfma_f32_16x16x32_bf16 v[44:47], v[154:157], v[178:181], v[44:47]
	v_mfma_f32_16x16x32_bf16 v[40:43], v[162:165], v[178:181], v[40:43]
	v_mfma_f32_16x16x32_bf16 v[28:31], v[154:157], v[186:189], v[28:31]
	v_mfma_f32_16x16x32_bf16 v[24:27], v[162:165], v[186:189], v[24:27]
	v_mfma_f32_16x16x32_bf16 v[12:15], v[154:157], v[194:197], v[12:15]
	v_mfma_f32_16x16x32_bf16 v[8:11], v[162:165], v[194:197], v[8:11]
	v_mfma_f32_16x16x32_bf16 v[52:55], v[198:201], v[166:169], v[52:55]
	v_mfma_f32_16x16x32_bf16 v[48:51], v[206:209], v[166:169], v[48:51]
	v_mfma_f32_16x16x32_bf16 v[36:39], v[198:201], v[174:177], v[36:39]
	v_mfma_f32_16x16x32_bf16 v[32:35], v[206:209], v[174:177], v[32:35]
	v_mfma_f32_16x16x32_bf16 v[20:23], v[198:201], v[182:185], v[20:23]
	v_mfma_f32_16x16x32_bf16 v[16:19], v[206:209], v[182:185], v[16:19]
	v_mfma_f32_16x16x32_bf16 v[4:7], v[198:201], v[190:193], v[4:7]
	v_mfma_f32_16x16x32_bf16 v[0:3], v[206:209], v[190:193], v[0:3]
	v_mfma_f32_16x16x32_bf16 v[52:55], v[202:205], v[170:173], v[52:55]
	v_mfma_f32_16x16x32_bf16 v[48:51], v[210:213], v[170:173], v[48:51]
	v_mfma_f32_16x16x32_bf16 v[36:39], v[202:205], v[178:181], v[36:39]
	v_mfma_f32_16x16x32_bf16 v[32:35], v[210:213], v[178:181], v[32:35]
	v_mfma_f32_16x16x32_bf16 v[20:23], v[202:205], v[186:189], v[20:23]
	v_mfma_f32_16x16x32_bf16 v[16:19], v[210:213], v[186:189], v[16:19]
	v_mfma_f32_16x16x32_bf16 v[4:7], v[202:205], v[194:197], v[4:7]
	v_mfma_f32_16x16x32_bf16 v[0:3], v[210:213], v[194:197], v[0:3]
	s_barrier
; #define PG8_STAGE(bufoff, gbase, voff) do { _Pragma("unroll") for (int _i = 0; _i < 2; ++_i) \
;         __builtin_amdgcn_global_load_lds((const unsigned*)((const char*)(gbase) + (voff)[_i]), (PG8_LAS unsigned*)(lds + (bufoff) + ldsw + _i * 8192), 16, 0, 0); } while (0)
; #define PG8_LDA(dst, b, h) do { _Pragma("unroll") for (int m = 0; m < 4; ++m) _Pragma("unroll") for (int k = 0; k < 2; ++k) dst[m][k] = *(const PG8_LAS bf16x8*)(lds + PG8_SA(b, h) + aoff + m * 2048 + k * 1024); } while (0)
; #define PG8_LDB(dst, b, h) do { _Pragma("unroll") for (int n = 0; n < 2; ++n) _Pragma("unroll") for (int k = 0; k < 2; ++k) dst[n][k] = *(const PG8_LAS bf16x8*)(lds + PG8_SB(b, h) + boff + n * 2048 + k * 1024); } while (0)
; #define PG8_MMA(ai, bj, At, Bt) do { __builtin_amdgcn_s_setprio(1); _Pragma("unroll") for (int m = 0; m < 4; ++m) _Pragma("unroll") for (int n = 0; n < 2; ++n) _Pragma("unroll") for (int k = 0; k < 2; ++k) \
;         acc[ai][bj][m][n] = __builtin_amdgcn_mfma_f32_16x16x32_bf16(Bt[n][k], At[m][k], acc[ai][bj][m][n], 0, 0, 0); __builtin_amdgcn_s_setprio(0); } while (0)
; #define PG8_WAIT_V(n) asm volatile("s_waitcnt vmcnt(" #n ")" ::: "memory")
; #define PG8_WAIT_L(n) asm volatile("s_waitcnt lgkmcnt(" #n ")" ::: "memory")
; #define PG8_BAR __builtin_amdgcn_s_barrier()
; #define PG8_SCHED __builtin_amdgcn_sched_barrier(0)
; template <class Epi, class Sched>
; __device__ __forceinline__ void gemm_phase(PG8_LAS unsigned char* lds, const Gemm g, const Sched& S, const Epi& E) {
;     ...
;             PG8_WAIT_V(6); PG8_BAR; PG8_MMA(1, 1, At, B1); PG8_BAR;
;             PG8_LDB(B0, 1, 0); PG8_SCHED; PG8_LDA(At, 1, 0); PG8_STAGE(PG8_SA(0, 1), a2 + hstep, voffA);
;             PG8_WAIT_L(8); PG8_BAR; PG8_WAIT_L(0); PG8_MMA(0, 0, At, B0); PG8_BAR; PG8_SCHED;
;             PG8_LDB(B1, 1, 1); PG8_STAGE(PG8_SB(1, 0), b3, voffB);
;             PG8_BAR; PG8_WAIT_L(0); PG8_MMA(0, 1, At, B1); PG8_BAR;
;             PG8_LDA(At, 1, 1); PG8_STAGE(PG8_SA(1, 0), a3, voffA);
;             PG8_BAR; PG8_WAIT_L(0); PG8_MMA(1, 0, At, B0); PG8_BAR; PG8_SCHED;
;             PG8_STAGE(PG8_SB(1, 1), b3 + hstep, voffB);
;             PG8_WAIT_V(6); PG8_BAR; PG8_MMA(1, 1, At, B1); PG8_BAR;
	s_setprio 0
	ds_read_b128 v[150:153], v147 offset:32768
	ds_read_b128 v[154:157], v147 offset:33792
	ds_read_b128 v[158:161], v147 offset:34816
	ds_read_b128 v[162:165], v147 offset:35840
	ds_read_b128 v[166:169], v148 offset:32768
	ds_read_b128 v[170:173], v148 offset:33792
	ds_read_b128 v[174:177], v148 offset:34816
	ds_read_b128 v[178:181], v148 offset:35840
	ds_read_b128 v[182:185], v148 offset:36864
	ds_read_b128 v[186:189], v148 offset:37888
	ds_read_b128 v[190:193], v148 offset:38912
	ds_read_b128 v[194:197], v148 offset:39936
	s_waitcnt lgkmcnt(11)
	ds_read_b128 v[198:201], v149 offset:32768
	ds_read_b128 v[202:205], v149 offset:33792
	ds_read_b128 v[206:209], v149 offset:34816
	ds_read_b128 v[210:213], v149 offset:35840
	s_add_u32 s10, s30, 0x80000
	s_addc_u32 s11, s31, 0
	s_mov_b32 m0, s43
	s_nop 0
	global_load_lds_dwordx4 v134, s[10:11]
	s_mov_b32 m0, s44
	s_nop 0
	global_load_lds_dwordx4 v130, s[10:11]
	s_waitcnt vmcnt(8)
	s_waitcnt lgkmcnt(0)
	s_setprio 1
	s_barrier
	v_mfma_f32_16x16x32_bf16 v[124:127], v[150:153], v[166:169], v[124:127]
	v_mfma_f32_16x16x32_bf16 v[120:123], v[158:161], v[166:169], v[120:123]
	v_mfma_f32_16x16x32_bf16 v[108:111], v[150:153], v[174:177], v[108:111]
	v_mfma_f32_16x16x32_bf16 v[104:107], v[158:161], v[174:177], v[104:107]
	v_mfma_f32_16x16x32_bf16 v[92:95], v[150:153], v[182:185], v[92:95]
	v_mfma_f32_16x16x32_bf16 v[88:91], v[158:161], v[182:185], v[88:91]
	v_mfma_f32_16x16x32_bf16 v[76:79], v[150:153], v[190:193], v[76:79]
	v_mfma_f32_16x16x32_bf16 v[72:75], v[158:161], v[190:193], v[72:75]
	v_mfma_f32_16x16x32_bf16 v[124:127], v[154:157], v[170:173], v[124:127]
	v_mfma_f32_16x16x32_bf16 v[120:123], v[162:165], v[170:173], v[120:123]
	v_mfma_f32_16x16x32_bf16 v[108:111], v[154:157], v[178:181], v[108:111]
	v_mfma_f32_16x16x32_bf16 v[104:107], v[162:165], v[178:181], v[104:107]
	v_mfma_f32_16x16x32_bf16 v[92:95], v[154:157], v[186:189], v[92:95]
	v_mfma_f32_16x16x32_bf16 v[88:91], v[162:165], v[186:189], v[88:91]
	v_mfma_f32_16x16x32_bf16 v[76:79], v[154:157], v[194:197], v[76:79]
	v_mfma_f32_16x16x32_bf16 v[72:75], v[162:165], v[194:197], v[72:75]
	v_mfma_f32_16x16x32_bf16 v[116:119], v[198:201], v[166:169], v[116:119]
	v_mfma_f32_16x16x32_bf16 v[112:115], v[206:209], v[166:169], v[112:115]
	v_mfma_f32_16x16x32_bf16 v[100:103], v[198:201], v[174:177], v[100:103]
	v_mfma_f32_16x16x32_bf16 v[96:99], v[206:209], v[174:177], v[96:99]
	v_mfma_f32_16x16x32_bf16 v[84:87], v[198:201], v[182:185], v[84:87]
	v_mfma_f32_16x16x32_bf16 v[80:83], v[206:209], v[182:185], v[80:83]
	v_mfma_f32_16x16x32_bf16 v[68:71], v[198:201], v[190:193], v[68:71]
	v_mfma_f32_16x16x32_bf16 v[64:67], v[206:209], v[190:193], v[64:67]
	v_mfma_f32_16x16x32_bf16 v[116:119], v[202:205], v[170:173], v[116:119]
	v_mfma_f32_16x16x32_bf16 v[112:115], v[210:213], v[170:173], v[112:115]
	v_mfma_f32_16x16x32_bf16 v[100:103], v[202:205], v[178:181], v[100:103]
	v_mfma_f32_16x16x32_bf16 v[96:99], v[210:213], v[178:181], v[96:99]
	v_mfma_f32_16x16x32_bf16 v[84:87], v[202:205], v[186:189], v[84:87]
	v_mfma_f32_16x16x32_bf16 v[80:83], v[210:213], v[186:189], v[80:83]
	v_mfma_f32_16x16x32_bf16 v[68:71], v[202:205], v[194:197], v[68:71]
	v_mfma_f32_16x16x32_bf16 v[64:67], v[210:213], v[194:197], v[64:67]
	s_barrier
	s_setprio 0
	ds_read_b128 v[166:169], v148 offset:49152
	ds_read_b128 v[170:173], v148 offset:50176
	ds_read_b128 v[174:177], v148 offset:51200
	ds_read_b128 v[178:181], v148 offset:52224
	ds_read_b128 v[182:185], v148 offset:53248
	ds_read_b128 v[186:189], v148 offset:54272
	ds_read_b128 v[190:193], v148 offset:55296
	ds_read_b128 v[194:197], v148 offset:56320
	s_add_i32 s30, 0, 0x1c000
	s_add_i32 s10, s33, s39
	s_mov_b32 m0, s10
	s_nop 0
	global_load_lds_dwordx4 v132, s[98:99]
	s_add_i32 m0, s10, 0x2000
	s_nop 0
	global_load_lds_dwordx4 v128, s[98:99]
	s_mov_b32 m0, s46
	s_nop 0
	global_load_lds_dwordx4 v134, s[100:101]
	s_mov_b32 m0, s47
	s_nop 0
	global_load_lds_dwordx4 v130, s[100:101]
	s_add_u32 s10, s28, 0x80080
	s_addc_u32 s11, s29, 0
	s_add_i32 s28, s30, s39
	s_mov_b32 m0, s28
	s_nop 0
	global_load_lds_dwordx4 v132, s[10:11]
	s_add_i32 m0, s28, 0x2000
	s_nop 0
	global_load_lds_dwordx4 v128, s[10:11]
	s_waitcnt vmcnt(8)
	s_waitcnt lgkmcnt(0)
	s_setprio 1
	s_barrier
	v_mfma_f32_16x16x32_bf16 v[60:63], v[150:153], v[166:169], v[60:63]
	v_mfma_f32_16x16x32_bf16 v[56:59], v[158:161], v[166:169], v[56:59]
	v_mfma_f32_16x16x32_bf16 v[44:47], v[150:153], v[174:177], v[44:47]
	v_mfma_f32_16x16x32_bf16 v[40:43], v[158:161], v[174:177], v[40:43]
	v_mfma_f32_16x16x32_bf16 v[28:31], v[150:153], v[182:185], v[28:31]
	v_mfma_f32_16x16x32_bf16 v[24:27], v[158:161], v[182:185], v[24:27]
	v_mfma_f32_16x16x32_bf16 v[12:15], v[150:153], v[190:193], v[12:15]
	v_mfma_f32_16x16x32_bf16 v[8:11], v[158:161], v[190:193], v[8:11]
	s_add_i32 s70, s70, 2
	s_add_u32 s26, s26, 0x100
	s_addc_u32 s27, s27, 0
	s_add_u32 s68, s68, 0x100
	s_addc_u32 s69, s69, 0
	s_cmp_gt_u32 s70, 29
	v_mfma_f32_16x16x32_bf16 v[60:63], v[154:157], v[170:173], v[60:63]
	v_mfma_f32_16x16x32_bf16 v[56:59], v[162:165], v[170:173], v[56:59]
	v_mfma_f32_16x16x32_bf16 v[44:47], v[154:157], v[178:181], v[44:47]
	v_mfma_f32_16x16x32_bf16 v[40:43], v[162:165], v[178:181], v[40:43]
	v_mfma_f32_16x16x32_bf16 v[28:31], v[154:157], v[186:189], v[28:31]
	v_mfma_f32_16x16x32_bf16 v[24:27], v[162:165], v[186:189], v[24:27]
	v_mfma_f32_16x16x32_bf16 v[12:15], v[154:157], v[194:197], v[12:15]
	v_mfma_f32_16x16x32_bf16 v[8:11], v[162:165], v[194:197], v[8:11]
	v_mfma_f32_16x16x32_bf16 v[52:55], v[198:201], v[166:169], v[52:55]
	v_mfma_f32_16x16x32_bf16 v[48:51], v[206:209], v[166:169], v[48:51]
	v_mfma_f32_16x16x32_bf16 v[36:39], v[198:201], v[174:177], v[36:39]
	v_mfma_f32_16x16x32_bf16 v[32:35], v[206:209], v[174:177], v[32:35]
	v_mfma_f32_16x16x32_bf16 v[20:23], v[198:201], v[182:185], v[20:23]
	v_mfma_f32_16x16x32_bf16 v[16:19], v[206:209], v[182:185], v[16:19]
	v_mfma_f32_16x16x32_bf16 v[4:7], v[198:201], v[190:193], v[4:7]
	v_mfma_f32_16x16x32_bf16 v[0:3], v[206:209], v[190:193], v[0:3]
	v_mfma_f32_16x16x32_bf16 v[52:55], v[202:205], v[170:173], v[52:55]
	v_mfma_f32_16x16x32_bf16 v[48:51], v[210:213], v[170:173], v[48:51]
	v_mfma_f32_16x16x32_bf16 v[36:39], v[202:205], v[178:181], v[36:39]
	v_mfma_f32_16x16x32_bf16 v[32:35], v[210:213], v[178:181], v[32:35]
	v_mfma_f32_16x16x32_bf16 v[20:23], v[202:205], v[186:189], v[20:23]
	v_mfma_f32_16x16x32_bf16 v[16:19], v[210:213], v[186:189], v[16:19]
	v_mfma_f32_16x16x32_bf16 v[4:7], v[202:205], v[194:197], v[4:7]
	v_mfma_f32_16x16x32_bf16 v[0:3], v[210:213], v[194:197], v[0:3]
	s_barrier
; __device__ __forceinline__ unsigned cvt_pk_bf16(float lo, float hi) { const bf16v2_t v = __builtin_convertvector((f32x2){lo, hi}, bf16v2_t); return __builtin_bit_cast(unsigned, v); }
; __device__ __forceinline__ float silu_f(float v) { return v * __builtin_amdgcn_rcpf(1.0f + __expf(-v)); }
;     __device__ __forceinline__ void operator()(const AccT& acc, const pg8::Unit& u, int wr, int wc, int fr, int fq) const {
;         const int row0 = u.pm * 256 + wr * 64 + fr, col = u.pn * 128 + wc * 32 + 8 * fq;
; #pragma unroll
;         for (int ai = 0; ai < 2; ++ai)
; #pragma unroll
;             for (int m = 0; m < 4; ++m) {
;                 f32x4 a = acc[ai][0][m][0], b = acc[ai][0][m][1];
; #pragma unroll
;                 for (int j = 0; j < 4; ++j) { a[j] = silu_f(a[j]) * acc[ai][1][m][0][j]; b[j] = silu_f(b[j]) * acc[ai][1][m][1][j]; }
;                 u32x4 w; w.x = cvt_pk_bf16(a[0], a[1]); w.y = cvt_pk_bf16(a[2], a[3]); w.z = cvt_pk_bf16(b[0], b[1]); w.w = cvt_pk_bf16(b[2], b[3]);
;                 *(u32x4*)(HID + (size_t)(row0 + ai * 128 + m * 16) * DFF + col) = w;
	s_cbranch_scc0 .LBB0_803
	s_setprio 0
	v_mul_f32_e32 v151, 0xbfb8aa3b, v124
	v_mul_f32_e32 v154, 0xbfb8aa3b, v120
	v_exp_f32_e32 v151, v151
	v_exp_f32_e32 v155, v154
	v_mul_f32_e32 v154, 0xbfb8aa3b, v125
	v_exp_f32_e32 v156, v154
	v_add_f32_e32 v151, 1.0, v151
	v_rcp_f32_e32 v154, v151
	v_add_f32_e32 v151, 1.0, v155
	v_add_f32_e32 v155, 1.0, v156
	v_rcp_f32_e32 v155, v155
	v_mul_f32_e32 v156, 0xbfb8aa3b, v121
	v_exp_f32_e32 v157, v156
	v_rcp_f32_e32 v156, v151
	v_pk_mul_f32 v[124:125], v[124:125], v[154:155]
	v_mul_f32_e32 v151, 0xbfb8aa3b, v127
	v_pk_mul_f32 v[116:117], v[124:125], v[116:117]
	v_add_f32_e32 v124, 1.0, v157
	v_mul_f32_e32 v125, 0xbfb8aa3b, v122
	v_rcp_f32_e32 v157, v124
	v_mul_f32_e32 v124, 0xbfb8aa3b, v126
	v_exp_f32_e32 v125, v125
	v_exp_f32_e32 v124, v124
	v_exp_f32_e32 v151, v151
	v_mul_f32_e32 v154, 0xbfb8aa3b, v123
	v_exp_f32_e32 v155, v154
	v_add_f32_e32 v125, 1.0, v125
	v_add_f32_e32 v124, 1.0, v124
	v_rcp_f32_e32 v154, v125
	v_add_f32_e32 v125, 1.0, v151
	v_rcp_f32_e32 v124, v124
	v_rcp_f32_e32 v125, v125
	v_add_f32_e32 v151, 1.0, v155
	v_rcp_f32_e32 v155, v151
	v_pk_mul_f32 v[120:121], v[120:121], v[156:157]
	v_lshl_or_b32 v152, s65, 7, v146
	v_pk_mul_f32 v[112:113], v[120:121], v[112:113]
	v_pk_mul_f32 v[120:121], v[126:127], v[124:125]
	v_lshl_add_u32 v150, s20, 8, v144
	v_pk_mul_f32 v[118:119], v[120:121], v[118:119]
	v_pk_mul_f32 v[120:121], v[122:123], v[154:155]
	v_ashrrev_i32_e32 v153, 31, v152
	v_pk_mul_f32 v[114:115], v[120:121], v[114:115]
	v_cvt_pk_bf16_f32 v116, v116, v117
	v_cvt_pk_bf16_f32 v117, v118, v119
	v_cvt_pk_bf16_f32 v118, v112, v113
	v_mov_b64_e32 v[112:113], s[0:1]
	v_cvt_pk_bf16_f32 v119, v114, v115
	v_mad_i64_i32 v[120:121], s[10:11], v150, s64, v[112:113]
	v_lshlrev_b64 v[114:115], 1, v[152:153]
	v_lshl_add_u64 v[120:121], v[120:121], 0, v[114:115]
	global_store_dwordx4 v[120:121], v[116:119], off
	s_and_b64 vcc, exec, s[2:3]
	s_mov_b32 s65, s6
	v_mul_f32_e32 v116, 0xbfb8aa3b, v108
	v_mul_f32_e32 v117, 0xbfb8aa3b, v104
	v_mul_f32_e32 v118, 0xbfb8aa3b, v109
	v_exp_f32_e32 v116, v116
	v_exp_f32_e32 v117, v117
	v_exp_f32_e32 v118, v118
	s_mov_b32 s20, s8
	v_add_f32_e32 v116, 1.0, v116
	v_add_f32_e32 v119, 1.0, v117
	v_add_f32_e32 v117, 1.0, v118
	v_rcp_f32_e32 v116, v116
	v_rcp_f32_e32 v117, v117
	v_mul_f32_e32 v118, 0xbfb8aa3b, v105
	v_exp_f32_e32 v120, v118
	v_rcp_f32_e32 v118, v119
	v_pk_mul_f32 v[108:109], v[108:109], v[116:117]
	v_mul_f32_e32 v116, 0xbfb8aa3b, v111
	v_pk_mul_f32 v[100:101], v[108:109], v[100:101]
	v_add_f32_e32 v108, 1.0, v120
	v_rcp_f32_e32 v119, v108
	v_mul_f32_e32 v109, 0xbfb8aa3b, v106
	v_mul_f32_e32 v108, 0xbfb8aa3b, v110
	v_exp_f32_e32 v109, v109
	v_exp_f32_e32 v108, v108
	v_exp_f32_e32 v117, v116
	v_mul_f32_e32 v116, 0xbfb8aa3b, v107
	v_pk_mul_f32 v[104:105], v[104:105], v[118:119]
	v_exp_f32_e32 v118, v116
	v_add_f32_e32 v109, 1.0, v109
	v_add_f32_e32 v108, 1.0, v108
	v_rcp_f32_e32 v116, v109
	v_add_f32_e32 v109, 1.0, v117
	v_rcp_f32_e32 v108, v108
	v_rcp_f32_e32 v109, v109
	v_add_f32_e32 v117, 1.0, v118
	v_rcp_f32_e32 v117, v117
	v_pk_mul_f32 v[104:105], v[104:105], v[96:97]
	v_pk_mul_f32 v[96:97], v[110:111], v[108:109]
	s_mov_b64 s[28:29], s[18:19]
	v_pk_mul_f32 v[102:103], v[96:97], v[102:103]
	v_pk_mul_f32 v[96:97], v[106:107], v[116:117]
	s_mov_b64 s[26:27], s[16:17]
	v_pk_mul_f32 v[106:107], v[96:97], v[98:99]
	v_cvt_pk_bf16_f32 v96, v100, v101
	v_or_b32_e32 v100, 16, v150
	v_mad_i64_i32 v[100:101], s[10:11], v100, s64, v[112:113]
	v_cvt_pk_bf16_f32 v97, v102, v103
	v_cvt_pk_bf16_f32 v98, v104, v105
	v_cvt_pk_bf16_f32 v99, v106, v107
	v_lshl_add_u64 v[100:101], v[100:101], 0, v[114:115]
	global_store_dwordx4 v[100:101], v[96:99], off
	s_nop 1
	v_mul_f32_e32 v96, 0xbfb8aa3b, v92
	v_mul_f32_e32 v97, 0xbfb8aa3b, v88
	v_mul_f32_e32 v98, 0xbfb8aa3b, v93
	v_exp_f32_e32 v96, v96
	v_exp_f32_e32 v97, v97
	v_exp_f32_e32 v98, v98
	v_add_f32_e32 v96, 1.0, v96
	v_add_f32_e32 v99, 1.0, v97
	v_add_f32_e32 v97, 1.0, v98
	v_rcp_f32_e32 v96, v96
	v_rcp_f32_e32 v97, v97
	v_mul_f32_e32 v98, 0xbfb8aa3b, v89
	v_exp_f32_e32 v100, v98
	v_rcp_f32_e32 v98, v99
	v_pk_mul_f32 v[92:93], v[92:93], v[96:97]
	v_mul_f32_e32 v96, 0xbfb8aa3b, v95
	v_pk_mul_f32 v[84:85], v[92:93], v[84:85]
	v_add_f32_e32 v92, 1.0, v100
	v_rcp_f32_e32 v99, v92
	v_mul_f32_e32 v93, 0xbfb8aa3b, v90
	v_mul_f32_e32 v92, 0xbfb8aa3b, v94
	v_exp_f32_e32 v93, v93
	v_exp_f32_e32 v92, v92
	v_exp_f32_e32 v97, v96
	v_mul_f32_e32 v96, 0xbfb8aa3b, v91
	v_pk_mul_f32 v[88:89], v[88:89], v[98:99]
	v_exp_f32_e32 v98, v96
	v_add_f32_e32 v93, 1.0, v93
	v_add_f32_e32 v92, 1.0, v92
	v_rcp_f32_e32 v96, v93
	v_add_f32_e32 v93, 1.0, v97
	v_rcp_f32_e32 v92, v92
	v_rcp_f32_e32 v93, v93
	v_add_f32_e32 v97, 1.0, v98
	v_rcp_f32_e32 v97, v97
	v_pk_mul_f32 v[88:89], v[88:89], v[80:81]
	v_pk_mul_f32 v[80:81], v[94:95], v[92:93]
	s_nop 0
	v_pk_mul_f32 v[86:87], v[80:81], v[86:87]
	v_pk_mul_f32 v[80:81], v[90:91], v[96:97]
	s_nop 0
	v_pk_mul_f32 v[90:91], v[80:81], v[82:83]
	v_cvt_pk_bf16_f32 v80, v84, v85
	v_or_b32_e32 v84, 32, v150
	v_mad_i64_i32 v[84:85], s[10:11], v84, s64, v[112:113]
	v_cvt_pk_bf16_f32 v81, v86, v87
	v_cvt_pk_bf16_f32 v82, v88, v89
	v_cvt_pk_bf16_f32 v83, v90, v91
	v_lshl_add_u64 v[84:85], v[84:85], 0, v[114:115]
	global_store_dwordx4 v[84:85], v[80:83], off
	s_nop 1
	v_mul_f32_e32 v80, 0xbfb8aa3b, v76
	v_mul_f32_e32 v81, 0xbfb8aa3b, v72
	v_mul_f32_e32 v82, 0xbfb8aa3b, v77
	v_exp_f32_e32 v80, v80
	v_exp_f32_e32 v81, v81
	v_exp_f32_e32 v82, v82
	v_add_f32_e32 v80, 1.0, v80
	v_add_f32_e32 v83, 1.0, v81
	v_add_f32_e32 v81, 1.0, v82
	v_rcp_f32_e32 v80, v80
	v_rcp_f32_e32 v81, v81
	v_mul_f32_e32 v82, 0xbfb8aa3b, v73
; __device__ __forceinline__ unsigned cvt_pk_bf16(float lo, float hi) { const bf16v2_t v = __builtin_convertvector((f32x2){lo, hi}, bf16v2_t); return __builtin_bit_cast(unsigned, v); }
; __device__ __forceinline__ float silu_f(float v) { return v * __builtin_amdgcn_rcpf(1.0f + __expf(-v)); }
;     __device__ __forceinline__ void operator()(const AccT& acc, const pg8::Unit& u, int wr, int wc, int fr, int fq) const {
;     ...
;         for (int ai = 0; ai < 2; ++ai)
; #pragma unroll
;             for (int m = 0; m < 4; ++m) {
;                 f32x4 a = acc[ai][0][m][0], b = acc[ai][0][m][1];
; #pragma unroll
;                 for (int j = 0; j < 4; ++j) { a[j] = silu_f(a[j]) * acc[ai][1][m][0][j]; b[j] = silu_f(b[j]) * acc[ai][1][m][1][j]; }
;                 u32x4 w; w.x = cvt_pk_bf16(a[0], a[1]); w.y = cvt_pk_bf16(a[2], a[3]); w.z = cvt_pk_bf16(b[0], b[1]); w.w = cvt_pk_bf16(b[2], b[3]);
;                 *(u32x4*)(HID + (size_t)(row0 + ai * 128 + m * 16) * DFF + col) = w;
	v_exp_f32_e32 v84, v82
	v_rcp_f32_e32 v82, v83
	v_pk_mul_f32 v[76:77], v[76:77], v[80:81]
	v_mul_f32_e32 v80, 0xbfb8aa3b, v79
	v_pk_mul_f32 v[68:69], v[76:77], v[68:69]
	v_add_f32_e32 v76, 1.0, v84
	v_rcp_f32_e32 v83, v76
	v_mul_f32_e32 v77, 0xbfb8aa3b, v74
	v_mul_f32_e32 v76, 0xbfb8aa3b, v78
	v_exp_f32_e32 v77, v77
	v_exp_f32_e32 v76, v76
	v_exp_f32_e32 v81, v80
	v_mul_f32_e32 v80, 0xbfb8aa3b, v75
	v_pk_mul_f32 v[72:73], v[72:73], v[82:83]
	v_exp_f32_e32 v82, v80
	v_add_f32_e32 v77, 1.0, v77
	v_add_f32_e32 v76, 1.0, v76
	v_rcp_f32_e32 v80, v77
	v_add_f32_e32 v77, 1.0, v81
	v_rcp_f32_e32 v76, v76
	v_rcp_f32_e32 v77, v77
	v_add_f32_e32 v81, 1.0, v82
	v_rcp_f32_e32 v81, v81
	v_pk_mul_f32 v[72:73], v[72:73], v[64:65]
	v_pk_mul_f32 v[64:65], v[78:79], v[76:77]
	s_nop 0
	v_pk_mul_f32 v[70:71], v[64:65], v[70:71]
	v_pk_mul_f32 v[64:65], v[74:75], v[80:81]
	s_nop 0
	v_pk_mul_f32 v[74:75], v[64:65], v[66:67]
	v_cvt_pk_bf16_f32 v64, v68, v69
	v_or_b32_e32 v68, 48, v150
	v_mad_i64_i32 v[68:69], s[10:11], v68, s64, v[112:113]
	v_cvt_pk_bf16_f32 v65, v70, v71
	v_cvt_pk_bf16_f32 v66, v72, v73
	v_cvt_pk_bf16_f32 v67, v74, v75
	v_lshl_add_u64 v[68:69], v[68:69], 0, v[114:115]
	global_store_dwordx4 v[68:69], v[64:67], off
	v_add_u32_e32 v68, 0x80, v150
	s_nop 0
	v_mul_f32_e32 v64, 0xbfb8aa3b, v60
	v_mul_f32_e32 v65, 0xbfb8aa3b, v56
	v_mul_f32_e32 v66, 0xbfb8aa3b, v61
	v_exp_f32_e32 v64, v64
	v_exp_f32_e32 v65, v65
	v_exp_f32_e32 v66, v66
	v_add_f32_e32 v64, 1.0, v64
	v_add_f32_e32 v67, 1.0, v65
	v_add_f32_e32 v65, 1.0, v66
	v_rcp_f32_e32 v64, v64
	v_rcp_f32_e32 v65, v65
	v_mul_f32_e32 v66, 0xbfb8aa3b, v57
	v_exp_f32_e32 v69, v66
	v_rcp_f32_e32 v66, v67
	v_pk_mul_f32 v[60:61], v[60:61], v[64:65]
	v_mul_f32_e32 v64, 0xbfb8aa3b, v63
	v_pk_mul_f32 v[52:53], v[60:61], v[52:53]
	v_add_f32_e32 v60, 1.0, v69
	v_rcp_f32_e32 v67, v60
	v_mul_f32_e32 v61, 0xbfb8aa3b, v58
	v_mul_f32_e32 v60, 0xbfb8aa3b, v62
	v_exp_f32_e32 v61, v61
	v_exp_f32_e32 v60, v60
	v_exp_f32_e32 v65, v64
	v_mul_f32_e32 v64, 0xbfb8aa3b, v59
	v_pk_mul_f32 v[56:57], v[56:57], v[66:67]
	v_exp_f32_e32 v66, v64
	v_add_f32_e32 v61, 1.0, v61
	v_add_f32_e32 v60, 1.0, v60
	v_rcp_f32_e32 v64, v61
	v_add_f32_e32 v61, 1.0, v65
	v_rcp_f32_e32 v60, v60
	v_rcp_f32_e32 v61, v61
	v_add_f32_e32 v65, 1.0, v66
	v_rcp_f32_e32 v65, v65
	v_pk_mul_f32 v[56:57], v[56:57], v[48:49]
	v_pk_mul_f32 v[48:49], v[62:63], v[60:61]
	s_nop 0
	v_pk_mul_f32 v[54:55], v[48:49], v[54:55]
	v_pk_mul_f32 v[48:49], v[58:59], v[64:65]
	s_nop 0
	v_pk_mul_f32 v[58:59], v[48:49], v[50:51]
	v_cvt_pk_bf16_f32 v48, v52, v53
	v_mad_i64_i32 v[52:53], s[10:11], v68, s64, v[112:113]
	v_cvt_pk_bf16_f32 v49, v54, v55
	v_cvt_pk_bf16_f32 v50, v56, v57
	v_cvt_pk_bf16_f32 v51, v58, v59
	v_lshl_add_u64 v[52:53], v[52:53], 0, v[114:115]
	global_store_dwordx4 v[52:53], v[48:51], off
	s_nop 1
	v_mul_f32_e32 v48, 0xbfb8aa3b, v44
	v_mul_f32_e32 v49, 0xbfb8aa3b, v40
	v_mul_f32_e32 v50, 0xbfb8aa3b, v45
	v_exp_f32_e32 v48, v48
	v_exp_f32_e32 v49, v49
	v_exp_f32_e32 v50, v50
	v_add_f32_e32 v48, 1.0, v48
	v_add_f32_e32 v51, 1.0, v49
	v_add_f32_e32 v49, 1.0, v50
	v_rcp_f32_e32 v48, v48
	v_rcp_f32_e32 v49, v49
	v_mul_f32_e32 v50, 0xbfb8aa3b, v41
	v_exp_f32_e32 v52, v50
	v_rcp_f32_e32 v50, v51
	v_pk_mul_f32 v[44:45], v[44:45], v[48:49]
	v_mul_f32_e32 v48, 0xbfb8aa3b, v47
	v_pk_mul_f32 v[36:37], v[44:45], v[36:37]
	v_add_f32_e32 v44, 1.0, v52
	v_rcp_f32_e32 v51, v44
	v_mul_f32_e32 v45, 0xbfb8aa3b, v42
	v_mul_f32_e32 v44, 0xbfb8aa3b, v46
	v_exp_f32_e32 v45, v45
	v_exp_f32_e32 v44, v44
	v_exp_f32_e32 v49, v48
	v_mul_f32_e32 v48, 0xbfb8aa3b, v43
	v_pk_mul_f32 v[40:41], v[40:41], v[50:51]
	v_exp_f32_e32 v50, v48
	v_add_f32_e32 v45, 1.0, v45
	v_add_f32_e32 v44, 1.0, v44
	v_rcp_f32_e32 v48, v45
	v_add_f32_e32 v45, 1.0, v49
	v_rcp_f32_e32 v44, v44
	v_rcp_f32_e32 v45, v45
	v_add_f32_e32 v49, 1.0, v50
; __device__ __forceinline__ unsigned cvt_pk_bf16(float lo, float hi) { const bf16v2_t v = __builtin_convertvector((f32x2){lo, hi}, bf16v2_t); return __builtin_bit_cast(unsigned, v); }
; __device__ __forceinline__ float silu_f(float v) { return v * __builtin_amdgcn_rcpf(1.0f + __expf(-v)); }
; #define PG8_WAIT_V(n) asm volatile("s_waitcnt vmcnt(" #n ")" ::: "memory")
; #define PG8_BAR __builtin_amdgcn_s_barrier()
; template <class Epi, class Sched>
; __device__ __forceinline__ void gemm_phase(PG8_LAS unsigned char* lds, const Gemm g, const Sched& S, const Epi& E) {
;     ...
;         if (!has_next) break;
; #pragma unroll
;         for (int a = 0; a < 2; ++a)
; #pragma unroll
;             for (int b = 0; b < 2; ++b)
; #pragma unroll
;                 for (int m = 0; m < 4; ++m)
; #pragma unroll
;                     for (int n = 0; n < 2; ++n) acc[a][b][m][n] = (f32x4){0.f, 0.f, 0.f, 0.f};
;         cur = nxt; cA = nA; cB = nB; ++ui;
;     }
;     PG8_WAIT_V(0);
;     if (wr == 0) PG8_BAR;
;     PG8_BAR;
;     __device__ __forceinline__ void operator()(const AccT& acc, const pg8::Unit& u, int wr, int wc, int fr, int fq) const {
;     ...
;         for (int ai = 0; ai < 2; ++ai)
; #pragma unroll
;             for (int m = 0; m < 4; ++m) {
;                 f32x4 a = acc[ai][0][m][0], b = acc[ai][0][m][1];
; #pragma unroll
;                 for (int j = 0; j < 4; ++j) { a[j] = silu_f(a[j]) * acc[ai][1][m][0][j]; b[j] = silu_f(b[j]) * acc[ai][1][m][1][j]; }
;                 u32x4 w; w.x = cvt_pk_bf16(a[0], a[1]); w.y = cvt_pk_bf16(a[2], a[3]); w.z = cvt_pk_bf16(b[0], b[1]); w.w = cvt_pk_bf16(b[2], b[3]);
;                 *(u32x4*)(HID + (size_t)(row0 + ai * 128 + m * 16) * DFF + col) = w;
	v_rcp_f32_e32 v49, v49
	v_pk_mul_f32 v[40:41], v[40:41], v[32:33]
	v_pk_mul_f32 v[32:33], v[46:47], v[44:45]
	s_nop 0
	v_pk_mul_f32 v[38:39], v[32:33], v[38:39]
	v_pk_mul_f32 v[32:33], v[42:43], v[48:49]
	s_nop 0
	v_pk_mul_f32 v[42:43], v[32:33], v[34:35]
	v_cvt_pk_bf16_f32 v32, v36, v37
	v_add_u32_e32 v36, 0x90, v150
	v_mad_i64_i32 v[36:37], s[10:11], v36, s64, v[112:113]
	v_cvt_pk_bf16_f32 v33, v38, v39
	v_cvt_pk_bf16_f32 v34, v40, v41
	v_cvt_pk_bf16_f32 v35, v42, v43
	v_lshl_add_u64 v[36:37], v[36:37], 0, v[114:115]
	global_store_dwordx4 v[36:37], v[32:35], off
	s_nop 1
	v_mul_f32_e32 v32, 0xbfb8aa3b, v28
	v_mul_f32_e32 v33, 0xbfb8aa3b, v24
	v_mul_f32_e32 v34, 0xbfb8aa3b, v29
	v_exp_f32_e32 v32, v32
	v_exp_f32_e32 v33, v33
	v_exp_f32_e32 v34, v34
	v_add_f32_e32 v32, 1.0, v32
	v_add_f32_e32 v35, 1.0, v33
	v_add_f32_e32 v33, 1.0, v34
	v_rcp_f32_e32 v32, v32
	v_rcp_f32_e32 v33, v33
	v_mul_f32_e32 v34, 0xbfb8aa3b, v25
	v_exp_f32_e32 v36, v34
	v_rcp_f32_e32 v34, v35
	v_pk_mul_f32 v[28:29], v[28:29], v[32:33]
	v_mul_f32_e32 v32, 0xbfb8aa3b, v31
	v_pk_mul_f32 v[20:21], v[28:29], v[20:21]
	v_add_f32_e32 v28, 1.0, v36
	v_rcp_f32_e32 v35, v28
	v_mul_f32_e32 v29, 0xbfb8aa3b, v26
	v_mul_f32_e32 v28, 0xbfb8aa3b, v30
	v_exp_f32_e32 v29, v29
	v_exp_f32_e32 v28, v28
	v_exp_f32_e32 v33, v32
	v_mul_f32_e32 v32, 0xbfb8aa3b, v27
	v_pk_mul_f32 v[24:25], v[24:25], v[34:35]
	v_exp_f32_e32 v34, v32
	v_add_f32_e32 v29, 1.0, v29
	v_add_f32_e32 v28, 1.0, v28
	v_rcp_f32_e32 v32, v29
	v_add_f32_e32 v29, 1.0, v33
	v_rcp_f32_e32 v28, v28
	v_rcp_f32_e32 v29, v29
	v_add_f32_e32 v33, 1.0, v34
	v_rcp_f32_e32 v33, v33
	v_pk_mul_f32 v[24:25], v[24:25], v[16:17]
	v_pk_mul_f32 v[16:17], v[30:31], v[28:29]
	s_nop 0
	v_pk_mul_f32 v[22:23], v[16:17], v[22:23]
	v_pk_mul_f32 v[16:17], v[26:27], v[32:33]
	s_nop 0
	v_pk_mul_f32 v[26:27], v[16:17], v[18:19]
	v_cvt_pk_bf16_f32 v16, v20, v21
	v_add_u32_e32 v20, 0xa0, v150
	v_mad_i64_i32 v[20:21], s[10:11], v20, s64, v[112:113]
	v_cvt_pk_bf16_f32 v17, v22, v23
	v_cvt_pk_bf16_f32 v18, v24, v25
	v_cvt_pk_bf16_f32 v19, v26, v27
	v_lshl_add_u64 v[20:21], v[20:21], 0, v[114:115]
	global_store_dwordx4 v[20:21], v[16:19], off
	s_nop 1
	v_mul_f32_e32 v16, 0xbfb8aa3b, v12
	v_mul_f32_e32 v17, 0xbfb8aa3b, v8
	v_mul_f32_e32 v18, 0xbfb8aa3b, v13
	v_exp_f32_e32 v16, v16
	v_exp_f32_e32 v17, v17
	v_exp_f32_e32 v18, v18
	v_add_f32_e32 v16, 1.0, v16
	v_add_f32_e32 v19, 1.0, v17
	v_add_f32_e32 v17, 1.0, v18
	v_rcp_f32_e32 v16, v16
	v_rcp_f32_e32 v17, v17
	v_mul_f32_e32 v18, 0xbfb8aa3b, v9
	v_exp_f32_e32 v20, v18
	v_rcp_f32_e32 v18, v19
	v_pk_mul_f32 v[12:13], v[12:13], v[16:17]
	v_mul_f32_e32 v16, 0xbfb8aa3b, v15
	v_pk_mul_f32 v[4:5], v[12:13], v[4:5]
	v_add_f32_e32 v12, 1.0, v20
	v_rcp_f32_e32 v19, v12
	v_mul_f32_e32 v13, 0xbfb8aa3b, v10
	v_mul_f32_e32 v12, 0xbfb8aa3b, v14
	v_exp_f32_e32 v13, v13
	v_exp_f32_e32 v12, v12
	v_exp_f32_e32 v17, v16
	v_mul_f32_e32 v16, 0xbfb8aa3b, v11
	v_pk_mul_f32 v[8:9], v[8:9], v[18:19]
	v_exp_f32_e32 v18, v16
	v_add_f32_e32 v13, 1.0, v13
	v_add_f32_e32 v12, 1.0, v12
	v_rcp_f32_e32 v16, v13
	v_add_f32_e32 v13, 1.0, v17
	v_rcp_f32_e32 v12, v12
	v_rcp_f32_e32 v13, v13
	v_add_f32_e32 v17, 1.0, v18
	v_rcp_f32_e32 v17, v17
	v_pk_mul_f32 v[8:9], v[8:9], v[0:1]
	v_pk_mul_f32 v[0:1], v[14:15], v[12:13]
	s_nop 0
	v_pk_mul_f32 v[6:7], v[0:1], v[6:7]
	v_pk_mul_f32 v[0:1], v[10:11], v[16:17]
	s_nop 0
	v_pk_mul_f32 v[10:11], v[0:1], v[2:3]
	v_cvt_pk_bf16_f32 v0, v4, v5
	v_add_u32_e32 v4, 0xb0, v150
	v_mad_i64_i32 v[4:5], s[10:11], v4, s64, v[112:113]
	v_cvt_pk_bf16_f32 v1, v6, v7
	v_cvt_pk_bf16_f32 v2, v8, v9
	v_cvt_pk_bf16_f32 v3, v10, v11
	v_lshl_add_u64 v[4:5], v[4:5], 0, v[114:115]
	global_store_dwordx4 v[4:5], v[0:3], off
	s_cbranch_vccz .LBB0_800
	s_waitcnt vmcnt(0)
	s_cmpk_gt_u32 s34, 0xff
	s_cbranch_scc1 .LBB0_807
	s_barrier

; #define PG8_STAGE(bufoff, gbase, voff) do { _Pragma("unroll") for (int _i = 0; _i < 2; ++_i) \
;         __builtin_amdgcn_global_load_lds((const unsigned*)((const char*)(gbase) + (voff)[_i]), (PG8_LAS unsigned*)(lds + (bufoff) + ldsw + _i * 8192), 16, 0, 0); } while (0)
; #define PG8_LDA(dst, b, h) do { _Pragma("unroll") for (int m = 0; m < 4; ++m) _Pragma("unroll") for (int k = 0; k < 2; ++k) dst[m][k] = *(const PG8_LAS bf16x8*)(lds + PG8_SA(b, h) + aoff + m * 2048 + k * 1024); } while (0)
; #define PG8_LDB(dst, b, h) do { _Pragma("unroll") for (int n = 0; n < 2; ++n) _Pragma("unroll") for (int k = 0; k < 2; ++k) dst[n][k] = *(const PG8_LAS bf16x8*)(lds + PG8_SB(b, h) + boff + n * 2048 + k * 1024); } while (0)
; #define PG8_WAIT_V(n) asm volatile("s_waitcnt vmcnt(" #n ")" ::: "memory")
; #define PG8_WAIT_L(n) asm volatile("s_waitcnt lgkmcnt(" #n ")" ::: "memory")
; #define PG8_BAR __builtin_amdgcn_s_barrier()
; #define PG8_SCHED __builtin_amdgcn_sched_barrier(0)
; template <class Epi, class Sched>
; __device__ __forceinline__ void gemm_phase(PG8_LAS unsigned char* lds, const Gemm g, const Sched& S, const Epi& E) {
;     ...
;         const bool has_next = S.next(ui + 1, nxt);
;         const char* nA = has_next ? (const char*)g.A + (size_t)nxt.pm * tstep : cA; const char* nB = has_next ? (const char*)g.Bt + (size_t)nxt.pn * tstep : cB;
;         for (int t = 0; t < nt; t += 2) {
;             const bool last = (t == nt - 2);
;             const char* a1 = cA + (size_t)(t + 1) * kstep;
;             const char* a2 = last ? nA : cA + (size_t)(t + 2) * kstep; const char* b2 = last ? nB : cB + (size_t)(t + 2) * kstep;
;             const char* a3 = a2 + kstep; const char* b3 = b2 + kstep;
;             if (last && has_next) S.a_ready(nxt);
;             PG8_LDB(B0, 0, 0); PG8_SCHED; PG8_LDA(At, 0, 0); PG8_STAGE(PG8_SA(1, 1), a1 + hstep, voffA);
;             PG8_WAIT_L(8); PG8_BAR; PG8_WAIT_L(0); PG8_MMA(0, 0, At, B0); PG8_BAR; PG8_SCHED;
;             PG8_LDB(B1, 0, 1); PG8_STAGE(PG8_SB(0, 0), b2, voffB);
;             PG8_BAR; PG8_WAIT_L(0); PG8_MMA(0, 1, At, B1); PG8_BAR;
;             PG8_LDA(At, 0, 1); PG8_STAGE(PG8_SA(0, 0), a2, voffA);
;             PG8_BAR; PG8_WAIT_L(0); PG8_MMA(1, 0, At, B0); PG8_BAR; PG8_SCHED;
;             PG8_STAGE(PG8_SB(0, 1), b2 + hstep, voffB);
;             PG8_WAIT_V(6); PG8_BAR; PG8_MMA(1, 1, At, B1); PG8_BAR;
.LBB0_881:
	s_add_u32 s26, s26, 0x160080
	s_addc_u32 s27, s27, 0
	s_add_u32 s67, s28, 0x100
	s_addc_u32 s68, s29, 0
	s_mov_b32 s69, -2
	s_setprio 0
	ds_read_b128 v[108:111], v247
	ds_read_b128 v[112:115], v247 offset:1024
	ds_read_b128 v[124:127], v247 offset:2048
	ds_read_b128 v[128:131], v247 offset:3072
	ds_read_b128 v[144:147], v248
	ds_read_b128 v[148:151], v248 offset:1024
	ds_read_b128 v[152:155], v248 offset:2048
	ds_read_b128 v[156:159], v248 offset:3072
	ds_read_b128 v[160:163], v248 offset:4096
	ds_read_b128 v[164:167], v248 offset:5120
	ds_read_b128 v[168:171], v248 offset:6144
	ds_read_b128 v[172:175], v248 offset:7168
	s_waitcnt lgkmcnt(11)
	ds_read_b128 v[188:191], v249
	ds_read_b128 v[192:195], v249 offset:1024
	ds_read_b128 v[196:199], v249 offset:2048
	ds_read_b128 v[200:203], v249 offset:3072
	s_add_u32 s10, s26, 0xffea0080
	s_addc_u32 s11, s27, -1
	s_cmpk_eq_i32 s69, 0x54
	s_cselect_b32 s31, s1, s11
	s_cselect_b32 s30, s0, s10
	s_cselect_b32 s29, s5, s68
	s_cselect_b32 s28, s4, s67
	s_add_u32 s98, s28, s18
	s_addc_u32 s99, s29, s19
	s_add_u32 s100, s30, s18
	s_addc_u32 s101, s31, s19
	s_add_i32 m0, s40, 0xc000
	s_nop 0
	global_load_lds_dwordx4 v184, s[26:27]
	s_add_i32 m0, s40, 0xe000
	s_nop 0
	global_load_lds_dwordx4 v186, s[26:27]
	s_waitcnt vmcnt(8)
	s_waitcnt lgkmcnt(0)
	s_setprio 1
	s_barrier
	v_mfma_f32_16x16x32_bf16 v[140:143], v[108:111], v[144:147], 0
	v_mfma_f32_16x16x32_bf16 v[136:139], v[124:127], v[144:147], 0
	v_mfma_f32_16x16x32_bf16 v[116:119], v[108:111], v[152:155], 0
	v_mfma_f32_16x16x32_bf16 v[104:107], v[124:127], v[152:155], 0
	v_mfma_f32_16x16x32_bf16 v[92:95], v[108:111], v[160:163], 0
	v_mfma_f32_16x16x32_bf16 v[88:91], v[124:127], v[160:163], 0
	v_mfma_f32_16x16x32_bf16 v[76:79], v[108:111], v[168:171], 0
	v_mfma_f32_16x16x32_bf16 v[72:75], v[124:127], v[168:171], 0
	v_mfma_f32_16x16x32_bf16 v[140:143], v[112:115], v[148:151], v[140:143]
	v_mfma_f32_16x16x32_bf16 v[136:139], v[128:131], v[148:151], v[136:139]
	v_mfma_f32_16x16x32_bf16 v[116:119], v[112:115], v[156:159], v[116:119]
	v_mfma_f32_16x16x32_bf16 v[104:107], v[128:131], v[156:159], v[104:107]
	v_mfma_f32_16x16x32_bf16 v[92:95], v[112:115], v[164:167], v[92:95]
	v_mfma_f32_16x16x32_bf16 v[88:91], v[128:131], v[164:167], v[88:91]
	v_mfma_f32_16x16x32_bf16 v[76:79], v[112:115], v[172:175], v[76:79]
	v_mfma_f32_16x16x32_bf16 v[72:75], v[128:131], v[172:175], v[72:75]
	v_mfma_f32_16x16x32_bf16 v[132:135], v[188:191], v[144:147], 0
	v_mfma_f32_16x16x32_bf16 v[120:123], v[196:199], v[144:147], 0
	v_mfma_f32_16x16x32_bf16 v[100:103], v[188:191], v[152:155], 0
	v_mfma_f32_16x16x32_bf16 v[96:99], v[196:199], v[152:155], 0
	v_mfma_f32_16x16x32_bf16 v[84:87], v[188:191], v[160:163], 0
	v_mfma_f32_16x16x32_bf16 v[80:83], v[196:199], v[160:163], 0
	v_mfma_f32_16x16x32_bf16 v[68:71], v[188:191], v[168:171], 0
	v_mfma_f32_16x16x32_bf16 v[64:67], v[196:199], v[168:171], 0
	v_mfma_f32_16x16x32_bf16 v[132:135], v[192:195], v[148:151], v[132:135]
	v_mfma_f32_16x16x32_bf16 v[120:123], v[200:203], v[148:151], v[120:123]
	v_mfma_f32_16x16x32_bf16 v[100:103], v[192:195], v[156:159], v[100:103]
	v_mfma_f32_16x16x32_bf16 v[96:99], v[200:203], v[156:159], v[96:99]
	v_mfma_f32_16x16x32_bf16 v[84:87], v[192:195], v[164:167], v[84:87]
	v_mfma_f32_16x16x32_bf16 v[80:83], v[200:203], v[164:167], v[80:83]
	v_mfma_f32_16x16x32_bf16 v[68:71], v[192:195], v[172:175], v[68:71]
	v_mfma_f32_16x16x32_bf16 v[64:67], v[200:203], v[172:175], v[64:67]
	s_barrier
	s_setprio 0
	ds_read_b128 v[144:147], v248 offset:16384
	ds_read_b128 v[148:151], v248 offset:17408
	ds_read_b128 v[152:155], v248 offset:18432
	ds_read_b128 v[156:159], v248 offset:19456
	ds_read_b128 v[160:163], v248 offset:20480
	ds_read_b128 v[164:167], v248 offset:21504
	ds_read_b128 v[168:171], v248 offset:22528
	ds_read_b128 v[172:175], v248 offset:23552
	s_add_i32 s10, s49, s39
	s_mov_b32 m0, s10
	s_nop 0
	global_load_lds_dwordx4 v178, s[28:29]
	s_add_i32 m0, s10, 0x2000
	s_nop 0
	global_load_lds_dwordx4 v182, s[28:29]
	s_mov_b32 m0, s40
	s_nop 0
	global_load_lds_dwordx4 v176, s[30:31]
	s_mov_b32 m0, s41
	s_nop 0
	global_load_lds_dwordx4 v180, s[30:31]
	s_add_u32 s10, s28, 0x160000
	s_addc_u32 s11, s29, 0
	s_add_i32 s33, s50, s39
	s_mov_b32 m0, s33
	s_nop 0
	global_load_lds_dwordx4 v178, s[10:11]
	s_add_i32 m0, s33, 0x2000
	s_nop 0
	global_load_lds_dwordx4 v182, s[10:11]
	s_waitcnt vmcnt(8)
	s_waitcnt lgkmcnt(0)
	s_setprio 1
	s_barrier
	v_mfma_f32_16x16x32_bf16 v[60:63], v[108:111], v[144:147], 0
	v_mfma_f32_16x16x32_bf16 v[56:59], v[124:127], v[144:147], 0
	v_mfma_f32_16x16x32_bf16 v[44:47], v[108:111], v[152:155], 0
	v_mfma_f32_16x16x32_bf16 v[40:43], v[124:127], v[152:155], 0
	v_mfma_f32_16x16x32_bf16 v[28:31], v[108:111], v[160:163], 0
	v_mfma_f32_16x16x32_bf16 v[24:27], v[124:127], v[160:163], 0
	v_mfma_f32_16x16x32_bf16 v[12:15], v[108:111], v[168:171], 0
	v_mfma_f32_16x16x32_bf16 v[8:11], v[124:127], v[168:171], 0
	s_add_i32 s33, 0, 0x18000
	v_mfma_f32_16x16x32_bf16 v[60:63], v[112:115], v[148:151], v[60:63]
	v_mfma_f32_16x16x32_bf16 v[56:59], v[128:131], v[148:151], v[56:59]
	v_mfma_f32_16x16x32_bf16 v[44:47], v[112:115], v[156:159], v[44:47]
	v_mfma_f32_16x16x32_bf16 v[40:43], v[128:131], v[156:159], v[40:43]
	v_mfma_f32_16x16x32_bf16 v[28:31], v[112:115], v[164:167], v[28:31]
	v_mfma_f32_16x16x32_bf16 v[24:27], v[128:131], v[164:167], v[24:27]
	v_mfma_f32_16x16x32_bf16 v[12:15], v[112:115], v[172:175], v[12:15]
	v_mfma_f32_16x16x32_bf16 v[8:11], v[128:131], v[172:175], v[8:11]
	v_mfma_f32_16x16x32_bf16 v[52:55], v[188:191], v[144:147], 0
	v_mfma_f32_16x16x32_bf16 v[48:51], v[196:199], v[144:147], 0
	v_mfma_f32_16x16x32_bf16 v[36:39], v[188:191], v[152:155], 0
	v_mfma_f32_16x16x32_bf16 v[32:35], v[196:199], v[152:155], 0
	v_mfma_f32_16x16x32_bf16 v[20:23], v[188:191], v[160:163], 0
	v_mfma_f32_16x16x32_bf16 v[16:19], v[196:199], v[160:163], 0
	v_mfma_f32_16x16x32_bf16 v[4:7], v[188:191], v[168:171], 0
	v_mfma_f32_16x16x32_bf16 v[0:3], v[196:199], v[168:171], 0
	v_mfma_f32_16x16x32_bf16 v[52:55], v[192:195], v[148:151], v[52:55]
	v_mfma_f32_16x16x32_bf16 v[48:51], v[200:203], v[148:151], v[48:51]
	v_mfma_f32_16x16x32_bf16 v[36:39], v[192:195], v[156:159], v[36:39]
	v_mfma_f32_16x16x32_bf16 v[32:35], v[200:203], v[156:159], v[32:35]
	v_mfma_f32_16x16x32_bf16 v[20:23], v[192:195], v[164:167], v[20:23]
	v_mfma_f32_16x16x32_bf16 v[16:19], v[200:203], v[164:167], v[16:19]
	v_mfma_f32_16x16x32_bf16 v[4:7], v[192:195], v[172:175], v[4:7]
	v_mfma_f32_16x16x32_bf16 v[0:3], v[200:203], v[172:175], v[0:3]
	s_barrier
; #define PG8_STAGE(bufoff, gbase, voff) do { _Pragma("unroll") for (int _i = 0; _i < 2; ++_i) \
;         __builtin_amdgcn_global_load_lds((const unsigned*)((const char*)(gbase) + (voff)[_i]), (PG8_LAS unsigned*)(lds + (bufoff) + ldsw + _i * 8192), 16, 0, 0); } while (0)
; #define PG8_LDA(dst, b, h) do { _Pragma("unroll") for (int m = 0; m < 4; ++m) _Pragma("unroll") for (int k = 0; k < 2; ++k) dst[m][k] = *(const PG8_LAS bf16x8*)(lds + PG8_SA(b, h) + aoff + m * 2048 + k * 1024); } while (0)
; #define PG8_LDB(dst, b, h) do { _Pragma("unroll") for (int n = 0; n < 2; ++n) _Pragma("unroll") for (int k = 0; k < 2; ++k) dst[n][k] = *(const PG8_LAS bf16x8*)(lds + PG8_SB(b, h) + boff + n * 2048 + k * 1024); } while (0)
; #define PG8_MMA(ai, bj, At, Bt) do { __builtin_amdgcn_s_setprio(1); _Pragma("unroll") for (int m = 0; m < 4; ++m) _Pragma("unroll") for (int n = 0; n < 2; ++n) _Pragma("unroll") for (int k = 0; k < 2; ++k) \
;         acc[ai][bj][m][n] = __builtin_amdgcn_mfma_f32_16x16x32_bf16(Bt[n][k], At[m][k], acc[ai][bj][m][n], 0, 0, 0); __builtin_amdgcn_s_setprio(0); } while (0)
; #define PG8_WAIT_V(n) asm volatile("s_waitcnt vmcnt(" #n ")" ::: "memory")
; #define PG8_WAIT_L(n) asm volatile("s_waitcnt lgkmcnt(" #n ")" ::: "memory")
; #define PG8_BAR __builtin_amdgcn_s_barrier()
; #define PG8_SCHED __builtin_amdgcn_sched_barrier(0)
; template <class Epi, class Sched>
; __device__ __forceinline__ void gemm_phase(PG8_LAS unsigned char* lds, const Gemm g, const Sched& S, const Epi& E) {
;     ...
;             PG8_BAR; PG8_WAIT_L(0); PG8_MMA(1, 0, At, B0); PG8_BAR; PG8_SCHED;
;             PG8_STAGE(PG8_SB(0, 1), b2 + hstep, voffB);
;             PG8_WAIT_V(6); PG8_BAR; PG8_MMA(1, 1, At, B1); PG8_BAR;
;             PG8_LDB(B0, 1, 0); PG8_SCHED; PG8_LDA(At, 1, 0); PG8_STAGE(PG8_SA(0, 1), a2 + hstep, voffA);
;             PG8_WAIT_L(8); PG8_BAR; PG8_WAIT_L(0); PG8_MMA(0, 0, At, B0); PG8_BAR; PG8_SCHED;
;             PG8_LDB(B1, 1, 1); PG8_STAGE(PG8_SB(1, 0), b3, voffB);
;             PG8_BAR; PG8_WAIT_L(0); PG8_MMA(0, 1, At, B1); PG8_BAR;
;             PG8_LDA(At, 1, 1); PG8_STAGE(PG8_SA(1, 0), a3, voffA);
;             PG8_BAR; PG8_WAIT_L(0); PG8_MMA(1, 0, At, B0); PG8_BAR; PG8_SCHED;
;             PG8_STAGE(PG8_SB(1, 1), b3 + hstep, voffB);
;             PG8_WAIT_V(6); PG8_BAR; PG8_MMA(1, 1, At, B1); PG8_BAR;
	s_setprio 0
	ds_read_b128 v[108:111], v247 offset:32768
	ds_read_b128 v[112:115], v247 offset:33792
	ds_read_b128 v[124:127], v247 offset:34816
	ds_read_b128 v[128:131], v247 offset:35840
	ds_read_b128 v[144:147], v248 offset:32768
	ds_read_b128 v[148:151], v248 offset:33792
	ds_read_b128 v[152:155], v248 offset:34816
	ds_read_b128 v[156:159], v248 offset:35840
	ds_read_b128 v[160:163], v248 offset:36864
	ds_read_b128 v[164:167], v248 offset:37888
	ds_read_b128 v[168:171], v248 offset:38912
	ds_read_b128 v[172:175], v248 offset:39936
	s_waitcnt lgkmcnt(11)
	ds_read_b128 v[188:191], v249 offset:32768
	ds_read_b128 v[192:195], v249 offset:33792
	ds_read_b128 v[196:199], v249 offset:34816
	ds_read_b128 v[200:203], v249 offset:35840
	s_add_u32 s10, s30, 0x160000
	s_addc_u32 s11, s31, 0
	s_mov_b32 m0, s42
	s_nop 0
	global_load_lds_dwordx4 v176, s[10:11]
	s_mov_b32 m0, s43
	s_nop 0
	global_load_lds_dwordx4 v180, s[10:11]
	s_waitcnt vmcnt(8)
	s_waitcnt lgkmcnt(0)
	s_setprio 1
	s_barrier
	v_mfma_f32_16x16x32_bf16 v[140:143], v[108:111], v[144:147], v[140:143]
	v_mfma_f32_16x16x32_bf16 v[136:139], v[124:127], v[144:147], v[136:139]
	v_mfma_f32_16x16x32_bf16 v[116:119], v[108:111], v[152:155], v[116:119]
	v_mfma_f32_16x16x32_bf16 v[104:107], v[124:127], v[152:155], v[104:107]
	v_mfma_f32_16x16x32_bf16 v[92:95], v[108:111], v[160:163], v[92:95]
	v_mfma_f32_16x16x32_bf16 v[88:91], v[124:127], v[160:163], v[88:91]
	v_mfma_f32_16x16x32_bf16 v[76:79], v[108:111], v[168:171], v[76:79]
	v_mfma_f32_16x16x32_bf16 v[72:75], v[124:127], v[168:171], v[72:75]
	v_mfma_f32_16x16x32_bf16 v[140:143], v[112:115], v[148:151], v[140:143]
	v_mfma_f32_16x16x32_bf16 v[136:139], v[128:131], v[148:151], v[136:139]
	v_mfma_f32_16x16x32_bf16 v[116:119], v[112:115], v[156:159], v[116:119]
	v_mfma_f32_16x16x32_bf16 v[104:107], v[128:131], v[156:159], v[104:107]
	v_mfma_f32_16x16x32_bf16 v[92:95], v[112:115], v[164:167], v[92:95]
	v_mfma_f32_16x16x32_bf16 v[88:91], v[128:131], v[164:167], v[88:91]
	v_mfma_f32_16x16x32_bf16 v[76:79], v[112:115], v[172:175], v[76:79]
	v_mfma_f32_16x16x32_bf16 v[72:75], v[128:131], v[172:175], v[72:75]
	v_mfma_f32_16x16x32_bf16 v[132:135], v[188:191], v[144:147], v[132:135]
	v_mfma_f32_16x16x32_bf16 v[120:123], v[196:199], v[144:147], v[120:123]
	v_mfma_f32_16x16x32_bf16 v[100:103], v[188:191], v[152:155], v[100:103]
	v_mfma_f32_16x16x32_bf16 v[96:99], v[196:199], v[152:155], v[96:99]
	v_mfma_f32_16x16x32_bf16 v[84:87], v[188:191], v[160:163], v[84:87]
	v_mfma_f32_16x16x32_bf16 v[80:83], v[196:199], v[160:163], v[80:83]
	v_mfma_f32_16x16x32_bf16 v[68:71], v[188:191], v[168:171], v[68:71]
	v_mfma_f32_16x16x32_bf16 v[64:67], v[196:199], v[168:171], v[64:67]
	v_mfma_f32_16x16x32_bf16 v[132:135], v[192:195], v[148:151], v[132:135]
	v_mfma_f32_16x16x32_bf16 v[120:123], v[200:203], v[148:151], v[120:123]
	v_mfma_f32_16x16x32_bf16 v[100:103], v[192:195], v[156:159], v[100:103]
	v_mfma_f32_16x16x32_bf16 v[96:99], v[200:203], v[156:159], v[96:99]
	v_mfma_f32_16x16x32_bf16 v[84:87], v[192:195], v[164:167], v[84:87]
	v_mfma_f32_16x16x32_bf16 v[80:83], v[200:203], v[164:167], v[80:83]
	v_mfma_f32_16x16x32_bf16 v[68:71], v[192:195], v[172:175], v[68:71]
	v_mfma_f32_16x16x32_bf16 v[64:67], v[200:203], v[172:175], v[64:67]
	s_barrier
	s_setprio 0
	ds_read_b128 v[144:147], v248 offset:49152
	ds_read_b128 v[148:151], v248 offset:50176
	ds_read_b128 v[152:155], v248 offset:51200
	ds_read_b128 v[156:159], v248 offset:52224
	ds_read_b128 v[160:163], v248 offset:53248
	ds_read_b128 v[164:167], v248 offset:54272
	ds_read_b128 v[168:171], v248 offset:55296
	ds_read_b128 v[172:175], v248 offset:56320
	s_add_i32 s30, 0, 0x1c000
	s_add_i32 s10, s33, s39
	s_mov_b32 m0, s10
	s_nop 0
	global_load_lds_dwordx4 v178, s[98:99]
	s_add_i32 m0, s10, 0x2000
	s_nop 0
	global_load_lds_dwordx4 v182, s[98:99]
	s_mov_b32 m0, s45
	s_nop 0
	global_load_lds_dwordx4 v176, s[100:101]
	s_mov_b32 m0, s46
	s_nop 0
	global_load_lds_dwordx4 v180, s[100:101]
	s_add_u32 s10, s28, 0x160080
	s_addc_u32 s11, s29, 0
	s_add_i32 s28, s30, s39
	s_mov_b32 m0, s28
	s_nop 0
	global_load_lds_dwordx4 v178, s[10:11]
	s_add_i32 m0, s28, 0x2000
	s_nop 0
	global_load_lds_dwordx4 v182, s[10:11]
	s_waitcnt vmcnt(8)
	s_waitcnt lgkmcnt(0)
	s_setprio 1
	s_barrier
	v_mfma_f32_16x16x32_bf16 v[60:63], v[108:111], v[144:147], v[60:63]
	v_mfma_f32_16x16x32_bf16 v[56:59], v[124:127], v[144:147], v[56:59]
	v_mfma_f32_16x16x32_bf16 v[44:47], v[108:111], v[152:155], v[44:47]
	v_mfma_f32_16x16x32_bf16 v[40:43], v[124:127], v[152:155], v[40:43]
	v_mfma_f32_16x16x32_bf16 v[28:31], v[108:111], v[160:163], v[28:31]
	v_mfma_f32_16x16x32_bf16 v[24:27], v[124:127], v[160:163], v[24:27]
	v_mfma_f32_16x16x32_bf16 v[12:15], v[108:111], v[168:171], v[12:15]
	v_mfma_f32_16x16x32_bf16 v[8:11], v[124:127], v[168:171], v[8:11]
	s_add_i32 s69, s69, 2
	s_add_u32 s26, s26, 0x100
	s_addc_u32 s27, s27, 0
	s_add_u32 s67, s67, 0x100
	s_addc_u32 s68, s68, 0
	s_cmpk_gt_u32 s69, 0x55
	v_mfma_f32_16x16x32_bf16 v[60:63], v[112:115], v[148:151], v[60:63]
	v_mfma_f32_16x16x32_bf16 v[56:59], v[128:131], v[148:151], v[56:59]
	v_mfma_f32_16x16x32_bf16 v[44:47], v[112:115], v[156:159], v[44:47]
	v_mfma_f32_16x16x32_bf16 v[40:43], v[128:131], v[156:159], v[40:43]
	v_mfma_f32_16x16x32_bf16 v[28:31], v[112:115], v[164:167], v[28:31]
	v_mfma_f32_16x16x32_bf16 v[24:27], v[128:131], v[164:167], v[24:27]
	v_mfma_f32_16x16x32_bf16 v[12:15], v[112:115], v[172:175], v[12:15]
	v_mfma_f32_16x16x32_bf16 v[8:11], v[128:131], v[172:175], v[8:11]
	v_mfma_f32_16x16x32_bf16 v[52:55], v[188:191], v[144:147], v[52:55]
	v_mfma_f32_16x16x32_bf16 v[48:51], v[196:199], v[144:147], v[48:51]
	v_mfma_f32_16x16x32_bf16 v[36:39], v[188:191], v[152:155], v[36:39]
	v_mfma_f32_16x16x32_bf16 v[32:35], v[196:199], v[152:155], v[32:35]
	v_mfma_f32_16x16x32_bf16 v[20:23], v[188:191], v[160:163], v[20:23]
	v_mfma_f32_16x16x32_bf16 v[16:19], v[196:199], v[160:163], v[16:19]
	v_mfma_f32_16x16x32_bf16 v[4:7], v[188:191], v[168:171], v[4:7]
	v_mfma_f32_16x16x32_bf16 v[0:3], v[196:199], v[168:171], v[0:3]
	v_mfma_f32_16x16x32_bf16 v[52:55], v[192:195], v[148:151], v[52:55]
	v_mfma_f32_16x16x32_bf16 v[48:51], v[200:203], v[148:151], v[48:51]
	v_mfma_f32_16x16x32_bf16 v[36:39], v[192:195], v[156:159], v[36:39]
	v_mfma_f32_16x16x32_bf16 v[32:35], v[200:203], v[156:159], v[32:35]
	v_mfma_f32_16x16x32_bf16 v[20:23], v[192:195], v[164:167], v[20:23]
	v_mfma_f32_16x16x32_bf16 v[16:19], v[200:203], v[164:167], v[16:19]
	v_mfma_f32_16x16x32_bf16 v[4:7], v[192:195], v[172:175], v[4:7]
	v_mfma_f32_16x16x32_bf16 v[0:3], v[200:203], v[172:175], v[0:3]
	s_barrier
; #define PG8_STAGE(bufoff, gbase, voff) do { _Pragma("unroll") for (int _i = 0; _i < 2; ++_i) \
;         __builtin_amdgcn_global_load_lds((const unsigned*)((const char*)(gbase) + (voff)[_i]), (PG8_LAS unsigned*)(lds + (bufoff) + ldsw + _i * 8192), 16, 0, 0); } while (0)
; #define PG8_LDA(dst, b, h) do { _Pragma("unroll") for (int m = 0; m < 4; ++m) _Pragma("unroll") for (int k = 0; k < 2; ++k) dst[m][k] = *(const PG8_LAS bf16x8*)(lds + PG8_SA(b, h) + aoff + m * 2048 + k * 1024); } while (0)
; #define PG8_LDB(dst, b, h) do { _Pragma("unroll") for (int n = 0; n < 2; ++n) _Pragma("unroll") for (int k = 0; k < 2; ++k) dst[n][k] = *(const PG8_LAS bf16x8*)(lds + PG8_SB(b, h) + boff + n * 2048 + k * 1024); } while (0)
; #define PG8_MMA(ai, bj, At, Bt) do { __builtin_amdgcn_s_setprio(1); _Pragma("unroll") for (int m = 0; m < 4; ++m) _Pragma("unroll") for (int n = 0; n < 2; ++n) _Pragma("unroll") for (int k = 0; k < 2; ++k) \
;         acc[ai][bj][m][n] = __builtin_amdgcn_mfma_f32_16x16x32_bf16(Bt[n][k], At[m][k], acc[ai][bj][m][n], 0, 0, 0); __builtin_amdgcn_s_setprio(0); } while (0)
; #define PG8_WAIT_V(n) asm volatile("s_waitcnt vmcnt(" #n ")" ::: "memory")
; #define PG8_WAIT_L(n) asm volatile("s_waitcnt lgkmcnt(" #n ")" ::: "memory")
; #define PG8_BAR __builtin_amdgcn_s_barrier()
; #define PG8_SCHED __builtin_amdgcn_sched_barrier(0)
; template <class Epi, class Sched>
; __device__ __forceinline__ void gemm_phase(PG8_LAS unsigned char* lds, const Gemm g, const Sched& S, const Epi& E) {
;     ...
;             PG8_LDB(B0, 0, 0); PG8_SCHED; PG8_LDA(At, 0, 0); PG8_STAGE(PG8_SA(1, 1), a1 + hstep, voffA);
;             PG8_WAIT_L(8); PG8_BAR; PG8_WAIT_L(0); PG8_MMA(0, 0, At, B0); PG8_BAR; PG8_SCHED;
;             PG8_LDB(B1, 0, 1); PG8_STAGE(PG8_SB(0, 0), b2, voffB);
;             PG8_BAR; PG8_WAIT_L(0); PG8_MMA(0, 1, At, B1); PG8_BAR;
;             PG8_LDA(At, 0, 1); PG8_STAGE(PG8_SA(0, 0), a2, voffA);
;             PG8_BAR; PG8_WAIT_L(0); PG8_MMA(1, 0, At, B0); PG8_BAR; PG8_SCHED;
;             PG8_STAGE(PG8_SB(0, 1), b2 + hstep, voffB);
;             PG8_WAIT_V(6); PG8_BAR; PG8_MMA(1, 1, At, B1); PG8_BAR;
;             PG8_LDB(B0, 1, 0); PG8_SCHED; PG8_LDA(At, 1, 0); PG8_STAGE(PG8_SA(0, 1), a2 + hstep, voffA);
;             PG8_WAIT_L(8); PG8_BAR; PG8_WAIT_L(0); PG8_MMA(0, 0, At, B0); PG8_BAR; PG8_SCHED;
.LBB0_882:
	s_setprio 0
	ds_read_b128 v[108:111], v247
	ds_read_b128 v[112:115], v247 offset:1024
	ds_read_b128 v[124:127], v247 offset:2048
	ds_read_b128 v[128:131], v247 offset:3072
	ds_read_b128 v[144:147], v248
	ds_read_b128 v[148:151], v248 offset:1024
	ds_read_b128 v[152:155], v248 offset:2048
	ds_read_b128 v[156:159], v248 offset:3072
	ds_read_b128 v[160:163], v248 offset:4096
	ds_read_b128 v[164:167], v248 offset:5120
	ds_read_b128 v[168:171], v248 offset:6144
	ds_read_b128 v[172:175], v248 offset:7168
	s_waitcnt lgkmcnt(11)
	ds_read_b128 v[188:191], v249
	ds_read_b128 v[192:195], v249 offset:1024
	ds_read_b128 v[196:199], v249 offset:2048
	ds_read_b128 v[200:203], v249 offset:3072
	s_add_u32 s10, s26, 0xffea0080
	s_addc_u32 s11, s27, -1
	s_cmpk_eq_i32 s69, 0x54
	s_cselect_b32 s31, s1, s11
	s_cselect_b32 s30, s0, s10
	s_cselect_b32 s29, s5, s68
	s_cselect_b32 s28, s4, s67
	s_add_u32 s98, s28, s18
	s_addc_u32 s99, s29, s19
	s_add_u32 s100, s30, s18
	s_addc_u32 s101, s31, s19
	s_add_i32 m0, s40, 0xc000
	s_nop 0
	global_load_lds_dwordx4 v184, s[26:27]
	s_add_i32 m0, s40, 0xe000
	s_nop 0
	global_load_lds_dwordx4 v186, s[26:27]
	s_waitcnt vmcnt(8)
	s_waitcnt lgkmcnt(0)
	s_setprio 1
	s_barrier
	v_mfma_f32_16x16x32_bf16 v[140:143], v[108:111], v[144:147], v[140:143]
	v_mfma_f32_16x16x32_bf16 v[136:139], v[124:127], v[144:147], v[136:139]
	v_mfma_f32_16x16x32_bf16 v[116:119], v[108:111], v[152:155], v[116:119]
	v_mfma_f32_16x16x32_bf16 v[104:107], v[124:127], v[152:155], v[104:107]
	v_mfma_f32_16x16x32_bf16 v[92:95], v[108:111], v[160:163], v[92:95]
	v_mfma_f32_16x16x32_bf16 v[88:91], v[124:127], v[160:163], v[88:91]
	v_mfma_f32_16x16x32_bf16 v[76:79], v[108:111], v[168:171], v[76:79]
	v_mfma_f32_16x16x32_bf16 v[72:75], v[124:127], v[168:171], v[72:75]
	v_mfma_f32_16x16x32_bf16 v[140:143], v[112:115], v[148:151], v[140:143]
	v_mfma_f32_16x16x32_bf16 v[136:139], v[128:131], v[148:151], v[136:139]
	v_mfma_f32_16x16x32_bf16 v[116:119], v[112:115], v[156:159], v[116:119]
	v_mfma_f32_16x16x32_bf16 v[104:107], v[128:131], v[156:159], v[104:107]
	v_mfma_f32_16x16x32_bf16 v[92:95], v[112:115], v[164:167], v[92:95]
	v_mfma_f32_16x16x32_bf16 v[88:91], v[128:131], v[164:167], v[88:91]
	v_mfma_f32_16x16x32_bf16 v[76:79], v[112:115], v[172:175], v[76:79]
	v_mfma_f32_16x16x32_bf16 v[72:75], v[128:131], v[172:175], v[72:75]
	v_mfma_f32_16x16x32_bf16 v[132:135], v[188:191], v[144:147], v[132:135]
	v_mfma_f32_16x16x32_bf16 v[120:123], v[196:199], v[144:147], v[120:123]
	v_mfma_f32_16x16x32_bf16 v[100:103], v[188:191], v[152:155], v[100:103]
	v_mfma_f32_16x16x32_bf16 v[96:99], v[196:199], v[152:155], v[96:99]
	v_mfma_f32_16x16x32_bf16 v[84:87], v[188:191], v[160:163], v[84:87]
	v_mfma_f32_16x16x32_bf16 v[80:83], v[196:199], v[160:163], v[80:83]
	v_mfma_f32_16x16x32_bf16 v[68:71], v[188:191], v[168:171], v[68:71]
	v_mfma_f32_16x16x32_bf16 v[64:67], v[196:199], v[168:171], v[64:67]
	v_mfma_f32_16x16x32_bf16 v[132:135], v[192:195], v[148:151], v[132:135]
	v_mfma_f32_16x16x32_bf16 v[120:123], v[200:203], v[148:151], v[120:123]
	v_mfma_f32_16x16x32_bf16 v[100:103], v[192:195], v[156:159], v[100:103]
	v_mfma_f32_16x16x32_bf16 v[96:99], v[200:203], v[156:159], v[96:99]
	v_mfma_f32_16x16x32_bf16 v[84:87], v[192:195], v[164:167], v[84:87]
	v_mfma_f32_16x16x32_bf16 v[80:83], v[200:203], v[164:167], v[80:83]
	v_mfma_f32_16x16x32_bf16 v[68:71], v[192:195], v[172:175], v[68:71]
	v_mfma_f32_16x16x32_bf16 v[64:67], v[200:203], v[172:175], v[64:67]
	s_barrier
	s_setprio 0
	ds_read_b128 v[144:147], v248 offset:16384
	ds_read_b128 v[148:151], v248 offset:17408
	ds_read_b128 v[152:155], v248 offset:18432
	ds_read_b128 v[156:159], v248 offset:19456
	ds_read_b128 v[160:163], v248 offset:20480
	ds_read_b128 v[164:167], v248 offset:21504
	ds_read_b128 v[168:171], v248 offset:22528
	ds_read_b128 v[172:175], v248 offset:23552
	s_add_i32 s10, s49, s39
	s_mov_b32 m0, s10
	s_nop 0
	global_load_lds_dwordx4 v178, s[28:29]
	s_add_i32 m0, s10, 0x2000
	s_nop 0
	global_load_lds_dwordx4 v182, s[28:29]
	s_mov_b32 m0, s40
	s_nop 0
	global_load_lds_dwordx4 v176, s[30:31]
	s_mov_b32 m0, s41
	s_nop 0
	global_load_lds_dwordx4 v180, s[30:31]
	s_add_u32 s10, s28, 0x160000
	s_addc_u32 s11, s29, 0
	s_add_i32 s33, s50, s39
	s_mov_b32 m0, s33
	s_nop 0
	global_load_lds_dwordx4 v178, s[10:11]
	s_add_i32 m0, s33, 0x2000
	s_nop 0
	global_load_lds_dwordx4 v182, s[10:11]
	s_waitcnt vmcnt(8)
	s_waitcnt lgkmcnt(0)
	s_setprio 1
	s_barrier
	v_mfma_f32_16x16x32_bf16 v[60:63], v[108:111], v[144:147], v[60:63]
	v_mfma_f32_16x16x32_bf16 v[56:59], v[124:127], v[144:147], v[56:59]
	v_mfma_f32_16x16x32_bf16 v[44:47], v[108:111], v[152:155], v[44:47]
	v_mfma_f32_16x16x32_bf16 v[40:43], v[124:127], v[152:155], v[40:43]
	v_mfma_f32_16x16x32_bf16 v[28:31], v[108:111], v[160:163], v[28:31]
	v_mfma_f32_16x16x32_bf16 v[24:27], v[124:127], v[160:163], v[24:27]
	v_mfma_f32_16x16x32_bf16 v[12:15], v[108:111], v[168:171], v[12:15]
	v_mfma_f32_16x16x32_bf16 v[8:11], v[124:127], v[168:171], v[8:11]
	s_add_i32 s33, 0, 0x18000
	v_mfma_f32_16x16x32_bf16 v[60:63], v[112:115], v[148:151], v[60:63]
	v_mfma_f32_16x16x32_bf16 v[56:59], v[128:131], v[148:151], v[56:59]
	v_mfma_f32_16x16x32_bf16 v[44:47], v[112:115], v[156:159], v[44:47]
	v_mfma_f32_16x16x32_bf16 v[40:43], v[128:131], v[156:159], v[40:43]
	v_mfma_f32_16x16x32_bf16 v[28:31], v[112:115], v[164:167], v[28:31]
	v_mfma_f32_16x16x32_bf16 v[24:27], v[128:131], v[164:167], v[24:27]
	v_mfma_f32_16x16x32_bf16 v[12:15], v[112:115], v[172:175], v[12:15]
	v_mfma_f32_16x16x32_bf16 v[8:11], v[128:131], v[172:175], v[8:11]
	v_mfma_f32_16x16x32_bf16 v[52:55], v[188:191], v[144:147], v[52:55]
	v_mfma_f32_16x16x32_bf16 v[48:51], v[196:199], v[144:147], v[48:51]
	v_mfma_f32_16x16x32_bf16 v[36:39], v[188:191], v[152:155], v[36:39]
	v_mfma_f32_16x16x32_bf16 v[32:35], v[196:199], v[152:155], v[32:35]
	v_mfma_f32_16x16x32_bf16 v[20:23], v[188:191], v[160:163], v[20:23]
	v_mfma_f32_16x16x32_bf16 v[16:19], v[196:199], v[160:163], v[16:19]
	v_mfma_f32_16x16x32_bf16 v[4:7], v[188:191], v[168:171], v[4:7]
	v_mfma_f32_16x16x32_bf16 v[0:3], v[196:199], v[168:171], v[0:3]
	v_mfma_f32_16x16x32_bf16 v[52:55], v[192:195], v[148:151], v[52:55]
	v_mfma_f32_16x16x32_bf16 v[48:51], v[200:203], v[148:151], v[48:51]
	v_mfma_f32_16x16x32_bf16 v[36:39], v[192:195], v[156:159], v[36:39]
	v_mfma_f32_16x16x32_bf16 v[32:35], v[200:203], v[156:159], v[32:35]
	v_mfma_f32_16x16x32_bf16 v[20:23], v[192:195], v[164:167], v[20:23]
	v_mfma_f32_16x16x32_bf16 v[16:19], v[200:203], v[164:167], v[16:19]
	v_mfma_f32_16x16x32_bf16 v[4:7], v[192:195], v[172:175], v[4:7]
	v_mfma_f32_16x16x32_bf16 v[0:3], v[200:203], v[172:175], v[0:3]
	s_barrier
; #define PG8_STAGE(bufoff, gbase, voff) do { _Pragma("unroll") for (int _i = 0; _i < 2; ++_i) \
;         __builtin_amdgcn_global_load_lds((const unsigned*)((const char*)(gbase) + (voff)[_i]), (PG8_LAS unsigned*)(lds + (bufoff) + ldsw + _i * 8192), 16, 0, 0); } while (0)
; #define PG8_LDA(dst, b, h) do { _Pragma("unroll") for (int m = 0; m < 4; ++m) _Pragma("unroll") for (int k = 0; k < 2; ++k) dst[m][k] = *(const PG8_LAS bf16x8*)(lds + PG8_SA(b, h) + aoff + m * 2048 + k * 1024); } while (0)
; #define PG8_LDB(dst, b, h) do { _Pragma("unroll") for (int n = 0; n < 2; ++n) _Pragma("unroll") for (int k = 0; k < 2; ++k) dst[n][k] = *(const PG8_LAS bf16x8*)(lds + PG8_SB(b, h) + boff + n * 2048 + k * 1024); } while (0)
; #define PG8_MMA(ai, bj, At, Bt) do { __builtin_amdgcn_s_setprio(1); _Pragma("unroll") for (int m = 0; m < 4; ++m) _Pragma("unroll") for (int n = 0; n < 2; ++n) _Pragma("unroll") for (int k = 0; k < 2; ++k) \
;         acc[ai][bj][m][n] = __builtin_amdgcn_mfma_f32_16x16x32_bf16(Bt[n][k], At[m][k], acc[ai][bj][m][n], 0, 0, 0); __builtin_amdgcn_s_setprio(0); } while (0)
; #define PG8_WAIT_V(n) asm volatile("s_waitcnt vmcnt(" #n ")" ::: "memory")
; #define PG8_WAIT_L(n) asm volatile("s_waitcnt lgkmcnt(" #n ")" ::: "memory")
; #define PG8_BAR __builtin_amdgcn_s_barrier()
; #define PG8_SCHED __builtin_amdgcn_sched_barrier(0)
; template <class Epi, class Sched>
; __device__ __forceinline__ void gemm_phase(PG8_LAS unsigned char* lds, const Gemm g, const Sched& S, const Epi& E) {
;     ...
;             PG8_WAIT_V(6); PG8_BAR; PG8_MMA(1, 1, At, B1); PG8_BAR;
;             PG8_LDB(B0, 1, 0); PG8_SCHED; PG8_LDA(At, 1, 0); PG8_STAGE(PG8_SA(0, 1), a2 + hstep, voffA);
;             PG8_WAIT_L(8); PG8_BAR; PG8_WAIT_L(0); PG8_MMA(0, 0, At, B0); PG8_BAR; PG8_SCHED;
;             PG8_LDB(B1, 1, 1); PG8_STAGE(PG8_SB(1, 0), b3, voffB);
;             PG8_BAR; PG8_WAIT_L(0); PG8_MMA(0, 1, At, B1); PG8_BAR;
;             PG8_LDA(At, 1, 1); PG8_STAGE(PG8_SA(1, 0), a3, voffA);
;             PG8_BAR; PG8_WAIT_L(0); PG8_MMA(1, 0, At, B0); PG8_BAR; PG8_SCHED;
;             PG8_STAGE(PG8_SB(1, 1), b3 + hstep, voffB);
;             PG8_WAIT_V(6); PG8_BAR; PG8_MMA(1, 1, At, B1); PG8_BAR;
	s_setprio 0
	ds_read_b128 v[108:111], v247 offset:32768
	ds_read_b128 v[112:115], v247 offset:33792
	ds_read_b128 v[124:127], v247 offset:34816
	ds_read_b128 v[128:131], v247 offset:35840
	ds_read_b128 v[144:147], v248 offset:32768
	ds_read_b128 v[148:151], v248 offset:33792
	ds_read_b128 v[152:155], v248 offset:34816
	ds_read_b128 v[156:159], v248 offset:35840
	ds_read_b128 v[160:163], v248 offset:36864
	ds_read_b128 v[164:167], v248 offset:37888
	ds_read_b128 v[168:171], v248 offset:38912
	ds_read_b128 v[172:175], v248 offset:39936
	s_waitcnt lgkmcnt(11)
	ds_read_b128 v[188:191], v249 offset:32768
	ds_read_b128 v[192:195], v249 offset:33792
	ds_read_b128 v[196:199], v249 offset:34816
	ds_read_b128 v[200:203], v249 offset:35840
	s_add_u32 s10, s30, 0x160000
	s_addc_u32 s11, s31, 0
	s_mov_b32 m0, s42
	s_nop 0
	global_load_lds_dwordx4 v176, s[10:11]
	s_mov_b32 m0, s43
	s_nop 0
	global_load_lds_dwordx4 v180, s[10:11]
	s_waitcnt vmcnt(8)
	s_waitcnt lgkmcnt(0)
	s_setprio 1
	s_barrier
	v_mfma_f32_16x16x32_bf16 v[140:143], v[108:111], v[144:147], v[140:143]
	v_mfma_f32_16x16x32_bf16 v[136:139], v[124:127], v[144:147], v[136:139]
	v_mfma_f32_16x16x32_bf16 v[116:119], v[108:111], v[152:155], v[116:119]
	v_mfma_f32_16x16x32_bf16 v[104:107], v[124:127], v[152:155], v[104:107]
	v_mfma_f32_16x16x32_bf16 v[92:95], v[108:111], v[160:163], v[92:95]
	v_mfma_f32_16x16x32_bf16 v[88:91], v[124:127], v[160:163], v[88:91]
	v_mfma_f32_16x16x32_bf16 v[76:79], v[108:111], v[168:171], v[76:79]
	v_mfma_f32_16x16x32_bf16 v[72:75], v[124:127], v[168:171], v[72:75]
	v_mfma_f32_16x16x32_bf16 v[140:143], v[112:115], v[148:151], v[140:143]
	v_mfma_f32_16x16x32_bf16 v[136:139], v[128:131], v[148:151], v[136:139]
	v_mfma_f32_16x16x32_bf16 v[116:119], v[112:115], v[156:159], v[116:119]
	v_mfma_f32_16x16x32_bf16 v[104:107], v[128:131], v[156:159], v[104:107]
	v_mfma_f32_16x16x32_bf16 v[92:95], v[112:115], v[164:167], v[92:95]
	v_mfma_f32_16x16x32_bf16 v[88:91], v[128:131], v[164:167], v[88:91]
	v_mfma_f32_16x16x32_bf16 v[76:79], v[112:115], v[172:175], v[76:79]
	v_mfma_f32_16x16x32_bf16 v[72:75], v[128:131], v[172:175], v[72:75]
	v_mfma_f32_16x16x32_bf16 v[132:135], v[188:191], v[144:147], v[132:135]
	v_mfma_f32_16x16x32_bf16 v[120:123], v[196:199], v[144:147], v[120:123]
	v_mfma_f32_16x16x32_bf16 v[100:103], v[188:191], v[152:155], v[100:103]
	v_mfma_f32_16x16x32_bf16 v[96:99], v[196:199], v[152:155], v[96:99]
	v_mfma_f32_16x16x32_bf16 v[84:87], v[188:191], v[160:163], v[84:87]
	v_mfma_f32_16x16x32_bf16 v[80:83], v[196:199], v[160:163], v[80:83]
	v_mfma_f32_16x16x32_bf16 v[68:71], v[188:191], v[168:171], v[68:71]
	v_mfma_f32_16x16x32_bf16 v[64:67], v[196:199], v[168:171], v[64:67]
	v_mfma_f32_16x16x32_bf16 v[132:135], v[192:195], v[148:151], v[132:135]
	v_mfma_f32_16x16x32_bf16 v[120:123], v[200:203], v[148:151], v[120:123]
	v_mfma_f32_16x16x32_bf16 v[100:103], v[192:195], v[156:159], v[100:103]
	v_mfma_f32_16x16x32_bf16 v[96:99], v[200:203], v[156:159], v[96:99]
	v_mfma_f32_16x16x32_bf16 v[84:87], v[192:195], v[164:167], v[84:87]
	v_mfma_f32_16x16x32_bf16 v[80:83], v[200:203], v[164:167], v[80:83]
	v_mfma_f32_16x16x32_bf16 v[68:71], v[192:195], v[172:175], v[68:71]
	v_mfma_f32_16x16x32_bf16 v[64:67], v[200:203], v[172:175], v[64:67]
	s_barrier
	s_setprio 0
	ds_read_b128 v[144:147], v248 offset:49152
	ds_read_b128 v[148:151], v248 offset:50176
	ds_read_b128 v[152:155], v248 offset:51200
	ds_read_b128 v[156:159], v248 offset:52224
	ds_read_b128 v[160:163], v248 offset:53248
	ds_read_b128 v[164:167], v248 offset:54272
	ds_read_b128 v[168:171], v248 offset:55296
	ds_read_b128 v[172:175], v248 offset:56320
	s_add_i32 s30, 0, 0x1c000
	s_add_i32 s10, s33, s39
	s_mov_b32 m0, s10
	s_nop 0
	global_load_lds_dwordx4 v178, s[98:99]
	s_add_i32 m0, s10, 0x2000
	s_nop 0
	global_load_lds_dwordx4 v182, s[98:99]
	s_mov_b32 m0, s45
	s_nop 0
	global_load_lds_dwordx4 v176, s[100:101]
	s_mov_b32 m0, s46
	s_nop 0
	global_load_lds_dwordx4 v180, s[100:101]
	s_add_u32 s10, s28, 0x160080
	s_addc_u32 s11, s29, 0
	s_add_i32 s28, s30, s39
	s_mov_b32 m0, s28
	s_nop 0
	global_load_lds_dwordx4 v178, s[10:11]
	s_add_i32 m0, s28, 0x2000
	s_nop 0
	global_load_lds_dwordx4 v182, s[10:11]
	s_waitcnt vmcnt(8)
	s_waitcnt lgkmcnt(0)
	s_setprio 1
	s_barrier
	v_mfma_f32_16x16x32_bf16 v[60:63], v[108:111], v[144:147], v[60:63]
	v_mfma_f32_16x16x32_bf16 v[56:59], v[124:127], v[144:147], v[56:59]
	v_mfma_f32_16x16x32_bf16 v[44:47], v[108:111], v[152:155], v[44:47]
	v_mfma_f32_16x16x32_bf16 v[40:43], v[124:127], v[152:155], v[40:43]
	v_mfma_f32_16x16x32_bf16 v[28:31], v[108:111], v[160:163], v[28:31]
	v_mfma_f32_16x16x32_bf16 v[24:27], v[124:127], v[160:163], v[24:27]
	v_mfma_f32_16x16x32_bf16 v[12:15], v[108:111], v[168:171], v[12:15]
	v_mfma_f32_16x16x32_bf16 v[8:11], v[124:127], v[168:171], v[8:11]
	s_add_i32 s69, s69, 2
	s_add_u32 s26, s26, 0x100
	s_addc_u32 s27, s27, 0
	s_add_u32 s67, s67, 0x100
	s_addc_u32 s68, s68, 0
	s_cmpk_gt_u32 s69, 0x55
	v_mfma_f32_16x16x32_bf16 v[60:63], v[112:115], v[148:151], v[60:63]
	v_mfma_f32_16x16x32_bf16 v[56:59], v[128:131], v[148:151], v[56:59]
	v_mfma_f32_16x16x32_bf16 v[44:47], v[112:115], v[156:159], v[44:47]
	v_mfma_f32_16x16x32_bf16 v[40:43], v[128:131], v[156:159], v[40:43]
	v_mfma_f32_16x16x32_bf16 v[28:31], v[112:115], v[164:167], v[28:31]
	v_mfma_f32_16x16x32_bf16 v[24:27], v[128:131], v[164:167], v[24:27]
	v_mfma_f32_16x16x32_bf16 v[12:15], v[112:115], v[172:175], v[12:15]
	v_mfma_f32_16x16x32_bf16 v[8:11], v[128:131], v[172:175], v[8:11]
	v_mfma_f32_16x16x32_bf16 v[52:55], v[188:191], v[144:147], v[52:55]
	v_mfma_f32_16x16x32_bf16 v[48:51], v[196:199], v[144:147], v[48:51]
	v_mfma_f32_16x16x32_bf16 v[36:39], v[188:191], v[152:155], v[36:39]
	v_mfma_f32_16x16x32_bf16 v[32:35], v[196:199], v[152:155], v[32:35]
	v_mfma_f32_16x16x32_bf16 v[20:23], v[188:191], v[160:163], v[20:23]
	v_mfma_f32_16x16x32_bf16 v[16:19], v[196:199], v[160:163], v[16:19]
	v_mfma_f32_16x16x32_bf16 v[4:7], v[188:191], v[168:171], v[4:7]
	v_mfma_f32_16x16x32_bf16 v[0:3], v[196:199], v[168:171], v[0:3]
	v_mfma_f32_16x16x32_bf16 v[52:55], v[192:195], v[148:151], v[52:55]
	v_mfma_f32_16x16x32_bf16 v[48:51], v[200:203], v[148:151], v[48:51]
	v_mfma_f32_16x16x32_bf16 v[36:39], v[192:195], v[156:159], v[36:39]
	v_mfma_f32_16x16x32_bf16 v[32:35], v[200:203], v[156:159], v[32:35]
	v_mfma_f32_16x16x32_bf16 v[20:23], v[192:195], v[164:167], v[20:23]
	v_mfma_f32_16x16x32_bf16 v[16:19], v[200:203], v[164:167], v[16:19]
	v_mfma_f32_16x16x32_bf16 v[4:7], v[192:195], v[172:175], v[4:7]
	v_mfma_f32_16x16x32_bf16 v[0:3], v[200:203], v[172:175], v[0:3]
	s_barrier
;     __device__ __forceinline__ void operator()(const AccT& acc, const pg8::Unit& u, int wr, int wc, int fr, int fq) const {
;         const int row0 = u.pm * 256 + wr * 64 + fr, col0 = u.pn * 256 + wc * 32 + 8 * fq;
;         const float* ga = mod + (u.pm >= 64 ? 12288 : 0) + 5 * 2048;
;         f32x4 gv[2][2], lg[2][2], lbv[2][2];
; #pragma unroll
;         for (int bj = 0; bj < 2; ++bj)
; #pragma unroll
;             for (int n = 0; n < 2; ++n) { const int c = col0 + bj * 128 + n * 4; gv[bj][n] = *(const f32x4*)(ga + c); lg[bj][n] = ALPHA * *(const f32x4*)(g1 + c); lbv[bj][n] = ALPHA * *(const f32x4*)(b1 + c); }
; #pragma unroll
;         for (int ai = 0; ai < 2; ++ai) {
;             u32x4 uraw[4][2]; f32x2 stv[4];
; #pragma unroll
;             for (int m = 0; m < 4; ++m) { const int row = row0 + ai * 128 + m * 16; const size_t off = (size_t)row * D + col0; stv[m] = *(const f32x2*)(stats + 2 * row);
; #pragma unroll
;                 for (int bj = 0; bj < 2; ++bj) uraw[m][bj] = *(const u32x4*)(U1 + off + bj * 128); }
; #pragma unroll
;             for (int m = 0; m < 4; ++m) { const int row = row0 + ai * 128 + m * 16; const size_t off = (size_t)row * D + col0; const f32x2 st = stv[m];
; #pragma unroll
;                 for (int bj = 0; bj < 2; ++bj) { float uf[8]; unpack_h8(uraw[m][bj], uf);
;                     const f32x4 ua = {uf[0], uf[1], uf[2], uf[3]}, ub = {uf[4], uf[5], uf[6], uf[7]};
;                     const f32x4 a = ((ua - st.x) * st.y) * lg[bj][0] + lbv[bj][0] + gv[bj][0] * acc[ai][bj][m][0], b = ((ub - st.x) * st.y) * lg[bj][1] + lbv[bj][1] + gv[bj][1] * acc[ai][bj][m][1];
;                     u32x4 w; w.x = pk_h2(a[0], a[1]); w.y = pk_h2(a[2], a[3]); w.z = pk_h2(b[0], b[1]); w.w = pk_h2(b[2], b[3]);
;                     *(u32x4*)(U2 + off + bj * 128) = w; } }
	s_cbranch_scc0 .LBB0_882
	s_setprio 0
	s_cmp_gt_i32 s65, 63
	s_cselect_b32 s10, 0xc000, 0
	s_add_u32 s10, s58, s10
	v_lshl_or_b32 v156, s66, 8, v246
	s_addc_u32 s11, s59, 0
	s_add_u32 s10, s10, 0x6a0a000
	v_ashrrev_i32_e32 v157, 31, v156
	s_addc_u32 s11, s11, 0
	v_lshlrev_b64 v[144:145], 2, v[156:157]
	v_lshl_add_u64 v[108:109], s[10:11], 0, v[144:145]
	v_lshl_add_u64 v[148:149], s[22:23], 0, v[144:145]
	global_load_dwordx4 v[112:115], v[108:109], off offset:16
	global_load_dwordx4 v[128:131], v[108:109], off
	s_nop 0
	global_load_dwordx4 v[108:111], v[148:149], off offset:16
	global_load_dwordx4 v[124:127], v[148:149], off
	v_lshl_add_u64 v[152:153], s[24:25], 0, v[144:145]
	v_lshl_add_u32 v224, s65, 8, v244
	v_lshlrev_b64 v[220:221], 1, v[156:157]
	v_ashrrev_i32_e32 v225, 31, v224
	v_lshl_add_u64 v[222:223], s[6:7], 0, v[220:221]
	v_lshlrev_b64 v[240:241], 12, v[224:225]
	s_and_b64 vcc, exec, s[2:3]
	s_mov_b32 s66, s51
	s_mov_b32 s65, s64
	s_mov_b64 s[28:29], s[4:5]
	s_mov_b64 s[26:27], s[0:1]
	s_waitcnt vmcnt(0)
	v_pk_mul_f32 v[210:211], v[108:109], s[20:21] op_sel_hi:[1,0]
	v_pk_mul_f32 v[204:205], v[126:127], s[20:21] op_sel_hi:[1,0]
	v_pk_mul_f32 v[206:207], v[124:125], s[20:21] op_sel_hi:[1,0]
	global_load_dwordx4 v[124:127], v[152:153], off offset:16
	global_load_dwordx4 v[144:147], v[152:153], off
	v_or_b32_e32 v108, 0x80, v156
	v_ashrrev_i32_e32 v109, 31, v108
	v_pk_mul_f32 v[208:209], v[110:111], s[20:21] op_sel_hi:[1,0]
	v_or_b32_e32 v156, 48, v224
	v_ashrrev_i32_e32 v157, 31, v156
	v_lshlrev_b32_e32 v158, 1, v156
	v_ashrrev_i32_e32 v159, 31, v158
	v_lshlrev_b64 v[232:233], 12, v[156:157]
	v_lshl_add_u64 v[158:159], v[158:159], 2, s[8:9]
	v_lshl_add_u64 v[156:157], v[222:223], 0, v[232:233]
	s_waitcnt vmcnt(0)
	v_pk_mul_f32 v[214:215], v[124:125], s[20:21] op_sel_hi:[1,0]
	v_lshl_add_u64 v[124:125], v[108:109], 2, s[10:11]
	v_pk_mul_f32 v[216:217], v[146:147], s[20:21] op_sel_hi:[1,0]
	v_pk_mul_f32 v[218:219], v[144:145], s[20:21] op_sel_hi:[1,0]
	v_pk_mul_f32 v[212:213], v[126:127], s[20:21] op_sel_hi:[1,0]
	global_load_dwordx4 v[108:111], v[124:125], off offset:16
	s_nop 0
	global_load_dwordx4 v[124:127], v[124:125], off
	s_nop 0
	global_load_dwordx4 v[144:147], v[148:149], off offset:528
	s_nop 0
	global_load_dwordx4 v[148:151], v[148:149], off offset:512
	s_waitcnt vmcnt(0)
	v_pk_mul_f32 v[190:191], v[144:145], s[20:21] op_sel_hi:[1,0]
	v_pk_mul_f32 v[196:197], v[150:151], s[20:21] op_sel_hi:[1,0]
	v_pk_mul_f32 v[198:199], v[148:149], s[20:21] op_sel_hi:[1,0]
	global_load_dwordx4 v[148:151], v[152:153], off offset:528
	s_nop 0
	global_load_dwordx4 v[152:155], v[152:153], off offset:512
	v_lshlrev_b32_e32 v144, 1, v224
	v_ashrrev_i32_e32 v145, 31, v144
	v_lshl_add_u64 v[144:145], v[144:145], 2, s[8:9]
	global_load_dwordx2 v[234:235], v[144:145], off
	v_lshl_add_u64 v[144:145], v[222:223], 0, v[240:241]
	global_load_dwordx4 v[172:175], v[144:145], off
	global_load_dwordx4 v[160:163], v[144:145], off offset:256
	v_or_b32_e32 v144, 16, v224
	v_pk_mul_f32 v[188:189], v[146:147], s[20:21] op_sel_hi:[1,0]
	v_ashrrev_i32_e32 v145, 31, v144
	v_lshlrev_b32_e32 v146, 1, v144
	v_ashrrev_i32_e32 v147, 31, v146
	v_lshlrev_b64 v[238:239], 12, v[144:145]
	v_lshl_add_u64 v[146:147], v[146:147], 2, s[8:9]
	v_lshl_add_u64 v[144:145], v[222:223], 0, v[238:239]
	global_load_dwordx2 v[236:237], v[146:147], off
	s_waitcnt vmcnt(0)
	v_pk_mul_f32 v[192:193], v[150:151], s[20:21] op_sel_hi:[1,0]
	v_pk_mul_f32 v[194:195], v[148:149], s[20:21] op_sel_hi:[1,0]
	global_load_dwordx4 v[164:167], v[144:145], off
	global_load_dwordx4 v[148:151], v[144:145], off offset:256
	v_or_b32_e32 v144, 32, v224
	v_ashrrev_i32_e32 v145, 31, v144
	v_lshlrev_b32_e32 v146, 1, v144
	v_ashrrev_i32_e32 v147, 31, v146
	v_lshlrev_b64 v[230:231], 12, v[144:145]
	v_lshl_add_u64 v[146:147], v[146:147], 2, s[8:9]
	v_lshl_add_u64 v[144:145], v[222:223], 0, v[230:231]
	v_pk_mul_f32 v[200:201], v[154:155], s[20:21] op_sel_hi:[1,0]
	v_pk_mul_f32 v[202:203], v[152:153], s[20:21] op_sel_hi:[1,0]
	global_load_dwordx2 v[228:229], v[146:147], off
	global_load_dwordx4 v[152:155], v[144:145], off
	s_nop 0
	global_load_dwordx4 v[144:147], v[144:145], off offset:256
	v_cvt_f32_f16_sdwa v225, v172 dst_sel:DWORD dst_unused:UNUSED_PAD src0_sel:WORD_1
	global_load_dwordx2 v[226:227], v[158:159], off
	global_load_dwordx4 v[168:171], v[156:157], off
	s_nop 0
	global_load_dwordx4 v[156:159], v[156:157], off offset:256
	v_cvt_f32_f16_e32 v172, v172
	v_cvt_f32_f16_sdwa v250, v173 dst_sel:DWORD dst_unused:UNUSED_PAD src0_sel:WORD_1
	v_cvt_f32_f16_e32 v251, v173
	v_cvt_f32_f16_sdwa v252, v174 dst_sel:DWORD dst_unused:UNUSED_PAD src0_sel:WORD_1
	v_cvt_f32_f16_e32 v253, v174
	v_cvt_f32_f16_sdwa v254, v175 dst_sel:DWORD dst_unused:UNUSED_PAD src0_sel:WORD_1
	v_cvt_f32_f16_e32 v243, v175
	v_sub_f32_e32 v172, v172, v234
	v_sub_f32_e32 v173, v225, v234
	v_sub_f32_e32 v174, v251, v234
	v_sub_f32_e32 v175, v250, v234
	v_pk_mul_f32 v[174:175], v[234:235], v[174:175] op_sel:[1,0]
	v_pk_mul_f32 v[172:173], v[234:235], v[172:173] op_sel:[1,0]
	v_pk_fma_f32 v[174:175], v[204:205], v[174:175], v[216:217]
	v_pk_fma_f32 v[172:173], v[206:207], v[172:173], v[218:219]
	v_pk_fma_f32 v[142:143], v[142:143], v[130:131], v[174:175]
	v_pk_fma_f32 v[140:141], v[140:141], v[128:129], v[172:173]
	v_sub_f32_e32 v172, v253, v234
	v_sub_f32_e32 v173, v252, v234
	v_sub_f32_e32 v174, v243, v234
	v_sub_f32_e32 v175, v254, v234
	v_pk_mul_f32 v[174:175], v[234:235], v[174:175] op_sel:[1,0]
	v_pk_mul_f32 v[172:173], v[234:235], v[172:173] op_sel:[1,0]
	v_pk_fma_f32 v[174:175], v[208:209], v[174:175], v[212:213]
;     __device__ __forceinline__ void operator()(const AccT& acc, const pg8::Unit& u, int wr, int wc, int fr, int fq) const {
;     ...
;             for (int m = 0; m < 4; ++m) { const int row = row0 + ai * 128 + m * 16; const size_t off = (size_t)row * D + col0; const f32x2 st = stv[m];
; #pragma unroll
;                 for (int bj = 0; bj < 2; ++bj) { float uf[8]; unpack_h8(uraw[m][bj], uf);
;                     const f32x4 ua = {uf[0], uf[1], uf[2], uf[3]}, ub = {uf[4], uf[5], uf[6], uf[7]};
;                     const f32x4 a = ((ua - st.x) * st.y) * lg[bj][0] + lbv[bj][0] + gv[bj][0] * acc[ai][bj][m][0], b = ((ub - st.x) * st.y) * lg[bj][1] + lbv[bj][1] + gv[bj][1] * acc[ai][bj][m][1];
;                     u32x4 w; w.x = pk_h2(a[0], a[1]); w.y = pk_h2(a[2], a[3]); w.z = pk_h2(b[0], b[1]); w.w = pk_h2(b[2], b[3]);
;                     *(u32x4*)(U2 + off + bj * 128) = w; } }
	v_pk_fma_f32 v[172:173], v[210:211], v[172:173], v[214:215]
	v_pk_fma_f32 v[174:175], v[138:139], v[114:115], v[174:175]
	v_pk_fma_f32 v[138:139], v[136:137], v[112:113], v[172:173]
	v_cvt_pk_f16_f32 v136, v140, v141
	v_lshl_add_u64 v[140:141], s[16:17], 0, v[240:241]
	v_cvt_pk_f16_f32 v137, v142, v143
	v_cvt_pk_f16_f32 v138, v138, v139
	v_cvt_pk_f16_f32 v139, v174, v175
	v_lshl_add_u64 v[140:141], v[140:141], 0, v[220:221]
	global_store_dwordx4 v[140:141], v[136:139], off
	v_cvt_f32_f16_sdwa v142, v162 dst_sel:DWORD dst_unused:UNUSED_PAD src0_sel:WORD_1
	v_cvt_f32_f16_e32 v143, v162
	v_cvt_f32_f16_sdwa v137, v160 dst_sel:DWORD dst_unused:UNUSED_PAD src0_sel:WORD_1
	v_cvt_f32_f16_e32 v136, v160
	v_cvt_f32_f16_sdwa v139, v161 dst_sel:DWORD dst_unused:UNUSED_PAD src0_sel:WORD_1
	v_cvt_f32_f16_e32 v138, v161
	v_cvt_f32_f16_sdwa v160, v163 dst_sel:DWORD dst_unused:UNUSED_PAD src0_sel:WORD_1
	v_cvt_f32_f16_e32 v161, v163
	v_sub_f32_e32 v136, v136, v234
	v_sub_f32_e32 v137, v137, v234
	v_sub_f32_e32 v138, v138, v234
	v_sub_f32_e32 v139, v139, v234
	v_pk_mul_f32 v[138:139], v[234:235], v[138:139] op_sel:[1,0]
	v_pk_mul_f32 v[136:137], v[234:235], v[136:137] op_sel:[1,0]
	v_pk_fma_f32 v[138:139], v[196:197], v[138:139], v[200:201]
	v_pk_fma_f32 v[136:137], v[198:199], v[136:137], v[202:203]
	v_pk_fma_f32 v[134:135], v[134:135], v[126:127], v[138:139]
	v_pk_fma_f32 v[132:133], v[132:133], v[124:125], v[136:137]
	v_sub_f32_e32 v136, v143, v234
	v_sub_f32_e32 v137, v142, v234
	v_sub_f32_e32 v138, v161, v234
	v_sub_f32_e32 v139, v160, v234
	v_pk_mul_f32 v[138:139], v[234:235], v[138:139] op_sel:[1,0]
	v_pk_mul_f32 v[136:137], v[234:235], v[136:137] op_sel:[1,0]
	v_pk_fma_f32 v[138:139], v[188:189], v[138:139], v[192:193]
	v_pk_fma_f32 v[136:137], v[190:191], v[136:137], v[194:195]
	v_pk_fma_f32 v[138:139], v[122:123], v[110:111], v[138:139]
	v_pk_fma_f32 v[122:123], v[120:121], v[108:109], v[136:137]
	v_cvt_pk_f16_f32 v120, v132, v133
	v_cvt_pk_f16_f32 v121, v134, v135
	v_cvt_pk_f16_f32 v122, v122, v123
	v_cvt_pk_f16_f32 v123, v138, v139
	global_store_dwordx4 v[140:141], v[120:123], off offset:256
	s_waitcnt vmcnt(0)
	v_cvt_f32_f16_sdwa v132, v166 dst_sel:DWORD dst_unused:UNUSED_PAD src0_sel:WORD_1
	v_cvt_f32_f16_e32 v133, v166
	v_cvt_f32_f16_sdwa v121, v164 dst_sel:DWORD dst_unused:UNUSED_PAD src0_sel:WORD_1
	v_cvt_f32_f16_e32 v120, v164
	v_cvt_f32_f16_sdwa v123, v165 dst_sel:DWORD dst_unused:UNUSED_PAD src0_sel:WORD_1
	v_cvt_f32_f16_e32 v122, v165
	v_cvt_f32_f16_sdwa v134, v167 dst_sel:DWORD dst_unused:UNUSED_PAD src0_sel:WORD_1
	v_cvt_f32_f16_e32 v135, v167
	v_sub_f32_e32 v120, v120, v236
	v_sub_f32_e32 v121, v121, v236
	v_sub_f32_e32 v122, v122, v236
	v_sub_f32_e32 v123, v123, v236
	v_pk_mul_f32 v[122:123], v[236:237], v[122:123] op_sel:[1,0]
	v_pk_mul_f32 v[120:121], v[236:237], v[120:121] op_sel:[1,0]
	v_pk_fma_f32 v[122:123], v[204:205], v[122:123], v[216:217]
	v_pk_fma_f32 v[120:121], v[206:207], v[120:121], v[218:219]
	v_pk_fma_f32 v[118:119], v[118:119], v[130:131], v[122:123]
	v_pk_fma_f32 v[116:117], v[116:117], v[128:129], v[120:121]
	v_sub_f32_e32 v120, v133, v236
	v_sub_f32_e32 v121, v132, v236
	v_sub_f32_e32 v122, v135, v236
	v_sub_f32_e32 v123, v134, v236
	v_pk_mul_f32 v[122:123], v[236:237], v[122:123] op_sel:[1,0]
	v_pk_mul_f32 v[120:121], v[236:237], v[120:121] op_sel:[1,0]
	v_pk_fma_f32 v[122:123], v[208:209], v[122:123], v[212:213]
	v_pk_fma_f32 v[120:121], v[210:211], v[120:121], v[214:215]
	v_pk_fma_f32 v[122:123], v[106:107], v[114:115], v[122:123]
	v_pk_fma_f32 v[106:107], v[104:105], v[112:113], v[120:121]
	v_cvt_pk_f16_f32 v104, v116, v117
	v_lshl_add_u64 v[116:117], s[16:17], 0, v[238:239]
	v_cvt_pk_f16_f32 v105, v118, v119
	v_cvt_pk_f16_f32 v106, v106, v107
	v_cvt_pk_f16_f32 v107, v122, v123
	v_lshl_add_u64 v[116:117], v[116:117], 0, v[220:221]
	global_store_dwordx4 v[116:117], v[104:107], off
	v_cvt_f32_f16_sdwa v118, v150 dst_sel:DWORD dst_unused:UNUSED_PAD src0_sel:WORD_1
	v_cvt_f32_f16_e32 v119, v150
	v_cvt_f32_f16_sdwa v105, v148 dst_sel:DWORD dst_unused:UNUSED_PAD src0_sel:WORD_1
	v_cvt_f32_f16_e32 v104, v148
	v_cvt_f32_f16_sdwa v107, v149 dst_sel:DWORD dst_unused:UNUSED_PAD src0_sel:WORD_1
	v_cvt_f32_f16_e32 v106, v149
	v_cvt_f32_f16_sdwa v120, v151 dst_sel:DWORD dst_unused:UNUSED_PAD src0_sel:WORD_1
	v_cvt_f32_f16_e32 v121, v151
	v_sub_f32_e32 v104, v104, v236
	v_sub_f32_e32 v105, v105, v236
	v_sub_f32_e32 v106, v106, v236
	v_sub_f32_e32 v107, v107, v236
	v_pk_mul_f32 v[106:107], v[236:237], v[106:107] op_sel:[1,0]
	v_pk_mul_f32 v[104:105], v[236:237], v[104:105] op_sel:[1,0]
	v_pk_fma_f32 v[106:107], v[196:197], v[106:107], v[200:201]
	v_pk_fma_f32 v[104:105], v[198:199], v[104:105], v[202:203]
	v_pk_fma_f32 v[102:103], v[102:103], v[126:127], v[106:107]
	v_pk_fma_f32 v[100:101], v[100:101], v[124:125], v[104:105]
	v_sub_f32_e32 v104, v119, v236
	v_sub_f32_e32 v105, v118, v236
	v_sub_f32_e32 v106, v121, v236
	v_sub_f32_e32 v107, v120, v236
	v_pk_mul_f32 v[106:107], v[236:237], v[106:107] op_sel:[1,0]
	v_pk_mul_f32 v[104:105], v[236:237], v[104:105] op_sel:[1,0]
	v_pk_fma_f32 v[106:107], v[188:189], v[106:107], v[192:193]
	v_pk_fma_f32 v[104:105], v[190:191], v[104:105], v[194:195]
	v_pk_fma_f32 v[106:107], v[98:99], v[110:111], v[106:107]
	v_pk_fma_f32 v[98:99], v[96:97], v[108:109], v[104:105]
	v_cvt_pk_f16_f32 v96, v100, v101
	v_cvt_pk_f16_f32 v97, v102, v103
	v_cvt_pk_f16_f32 v98, v98, v99
	v_cvt_pk_f16_f32 v99, v106, v107
	global_store_dwordx4 v[116:117], v[96:99], off offset:256
	v_cvt_f32_f16_sdwa v100, v154 dst_sel:DWORD dst_unused:UNUSED_PAD src0_sel:WORD_1
	v_cvt_f32_f16_e32 v101, v154
;     __device__ __forceinline__ void operator()(const AccT& acc, const pg8::Unit& u, int wr, int wc, int fr, int fq) const {
;     ...
;             for (int m = 0; m < 4; ++m) { const int row = row0 + ai * 128 + m * 16; const size_t off = (size_t)row * D + col0; const f32x2 st = stv[m];
; #pragma unroll
;                 for (int bj = 0; bj < 2; ++bj) { float uf[8]; unpack_h8(uraw[m][bj], uf);
;                     const f32x4 ua = {uf[0], uf[1], uf[2], uf[3]}, ub = {uf[4], uf[5], uf[6], uf[7]};
;                     const f32x4 a = ((ua - st.x) * st.y) * lg[bj][0] + lbv[bj][0] + gv[bj][0] * acc[ai][bj][m][0], b = ((ub - st.x) * st.y) * lg[bj][1] + lbv[bj][1] + gv[bj][1] * acc[ai][bj][m][1];
;                     u32x4 w; w.x = pk_h2(a[0], a[1]); w.y = pk_h2(a[2], a[3]); w.z = pk_h2(b[0], b[1]); w.w = pk_h2(b[2], b[3]);
;                     *(u32x4*)(U2 + off + bj * 128) = w; } }
	v_cvt_f32_f16_sdwa v97, v152 dst_sel:DWORD dst_unused:UNUSED_PAD src0_sel:WORD_1
	v_cvt_f32_f16_e32 v96, v152
	v_cvt_f32_f16_sdwa v99, v153 dst_sel:DWORD dst_unused:UNUSED_PAD src0_sel:WORD_1
	v_cvt_f32_f16_e32 v98, v153
	v_cvt_f32_f16_sdwa v102, v155 dst_sel:DWORD dst_unused:UNUSED_PAD src0_sel:WORD_1
	v_cvt_f32_f16_e32 v103, v155
	v_sub_f32_e32 v96, v96, v228
	v_sub_f32_e32 v97, v97, v228
	v_sub_f32_e32 v98, v98, v228
	v_sub_f32_e32 v99, v99, v228
	v_pk_mul_f32 v[98:99], v[228:229], v[98:99] op_sel:[1,0]
	v_pk_mul_f32 v[96:97], v[228:229], v[96:97] op_sel:[1,0]
	v_pk_fma_f32 v[98:99], v[204:205], v[98:99], v[216:217]
	v_pk_fma_f32 v[96:97], v[206:207], v[96:97], v[218:219]
	v_pk_fma_f32 v[94:95], v[94:95], v[130:131], v[98:99]
	v_pk_fma_f32 v[92:93], v[92:93], v[128:129], v[96:97]
	v_sub_f32_e32 v96, v101, v228
	v_sub_f32_e32 v97, v100, v228
	v_sub_f32_e32 v98, v103, v228
	v_sub_f32_e32 v99, v102, v228
	v_pk_mul_f32 v[98:99], v[228:229], v[98:99] op_sel:[1,0]
	v_pk_mul_f32 v[96:97], v[228:229], v[96:97] op_sel:[1,0]
	v_pk_fma_f32 v[98:99], v[208:209], v[98:99], v[212:213]
	v_pk_fma_f32 v[96:97], v[210:211], v[96:97], v[214:215]
	v_pk_fma_f32 v[98:99], v[90:91], v[114:115], v[98:99]
	v_pk_fma_f32 v[90:91], v[88:89], v[112:113], v[96:97]
	v_cvt_pk_f16_f32 v88, v92, v93
	v_lshl_add_u64 v[92:93], s[16:17], 0, v[230:231]
	v_cvt_pk_f16_f32 v89, v94, v95
	v_cvt_pk_f16_f32 v90, v90, v91
	v_cvt_pk_f16_f32 v91, v98, v99
	v_lshl_add_u64 v[92:93], v[92:93], 0, v[220:221]
	global_store_dwordx4 v[92:93], v[88:91], off
	v_cvt_f32_f16_sdwa v94, v146 dst_sel:DWORD dst_unused:UNUSED_PAD src0_sel:WORD_1
	v_cvt_f32_f16_e32 v95, v146
	v_cvt_f32_f16_sdwa v89, v144 dst_sel:DWORD dst_unused:UNUSED_PAD src0_sel:WORD_1
	v_cvt_f32_f16_e32 v88, v144
	v_cvt_f32_f16_sdwa v91, v145 dst_sel:DWORD dst_unused:UNUSED_PAD src0_sel:WORD_1
	v_cvt_f32_f16_e32 v90, v145
	v_cvt_f32_f16_sdwa v96, v147 dst_sel:DWORD dst_unused:UNUSED_PAD src0_sel:WORD_1
	v_cvt_f32_f16_e32 v97, v147
	v_sub_f32_e32 v88, v88, v228
	v_sub_f32_e32 v89, v89, v228
	v_sub_f32_e32 v90, v90, v228
	v_sub_f32_e32 v91, v91, v228
	v_pk_mul_f32 v[90:91], v[228:229], v[90:91] op_sel:[1,0]
	v_pk_mul_f32 v[88:89], v[228:229], v[88:89] op_sel:[1,0]
	v_pk_fma_f32 v[90:91], v[196:197], v[90:91], v[200:201]
	v_pk_fma_f32 v[88:89], v[198:199], v[88:89], v[202:203]
	v_pk_fma_f32 v[86:87], v[86:87], v[126:127], v[90:91]
	v_pk_fma_f32 v[84:85], v[84:85], v[124:125], v[88:89]
	v_sub_f32_e32 v88, v95, v228
	v_sub_f32_e32 v89, v94, v228
	v_sub_f32_e32 v90, v97, v228
	v_sub_f32_e32 v91, v96, v228
	v_pk_mul_f32 v[90:91], v[228:229], v[90:91] op_sel:[1,0]
	v_pk_mul_f32 v[88:89], v[228:229], v[88:89] op_sel:[1,0]
	v_pk_fma_f32 v[90:91], v[188:189], v[90:91], v[192:193]
	v_pk_fma_f32 v[88:89], v[190:191], v[88:89], v[194:195]
	v_pk_fma_f32 v[90:91], v[82:83], v[110:111], v[90:91]
	v_pk_fma_f32 v[82:83], v[80:81], v[108:109], v[88:89]
	v_cvt_pk_f16_f32 v80, v84, v85
	v_cvt_pk_f16_f32 v81, v86, v87
	v_cvt_pk_f16_f32 v82, v82, v83
	v_cvt_pk_f16_f32 v83, v90, v91
	global_store_dwordx4 v[92:93], v[80:83], off offset:256
	v_cvt_f32_f16_sdwa v84, v170 dst_sel:DWORD dst_unused:UNUSED_PAD src0_sel:WORD_1
	v_cvt_f32_f16_e32 v85, v170
	v_cvt_f32_f16_sdwa v81, v168 dst_sel:DWORD dst_unused:UNUSED_PAD src0_sel:WORD_1
	v_cvt_f32_f16_e32 v80, v168
	v_cvt_f32_f16_sdwa v83, v169 dst_sel:DWORD dst_unused:UNUSED_PAD src0_sel:WORD_1
	v_cvt_f32_f16_e32 v82, v169
	v_cvt_f32_f16_sdwa v86, v171 dst_sel:DWORD dst_unused:UNUSED_PAD src0_sel:WORD_1
	v_cvt_f32_f16_e32 v87, v171
	v_sub_f32_e32 v80, v80, v226
	v_sub_f32_e32 v81, v81, v226
	v_sub_f32_e32 v82, v82, v226
	v_sub_f32_e32 v83, v83, v226
	v_pk_mul_f32 v[82:83], v[226:227], v[82:83] op_sel:[1,0]
	v_pk_mul_f32 v[80:81], v[226:227], v[80:81] op_sel:[1,0]
	v_pk_fma_f32 v[82:83], v[204:205], v[82:83], v[216:217]
	v_pk_fma_f32 v[80:81], v[206:207], v[80:81], v[218:219]
	v_pk_fma_f32 v[78:79], v[78:79], v[130:131], v[82:83]
	v_pk_fma_f32 v[76:77], v[76:77], v[128:129], v[80:81]
	v_sub_f32_e32 v80, v85, v226
	v_sub_f32_e32 v81, v84, v226
	v_sub_f32_e32 v82, v87, v226
	v_sub_f32_e32 v83, v86, v226
	v_pk_mul_f32 v[82:83], v[226:227], v[82:83] op_sel:[1,0]
	v_pk_mul_f32 v[80:81], v[226:227], v[80:81] op_sel:[1,0]
	v_pk_fma_f32 v[82:83], v[208:209], v[82:83], v[212:213]
	v_pk_fma_f32 v[80:81], v[210:211], v[80:81], v[214:215]
	v_pk_fma_f32 v[82:83], v[74:75], v[114:115], v[82:83]
	v_pk_fma_f32 v[74:75], v[72:73], v[112:113], v[80:81]
	v_cvt_pk_f16_f32 v72, v76, v77
	v_lshl_add_u64 v[76:77], s[16:17], 0, v[232:233]
	v_cvt_pk_f16_f32 v73, v78, v79
	v_cvt_pk_f16_f32 v74, v74, v75
	v_cvt_pk_f16_f32 v75, v82, v83
	v_lshl_add_u64 v[76:77], v[76:77], 0, v[220:221]
	global_store_dwordx4 v[76:77], v[72:75], off
	v_cvt_f32_f16_sdwa v78, v158 dst_sel:DWORD dst_unused:UNUSED_PAD src0_sel:WORD_1
	v_cvt_f32_f16_e32 v79, v158
	v_cvt_f32_f16_sdwa v73, v156 dst_sel:DWORD dst_unused:UNUSED_PAD src0_sel:WORD_1
	v_cvt_f32_f16_e32 v72, v156
	v_cvt_f32_f16_sdwa v75, v157 dst_sel:DWORD dst_unused:UNUSED_PAD src0_sel:WORD_1
	v_cvt_f32_f16_e32 v74, v157
	v_cvt_f32_f16_sdwa v80, v159 dst_sel:DWORD dst_unused:UNUSED_PAD src0_sel:WORD_1
	v_cvt_f32_f16_e32 v81, v159
	v_sub_f32_e32 v72, v72, v226
	v_sub_f32_e32 v73, v73, v226
	v_sub_f32_e32 v74, v74, v226
	v_sub_f32_e32 v75, v75, v226
	v_pk_mul_f32 v[74:75], v[226:227], v[74:75] op_sel:[1,0]
	v_pk_mul_f32 v[72:73], v[226:227], v[72:73] op_sel:[1,0]
	v_pk_fma_f32 v[74:75], v[196:197], v[74:75], v[200:201]
	v_pk_fma_f32 v[72:73], v[198:199], v[72:73], v[202:203]
	v_pk_fma_f32 v[70:71], v[70:71], v[126:127], v[74:75]
	v_pk_fma_f32 v[68:69], v[68:69], v[124:125], v[72:73]
	v_sub_f32_e32 v72, v79, v226
;     __device__ __forceinline__ void operator()(const AccT& acc, const pg8::Unit& u, int wr, int wc, int fr, int fq) const {
;     ...
;         for (int ai = 0; ai < 2; ++ai) {
;             u32x4 uraw[4][2]; f32x2 stv[4];
; #pragma unroll
;             for (int m = 0; m < 4; ++m) { const int row = row0 + ai * 128 + m * 16; const size_t off = (size_t)row * D + col0; stv[m] = *(const f32x2*)(stats + 2 * row);
; #pragma unroll
;                 for (int bj = 0; bj < 2; ++bj) uraw[m][bj] = *(const u32x4*)(U1 + off + bj * 128); }
; #pragma unroll
;             for (int m = 0; m < 4; ++m) { const int row = row0 + ai * 128 + m * 16; const size_t off = (size_t)row * D + col0; const f32x2 st = stv[m];
; #pragma unroll
;                 for (int bj = 0; bj < 2; ++bj) { float uf[8]; unpack_h8(uraw[m][bj], uf);
;                     const f32x4 ua = {uf[0], uf[1], uf[2], uf[3]}, ub = {uf[4], uf[5], uf[6], uf[7]};
;                     const f32x4 a = ((ua - st.x) * st.y) * lg[bj][0] + lbv[bj][0] + gv[bj][0] * acc[ai][bj][m][0], b = ((ub - st.x) * st.y) * lg[bj][1] + lbv[bj][1] + gv[bj][1] * acc[ai][bj][m][1];
;                     u32x4 w; w.x = pk_h2(a[0], a[1]); w.y = pk_h2(a[2], a[3]); w.z = pk_h2(b[0], b[1]); w.w = pk_h2(b[2], b[3]);
;                     *(u32x4*)(U2 + off + bj * 128) = w; } }
	v_sub_f32_e32 v73, v78, v226
	v_sub_f32_e32 v74, v81, v226
	v_sub_f32_e32 v75, v80, v226
	v_pk_mul_f32 v[74:75], v[226:227], v[74:75] op_sel:[1,0]
	v_pk_mul_f32 v[72:73], v[226:227], v[72:73] op_sel:[1,0]
	v_pk_fma_f32 v[74:75], v[188:189], v[74:75], v[192:193]
	v_pk_fma_f32 v[72:73], v[190:191], v[72:73], v[194:195]
	v_pk_fma_f32 v[74:75], v[66:67], v[110:111], v[74:75]
	v_pk_fma_f32 v[66:67], v[64:65], v[108:109], v[72:73]
	v_cvt_pk_f16_f32 v64, v68, v69
	v_cvt_pk_f16_f32 v65, v70, v71
	v_cvt_pk_f16_f32 v66, v66, v67
	v_cvt_pk_f16_f32 v67, v74, v75
	global_store_dwordx4 v[76:77], v[64:67], off offset:256
	s_nop 1
	v_add_u32_e32 v64, 0x80, v224
	v_ashrrev_i32_e32 v65, 31, v64
	v_lshlrev_b32_e32 v66, 1, v64
	v_ashrrev_i32_e32 v67, 31, v66
	v_lshlrev_b64 v[106:107], 12, v[64:65]
	v_lshl_add_u64 v[66:67], v[66:67], 2, s[8:9]
	v_lshl_add_u64 v[64:65], v[222:223], 0, v[106:107]
	global_load_dwordx2 v[104:105], v[66:67], off
	global_load_dwordx4 v[84:87], v[64:65], off
	global_load_dwordx4 v[88:91], v[64:65], off offset:256
	v_add_u32_e32 v64, 0x90, v224
	v_ashrrev_i32_e32 v65, 31, v64
	v_lshlrev_b32_e32 v66, 1, v64
	v_ashrrev_i32_e32 v67, 31, v66
	v_lshlrev_b64 v[118:119], 12, v[64:65]
	v_lshl_add_u64 v[66:67], v[66:67], 2, s[8:9]
	v_lshl_add_u64 v[64:65], v[222:223], 0, v[118:119]
	global_load_dwordx2 v[116:117], v[66:67], off
	global_load_dwordx4 v[92:95], v[64:65], off
	global_load_dwordx4 v[96:99], v[64:65], off offset:256
	v_add_u32_e32 v64, 0xa0, v224
	v_ashrrev_i32_e32 v65, 31, v64
	v_lshlrev_b32_e32 v66, 1, v64
	v_ashrrev_i32_e32 v67, 31, v66
	v_lshlrev_b64 v[82:83], 12, v[64:65]
	v_lshl_add_u64 v[66:67], v[66:67], 2, s[8:9]
	v_lshl_add_u64 v[64:65], v[222:223], 0, v[82:83]
	global_load_dwordx2 v[80:81], v[66:67], off
	global_load_dwordx4 v[100:103], v[64:65], off
	global_load_dwordx4 v[72:75], v[64:65], off offset:256
	v_add_u32_e32 v64, 0xb0, v224
	v_ashrrev_i32_e32 v65, 31, v64
	v_lshlrev_b32_e32 v66, 1, v64
	v_ashrrev_i32_e32 v67, 31, v66
	v_lshlrev_b64 v[78:79], 12, v[64:65]
	v_lshl_add_u64 v[66:67], v[66:67], 2, s[8:9]
	v_lshl_add_u64 v[64:65], v[222:223], 0, v[78:79]
	global_load_dwordx2 v[76:77], v[66:67], off
	global_load_dwordx4 v[68:71], v[64:65], off
	s_nop 0
	global_load_dwordx4 v[64:67], v[64:65], off offset:256
	s_waitcnt vmcnt(0)
	v_cvt_f32_f16_e32 v120, v84
	v_cvt_f32_f16_sdwa v84, v84 dst_sel:DWORD dst_unused:UNUSED_PAD src0_sel:WORD_1
	v_cvt_f32_f16_e32 v121, v85
	v_cvt_f32_f16_sdwa v122, v85 dst_sel:DWORD dst_unused:UNUSED_PAD src0_sel:WORD_1
	v_cvt_f32_f16_e32 v123, v86
	v_cvt_f32_f16_sdwa v132, v86 dst_sel:DWORD dst_unused:UNUSED_PAD src0_sel:WORD_1
	v_cvt_f32_f16_e32 v133, v87
	v_cvt_f32_f16_sdwa v134, v87 dst_sel:DWORD dst_unused:UNUSED_PAD src0_sel:WORD_1
	v_sub_f32_e32 v85, v84, v104
	v_sub_f32_e32 v84, v120, v104
	v_sub_f32_e32 v87, v122, v104
	v_sub_f32_e32 v86, v121, v104
	v_pk_mul_f32 v[86:87], v[104:105], v[86:87] op_sel:[1,0]
	v_pk_mul_f32 v[84:85], v[104:105], v[84:85] op_sel:[1,0]
	v_pk_fma_f32 v[86:87], v[204:205], v[86:87], v[216:217]
	v_pk_fma_f32 v[84:85], v[206:207], v[84:85], v[218:219]
	v_pk_fma_f32 v[62:63], v[62:63], v[130:131], v[86:87]
	v_pk_fma_f32 v[60:61], v[60:61], v[128:129], v[84:85]
	v_sub_f32_e32 v85, v132, v104
	v_sub_f32_e32 v84, v123, v104
	v_sub_f32_e32 v87, v134, v104
	v_sub_f32_e32 v86, v133, v104
	v_pk_mul_f32 v[86:87], v[104:105], v[86:87] op_sel:[1,0]
	v_pk_mul_f32 v[84:85], v[104:105], v[84:85] op_sel:[1,0]
	v_pk_fma_f32 v[86:87], v[208:209], v[86:87], v[212:213]
	v_pk_fma_f32 v[84:85], v[210:211], v[84:85], v[214:215]
	v_pk_fma_f32 v[86:87], v[58:59], v[114:115], v[86:87]
	v_pk_fma_f32 v[58:59], v[56:57], v[112:113], v[84:85]
	v_cvt_pk_f16_f32 v56, v60, v61
	v_lshl_add_u64 v[60:61], s[16:17], 0, v[106:107]
	v_cvt_pk_f16_f32 v57, v62, v63
	v_cvt_pk_f16_f32 v58, v58, v59
	v_cvt_pk_f16_f32 v59, v86, v87
	v_lshl_add_u64 v[60:61], v[60:61], 0, v[220:221]
	global_store_dwordx4 v[60:61], v[56:59], off
	v_cvt_f32_f16_e32 v62, v90
	v_cvt_f32_f16_sdwa v63, v90 dst_sel:DWORD dst_unused:UNUSED_PAD src0_sel:WORD_1
	v_cvt_f32_f16_e32 v56, v88
	v_cvt_f32_f16_sdwa v57, v88 dst_sel:DWORD dst_unused:UNUSED_PAD src0_sel:WORD_1
	v_cvt_f32_f16_e32 v58, v89
	v_cvt_f32_f16_sdwa v59, v89 dst_sel:DWORD dst_unused:UNUSED_PAD src0_sel:WORD_1
	v_cvt_f32_f16_e32 v84, v91
	v_cvt_f32_f16_sdwa v85, v91 dst_sel:DWORD dst_unused:UNUSED_PAD src0_sel:WORD_1
	v_sub_f32_e32 v57, v57, v104
	v_sub_f32_e32 v56, v56, v104
	v_sub_f32_e32 v59, v59, v104
	v_sub_f32_e32 v58, v58, v104
	v_pk_mul_f32 v[58:59], v[104:105], v[58:59] op_sel:[1,0]
	v_pk_mul_f32 v[56:57], v[104:105], v[56:57] op_sel:[1,0]
	v_pk_fma_f32 v[58:59], v[196:197], v[58:59], v[200:201]
	v_pk_fma_f32 v[56:57], v[198:199], v[56:57], v[202:203]
	v_pk_fma_f32 v[54:55], v[54:55], v[126:127], v[58:59]
	v_pk_fma_f32 v[52:53], v[52:53], v[124:125], v[56:57]
	v_sub_f32_e32 v57, v63, v104
	v_sub_f32_e32 v56, v62, v104
	v_sub_f32_e32 v59, v85, v104
	v_sub_f32_e32 v58, v84, v104
	v_pk_mul_f32 v[58:59], v[104:105], v[58:59] op_sel:[1,0]
	v_pk_mul_f32 v[56:57], v[104:105], v[56:57] op_sel:[1,0]
	v_pk_fma_f32 v[58:59], v[188:189], v[58:59], v[192:193]
	v_pk_fma_f32 v[56:57], v[190:191], v[56:57], v[194:195]
	v_pk_fma_f32 v[58:59], v[50:51], v[110:111], v[58:59]
	v_pk_fma_f32 v[50:51], v[48:49], v[108:109], v[56:57]
	v_cvt_pk_f16_f32 v48, v52, v53
	v_cvt_pk_f16_f32 v49, v54, v55
	v_cvt_pk_f16_f32 v50, v50, v51
	v_cvt_pk_f16_f32 v51, v58, v59
	global_store_dwordx4 v[60:61], v[48:51], off offset:256
	v_cvt_f32_f16_e32 v52, v94
	v_cvt_f32_f16_sdwa v53, v94 dst_sel:DWORD dst_unused:UNUSED_PAD src0_sel:WORD_1
	v_cvt_f32_f16_e32 v48, v92
;     __device__ __forceinline__ void operator()(const AccT& acc, const pg8::Unit& u, int wr, int wc, int fr, int fq) const {
;     ...
;             for (int m = 0; m < 4; ++m) { const int row = row0 + ai * 128 + m * 16; const size_t off = (size_t)row * D + col0; const f32x2 st = stv[m];
; #pragma unroll
;                 for (int bj = 0; bj < 2; ++bj) { float uf[8]; unpack_h8(uraw[m][bj], uf);
;                     const f32x4 ua = {uf[0], uf[1], uf[2], uf[3]}, ub = {uf[4], uf[5], uf[6], uf[7]};
;                     const f32x4 a = ((ua - st.x) * st.y) * lg[bj][0] + lbv[bj][0] + gv[bj][0] * acc[ai][bj][m][0], b = ((ub - st.x) * st.y) * lg[bj][1] + lbv[bj][1] + gv[bj][1] * acc[ai][bj][m][1];
;                     u32x4 w; w.x = pk_h2(a[0], a[1]); w.y = pk_h2(a[2], a[3]); w.z = pk_h2(b[0], b[1]); w.w = pk_h2(b[2], b[3]);
;                     *(u32x4*)(U2 + off + bj * 128) = w; } }
	v_cvt_f32_f16_sdwa v49, v92 dst_sel:DWORD dst_unused:UNUSED_PAD src0_sel:WORD_1
	v_cvt_f32_f16_e32 v50, v93
	v_cvt_f32_f16_sdwa v51, v93 dst_sel:DWORD dst_unused:UNUSED_PAD src0_sel:WORD_1
	v_cvt_f32_f16_e32 v54, v95
	v_cvt_f32_f16_sdwa v55, v95 dst_sel:DWORD dst_unused:UNUSED_PAD src0_sel:WORD_1
	v_sub_f32_e32 v49, v49, v116
	v_sub_f32_e32 v48, v48, v116
	v_sub_f32_e32 v51, v51, v116
	v_sub_f32_e32 v50, v50, v116
	v_pk_mul_f32 v[50:51], v[116:117], v[50:51] op_sel:[1,0]
	v_pk_mul_f32 v[48:49], v[116:117], v[48:49] op_sel:[1,0]
	v_pk_fma_f32 v[50:51], v[204:205], v[50:51], v[216:217]
	v_pk_fma_f32 v[48:49], v[206:207], v[48:49], v[218:219]
	v_pk_fma_f32 v[46:47], v[46:47], v[130:131], v[50:51]
	v_pk_fma_f32 v[44:45], v[44:45], v[128:129], v[48:49]
	v_sub_f32_e32 v49, v53, v116
	v_sub_f32_e32 v48, v52, v116
	v_sub_f32_e32 v51, v55, v116
	v_sub_f32_e32 v50, v54, v116
	v_pk_mul_f32 v[50:51], v[116:117], v[50:51] op_sel:[1,0]
	v_pk_mul_f32 v[48:49], v[116:117], v[48:49] op_sel:[1,0]
	v_pk_fma_f32 v[50:51], v[208:209], v[50:51], v[212:213]
	v_pk_fma_f32 v[48:49], v[210:211], v[48:49], v[214:215]
	v_pk_fma_f32 v[50:51], v[42:43], v[114:115], v[50:51]
	v_pk_fma_f32 v[42:43], v[40:41], v[112:113], v[48:49]
	v_cvt_pk_f16_f32 v40, v44, v45
	v_lshl_add_u64 v[44:45], s[16:17], 0, v[118:119]
	v_cvt_pk_f16_f32 v41, v46, v47
	v_cvt_pk_f16_f32 v42, v42, v43
	v_cvt_pk_f16_f32 v43, v50, v51
	v_lshl_add_u64 v[44:45], v[44:45], 0, v[220:221]
	global_store_dwordx4 v[44:45], v[40:43], off
	v_cvt_f32_f16_e32 v46, v98
	v_cvt_f32_f16_sdwa v47, v98 dst_sel:DWORD dst_unused:UNUSED_PAD src0_sel:WORD_1
	v_cvt_f32_f16_e32 v40, v96
	v_cvt_f32_f16_sdwa v41, v96 dst_sel:DWORD dst_unused:UNUSED_PAD src0_sel:WORD_1
	v_cvt_f32_f16_e32 v42, v97
	v_cvt_f32_f16_sdwa v43, v97 dst_sel:DWORD dst_unused:UNUSED_PAD src0_sel:WORD_1
	v_cvt_f32_f16_e32 v48, v99
	v_cvt_f32_f16_sdwa v49, v99 dst_sel:DWORD dst_unused:UNUSED_PAD src0_sel:WORD_1
	v_sub_f32_e32 v41, v41, v116
	v_sub_f32_e32 v40, v40, v116
	v_sub_f32_e32 v43, v43, v116
	v_sub_f32_e32 v42, v42, v116
	v_pk_mul_f32 v[42:43], v[116:117], v[42:43] op_sel:[1,0]
	v_pk_mul_f32 v[40:41], v[116:117], v[40:41] op_sel:[1,0]
	v_pk_fma_f32 v[42:43], v[196:197], v[42:43], v[200:201]
	v_pk_fma_f32 v[40:41], v[198:199], v[40:41], v[202:203]
	v_pk_fma_f32 v[38:39], v[38:39], v[126:127], v[42:43]
	v_pk_fma_f32 v[36:37], v[36:37], v[124:125], v[40:41]
	v_sub_f32_e32 v41, v47, v116
	v_sub_f32_e32 v40, v46, v116
	v_sub_f32_e32 v43, v49, v116
	v_sub_f32_e32 v42, v48, v116
	v_pk_mul_f32 v[42:43], v[116:117], v[42:43] op_sel:[1,0]
	v_pk_mul_f32 v[40:41], v[116:117], v[40:41] op_sel:[1,0]
	v_pk_fma_f32 v[42:43], v[188:189], v[42:43], v[192:193]
	v_pk_fma_f32 v[40:41], v[190:191], v[40:41], v[194:195]
	v_pk_fma_f32 v[42:43], v[34:35], v[110:111], v[42:43]
	v_pk_fma_f32 v[34:35], v[32:33], v[108:109], v[40:41]
	v_cvt_pk_f16_f32 v32, v36, v37
	v_cvt_pk_f16_f32 v33, v38, v39
	v_cvt_pk_f16_f32 v34, v34, v35
	v_cvt_pk_f16_f32 v35, v42, v43
	global_store_dwordx4 v[44:45], v[32:35], off offset:256
	v_cvt_f32_f16_e32 v36, v102
	v_cvt_f32_f16_sdwa v37, v102 dst_sel:DWORD dst_unused:UNUSED_PAD src0_sel:WORD_1
	v_cvt_f32_f16_e32 v32, v100
	v_cvt_f32_f16_sdwa v33, v100 dst_sel:DWORD dst_unused:UNUSED_PAD src0_sel:WORD_1
	v_cvt_f32_f16_e32 v34, v101
	v_cvt_f32_f16_sdwa v35, v101 dst_sel:DWORD dst_unused:UNUSED_PAD src0_sel:WORD_1
	v_cvt_f32_f16_e32 v38, v103
	v_cvt_f32_f16_sdwa v39, v103 dst_sel:DWORD dst_unused:UNUSED_PAD src0_sel:WORD_1
	v_sub_f32_e32 v33, v33, v80
	v_sub_f32_e32 v32, v32, v80
	v_sub_f32_e32 v35, v35, v80
	v_sub_f32_e32 v34, v34, v80
	v_pk_mul_f32 v[34:35], v[80:81], v[34:35] op_sel:[1,0]
	v_pk_mul_f32 v[32:33], v[80:81], v[32:33] op_sel:[1,0]
	v_pk_fma_f32 v[34:35], v[204:205], v[34:35], v[216:217]
	v_pk_fma_f32 v[32:33], v[206:207], v[32:33], v[218:219]
	v_pk_fma_f32 v[30:31], v[30:31], v[130:131], v[34:35]
	v_pk_fma_f32 v[28:29], v[28:29], v[128:129], v[32:33]
	v_sub_f32_e32 v33, v37, v80
	v_sub_f32_e32 v32, v36, v80
	v_sub_f32_e32 v35, v39, v80
	v_sub_f32_e32 v34, v38, v80
	v_pk_mul_f32 v[34:35], v[80:81], v[34:35] op_sel:[1,0]
	v_pk_mul_f32 v[32:33], v[80:81], v[32:33] op_sel:[1,0]
	v_pk_fma_f32 v[34:35], v[208:209], v[34:35], v[212:213]
	v_pk_fma_f32 v[32:33], v[210:211], v[32:33], v[214:215]
	v_pk_fma_f32 v[34:35], v[26:27], v[114:115], v[34:35]
	v_pk_fma_f32 v[26:27], v[24:25], v[112:113], v[32:33]
	v_cvt_pk_f16_f32 v24, v28, v29
	v_lshl_add_u64 v[28:29], s[16:17], 0, v[82:83]
	v_cvt_pk_f16_f32 v25, v30, v31
	v_cvt_pk_f16_f32 v26, v26, v27
	v_cvt_pk_f16_f32 v27, v34, v35
	v_lshl_add_u64 v[28:29], v[28:29], 0, v[220:221]
	global_store_dwordx4 v[28:29], v[24:27], off
	v_cvt_f32_f16_e32 v30, v74
; #define PG8_WAIT_V(n) asm volatile("s_waitcnt vmcnt(" #n ")" ::: "memory")
; #define PG8_BAR __builtin_amdgcn_s_barrier()
; template <class Epi, class Sched>
; __device__ __forceinline__ void gemm_phase(PG8_LAS unsigned char* lds, const Gemm g, const Sched& S, const Epi& E) {
;     ...
;         if (!has_next) break;
; #pragma unroll
;         for (int a = 0; a < 2; ++a)
; #pragma unroll
;             for (int b = 0; b < 2; ++b)
; #pragma unroll
;                 for (int m = 0; m < 4; ++m)
; #pragma unroll
;                     for (int n = 0; n < 2; ++n) acc[a][b][m][n] = (f32x4){0.f, 0.f, 0.f, 0.f};
;         cur = nxt; cA = nA; cB = nB; ++ui;
;     }
;     PG8_WAIT_V(0);
;     if (wr == 0) PG8_BAR;
;     PG8_BAR;
;     __device__ __forceinline__ void operator()(const AccT& acc, const pg8::Unit& u, int wr, int wc, int fr, int fq) const {
;     ...
;             for (int m = 0; m < 4; ++m) { const int row = row0 + ai * 128 + m * 16; const size_t off = (size_t)row * D + col0; const f32x2 st = stv[m];
; #pragma unroll
;                 for (int bj = 0; bj < 2; ++bj) { float uf[8]; unpack_h8(uraw[m][bj], uf);
;                     const f32x4 ua = {uf[0], uf[1], uf[2], uf[3]}, ub = {uf[4], uf[5], uf[6], uf[7]};
;                     const f32x4 a = ((ua - st.x) * st.y) * lg[bj][0] + lbv[bj][0] + gv[bj][0] * acc[ai][bj][m][0], b = ((ub - st.x) * st.y) * lg[bj][1] + lbv[bj][1] + gv[bj][1] * acc[ai][bj][m][1];
;                     u32x4 w; w.x = pk_h2(a[0], a[1]); w.y = pk_h2(a[2], a[3]); w.z = pk_h2(b[0], b[1]); w.w = pk_h2(b[2], b[3]);
;                     *(u32x4*)(U2 + off + bj * 128) = w; } }
	v_cvt_f32_f16_sdwa v31, v74 dst_sel:DWORD dst_unused:UNUSED_PAD src0_sel:WORD_1
	v_cvt_f32_f16_e32 v24, v72
	v_cvt_f32_f16_sdwa v25, v72 dst_sel:DWORD dst_unused:UNUSED_PAD src0_sel:WORD_1
	v_cvt_f32_f16_e32 v26, v73
	v_cvt_f32_f16_sdwa v27, v73 dst_sel:DWORD dst_unused:UNUSED_PAD src0_sel:WORD_1
	v_cvt_f32_f16_e32 v32, v75
	v_cvt_f32_f16_sdwa v33, v75 dst_sel:DWORD dst_unused:UNUSED_PAD src0_sel:WORD_1
	v_sub_f32_e32 v25, v25, v80
	v_sub_f32_e32 v24, v24, v80
	v_sub_f32_e32 v27, v27, v80
	v_sub_f32_e32 v26, v26, v80
	v_pk_mul_f32 v[26:27], v[80:81], v[26:27] op_sel:[1,0]
	v_pk_mul_f32 v[24:25], v[80:81], v[24:25] op_sel:[1,0]
	v_pk_fma_f32 v[26:27], v[196:197], v[26:27], v[200:201]
	v_pk_fma_f32 v[24:25], v[198:199], v[24:25], v[202:203]
	v_pk_fma_f32 v[22:23], v[22:23], v[126:127], v[26:27]
	v_pk_fma_f32 v[20:21], v[20:21], v[124:125], v[24:25]
	v_sub_f32_e32 v25, v31, v80
	v_sub_f32_e32 v24, v30, v80
	v_sub_f32_e32 v27, v33, v80
	v_sub_f32_e32 v26, v32, v80
	v_pk_mul_f32 v[26:27], v[80:81], v[26:27] op_sel:[1,0]
	v_pk_mul_f32 v[24:25], v[80:81], v[24:25] op_sel:[1,0]
	v_pk_fma_f32 v[26:27], v[188:189], v[26:27], v[192:193]
	v_pk_fma_f32 v[24:25], v[190:191], v[24:25], v[194:195]
	v_pk_fma_f32 v[26:27], v[18:19], v[110:111], v[26:27]
	v_pk_fma_f32 v[18:19], v[16:17], v[108:109], v[24:25]
	v_cvt_pk_f16_f32 v16, v20, v21
	v_cvt_pk_f16_f32 v17, v22, v23
	v_cvt_pk_f16_f32 v18, v18, v19
	v_cvt_pk_f16_f32 v19, v26, v27
	global_store_dwordx4 v[28:29], v[16:19], off offset:256
	v_cvt_f32_f16_e32 v20, v70
	v_cvt_f32_f16_sdwa v21, v70 dst_sel:DWORD dst_unused:UNUSED_PAD src0_sel:WORD_1
	v_cvt_f32_f16_e32 v16, v68
	v_cvt_f32_f16_sdwa v17, v68 dst_sel:DWORD dst_unused:UNUSED_PAD src0_sel:WORD_1
	v_cvt_f32_f16_e32 v18, v69
	v_cvt_f32_f16_sdwa v19, v69 dst_sel:DWORD dst_unused:UNUSED_PAD src0_sel:WORD_1
	v_cvt_f32_f16_e32 v22, v71
	v_cvt_f32_f16_sdwa v23, v71 dst_sel:DWORD dst_unused:UNUSED_PAD src0_sel:WORD_1
	v_sub_f32_e32 v17, v17, v76
	v_sub_f32_e32 v16, v16, v76
	v_sub_f32_e32 v19, v19, v76
	v_sub_f32_e32 v18, v18, v76
	v_pk_mul_f32 v[18:19], v[76:77], v[18:19] op_sel:[1,0]
	v_pk_mul_f32 v[16:17], v[76:77], v[16:17] op_sel:[1,0]
	v_pk_fma_f32 v[18:19], v[204:205], v[18:19], v[216:217]
	v_pk_fma_f32 v[16:17], v[206:207], v[16:17], v[218:219]
	v_pk_fma_f32 v[14:15], v[14:15], v[130:131], v[18:19]
	v_pk_fma_f32 v[12:13], v[12:13], v[128:129], v[16:17]
	v_sub_f32_e32 v17, v21, v76
	v_sub_f32_e32 v16, v20, v76
	v_sub_f32_e32 v19, v23, v76
	v_sub_f32_e32 v18, v22, v76
	v_pk_mul_f32 v[18:19], v[76:77], v[18:19] op_sel:[1,0]
	v_pk_mul_f32 v[16:17], v[76:77], v[16:17] op_sel:[1,0]
	v_pk_fma_f32 v[18:19], v[208:209], v[18:19], v[212:213]
	v_pk_fma_f32 v[16:17], v[210:211], v[16:17], v[214:215]
	v_pk_fma_f32 v[18:19], v[10:11], v[114:115], v[18:19]
	v_pk_fma_f32 v[10:11], v[8:9], v[112:113], v[16:17]
	v_cvt_pk_f16_f32 v8, v12, v13
	v_lshl_add_u64 v[12:13], s[16:17], 0, v[78:79]
	v_cvt_pk_f16_f32 v9, v14, v15
	v_cvt_pk_f16_f32 v10, v10, v11
	v_cvt_pk_f16_f32 v11, v18, v19
	v_lshl_add_u64 v[12:13], v[12:13], 0, v[220:221]
	global_store_dwordx4 v[12:13], v[8:11], off
	v_cvt_f32_f16_e32 v14, v66
	v_cvt_f32_f16_sdwa v15, v66 dst_sel:DWORD dst_unused:UNUSED_PAD src0_sel:WORD_1
	v_cvt_f32_f16_e32 v8, v64
	v_cvt_f32_f16_sdwa v9, v64 dst_sel:DWORD dst_unused:UNUSED_PAD src0_sel:WORD_1
	v_cvt_f32_f16_e32 v10, v65
	v_cvt_f32_f16_sdwa v11, v65 dst_sel:DWORD dst_unused:UNUSED_PAD src0_sel:WORD_1
	v_cvt_f32_f16_e32 v16, v67
	v_cvt_f32_f16_sdwa v17, v67 dst_sel:DWORD dst_unused:UNUSED_PAD src0_sel:WORD_1
	v_sub_f32_e32 v9, v9, v76
	v_sub_f32_e32 v8, v8, v76
	v_sub_f32_e32 v11, v11, v76
	v_sub_f32_e32 v10, v10, v76
	v_pk_mul_f32 v[10:11], v[76:77], v[10:11] op_sel:[1,0]
	v_pk_mul_f32 v[8:9], v[76:77], v[8:9] op_sel:[1,0]
	v_pk_fma_f32 v[10:11], v[196:197], v[10:11], v[200:201]
	v_pk_fma_f32 v[8:9], v[198:199], v[8:9], v[202:203]
	v_pk_fma_f32 v[6:7], v[6:7], v[126:127], v[10:11]
	v_pk_fma_f32 v[4:5], v[4:5], v[124:125], v[8:9]
	v_sub_f32_e32 v9, v15, v76
	v_sub_f32_e32 v8, v14, v76
	v_sub_f32_e32 v11, v17, v76
	v_sub_f32_e32 v10, v16, v76
	v_pk_mul_f32 v[10:11], v[76:77], v[10:11] op_sel:[1,0]
	v_pk_mul_f32 v[8:9], v[76:77], v[8:9] op_sel:[1,0]
	v_pk_fma_f32 v[10:11], v[188:189], v[10:11], v[192:193]
	v_pk_fma_f32 v[8:9], v[190:191], v[8:9], v[194:195]
	v_pk_fma_f32 v[10:11], v[2:3], v[110:111], v[10:11]
	v_pk_fma_f32 v[2:3], v[0:1], v[108:109], v[8:9]
	v_cvt_pk_f16_f32 v0, v4, v5
	v_cvt_pk_f16_f32 v1, v6, v7
	v_cvt_pk_f16_f32 v2, v2, v3
	v_cvt_pk_f16_f32 v3, v10, v11
	global_store_dwordx4 v[12:13], v[0:3], off offset:256
	s_cbranch_vccz .LBB0_871
	s_waitcnt vmcnt(0)
	s_cmpk_gt_u32 s21, 0xff
	s_cbranch_scc1 .LBB0_886
	s_barrier

; __global__ void __launch_bounds__(512, 2) hymba_fwd(Params p) {
;     extern __shared__ __attribute__((aligned(16))) unsigned char shm[];
;     cg::grid_group grid = cg::this_grid();
	.amdhsa_kernel _Z9hymba_fwd6Params
		.amdhsa_group_segment_fixed_size 0
		.amdhsa_private_segment_fixed_size 0
		.amdhsa_kernarg_size 424
		.amdhsa_user_sgpr_count 2
		.amdhsa_user_sgpr_dispatch_ptr 0
		.amdhsa_user_sgpr_queue_ptr 0
		.amdhsa_user_sgpr_kernarg_segment_ptr 1
		.amdhsa_user_sgpr_dispatch_id 0
		.amdhsa_user_sgpr_kernarg_preload_length 0
		.amdhsa_user_sgpr_kernarg_preload_offset 0
		.amdhsa_user_sgpr_private_segment_size 0
		.amdhsa_uses_dynamic_stack 0
		.amdhsa_enable_private_segment 0
		.amdhsa_system_sgpr_workgroup_id_x 1
		.amdhsa_system_sgpr_workgroup_id_y 0
		.amdhsa_system_sgpr_workgroup_id_z 0
		.amdhsa_system_sgpr_workgroup_info 0
		.amdhsa_system_vgpr_workitem_id 2
		.amdhsa_next_free_vgpr 256
		.amdhsa_next_free_sgpr 102
		.amdhsa_accum_offset 256
		.amdhsa_reserve_vcc 1
		.amdhsa_float_round_mode_32 0
		.amdhsa_float_round_mode_16_64 0
		.amdhsa_float_denorm_mode_32 3
		.amdhsa_float_denorm_mode_16_64 3
		.amdhsa_dx10_clamp 1
		.amdhsa_ieee_mode 1
		.amdhsa_fp16_overflow 0
		.amdhsa_tg_split 0
		.amdhsa_exception_fp_ieee_invalid_op 0
		.amdhsa_exception_fp_denorm_src 0
		.amdhsa_exception_fp_ieee_div_zero 0
		.amdhsa_exception_fp_ieee_overflow 0
		.amdhsa_exception_fp_ieee_underflow 0
		.amdhsa_exception_fp_ieee_inexact 0
		.amdhsa_exception_int_div_zero 0
	.end_amdhsa_kernel

; __global__ void __launch_bounds__(512, 2) hymba_fwd(Params p) {
;     extern __shared__ __attribute__((aligned(16))) unsigned char shm[];
;     cg::grid_group grid = cg::this_grid();
amdhsa.kernels:
  - .agpr_count:     0
    .args:
      - .offset:         0
        .size:           168
        .value_kind:     by_value
      - .offset:         168
        .size:           4
        .value_kind:     hidden_block_count_x
      - .offset:         172
        .size:           4
        .value_kind:     hidden_block_count_y
      - .offset:         176
        .size:           4
        .value_kind:     hidden_block_count_z
      - .offset:         180
        .size:           2
        .value_kind:     hidden_group_size_x
      - .offset:         182
        .size:           2
        .value_kind:     hidden_group_size_y
      - .offset:         184
        .size:           2
        .value_kind:     hidden_group_size_z
      - .offset:         186
        .size:           2
        .value_kind:     hidden_remainder_x
      - .offset:         188
        .size:           2
        .value_kind:     hidden_remainder_y
      - .offset:         190
        .size:           2
        .value_kind:     hidden_remainder_z
      - .offset:         208
        .size:           8
        .value_kind:     hidden_global_offset_x
      - .offset:         216
        .size:           8
        .value_kind:     hidden_global_offset_y
      - .offset:         224
        .size:           8
        .value_kind:     hidden_global_offset_z
      - .offset:         232
        .size:           2
        .value_kind:     hidden_grid_dims
      - .offset:         256
        .size:           8
        .value_kind:     hidden_multigrid_sync_arg
      - .offset:         288
        .size:           4
        .value_kind:     hidden_dynamic_lds_size
    .group_segment_fixed_size: 0
    .kernarg_segment_align: 8
    .kernarg_segment_size: 424
    .language:       OpenCL C
    .language_version:
      - 2
      - 0
    .max_flat_workgroup_size: 512
    .name:           _Z9hymba_fwd6Params
    .private_segment_fixed_size: 0
    .sgpr_count:     108
    .sgpr_spill_count: 3
    .symbol:         _Z9hymba_fwd6Params.kd
    .uniform_work_group_size: 1
    .uses_dynamic_stack: false
    .vgpr_count:     256
    .vgpr_spill_count: 0
    .wavefront_size: 64
